# MFMA order inside every 32-MFMA K-loop segment: snake over (m,n) so that exactly one source fragment changes between consecutive MFMAs; per-accumulator order unchanged
# speedup vs baseline: 1.0145x; 1.0059x over previous
; #define PG8_STAGE(bufoff, gbase, voff) do { _Pragma("unroll") for (int _i = 0; _i < 2; ++_i) \
;         __builtin_amdgcn_global_load_lds((const unsigned*)((const char*)(gbase) + (voff)[_i]), (PG8_LAS unsigned*)(lds + (bufoff) + ldsw + _i * 8192), 16, 0, 0); } while (0)
; #define PG8_LDA(dst, b, h) do { _Pragma("unroll") for (int m = 0; m < 4; ++m) _Pragma("unroll") for (int k = 0; k < 2; ++k) dst[m][k] = *(const PG8_LAS bf16x8*)(lds + PG8_SA(b, h) + aoff + m * 2048 + k * 1024); } while (0)
; #define PG8_LDB(dst, b, h) do { _Pragma("unroll") for (int n = 0; n < 2; ++n) _Pragma("unroll") for (int k = 0; k < 2; ++k) dst[n][k] = *(const PG8_LAS bf16x8*)(lds + PG8_SB(b, h) + boff + n * 2048 + k * 1024); } while (0)
; #define PG8_MMA(ai, bj, At, Bt) do { __builtin_amdgcn_s_setprio(1); _Pragma("unroll") for (int m = 0; m < 4; ++m) _Pragma("unroll") for (int n = 0; n < 2; ++n) _Pragma("unroll") for (int k = 0; k < 2; ++k) \
;         acc[ai][bj][m][n] = __builtin_amdgcn_mfma_f32_16x16x32_bf16(Bt[n][k], At[m][k], acc[ai][bj][m][n], 0, 0, 0); __builtin_amdgcn_s_setprio(0); } while (0)
; #define PG8_WAIT_V(n) asm volatile("s_waitcnt vmcnt(" #n ")" ::: "memory")
; #define PG8_WAIT_L(n) asm volatile("s_waitcnt lgkmcnt(" #n ")" ::: "memory")
; #define PG8_BAR __builtin_amdgcn_s_barrier()
; template <class Epi, class Sched, bool ALIGN_EPI = false, bool SP2 = false>
; __device__ __forceinline__ void gemm_phase(PG8_LAS unsigned char* lds, const Gemm g, const Sched& S, const Epi& E) {
;     ...
;             const char* a1 = cA + (size_t)(t + 1) * kstep;
;             const char* a2 = last ? nA : cA + (size_t)(t + 2) * kstep; const char* b2 = last ? nB : cB + (size_t)(t + 2) * kstep;
;             const char* a3 = a2 + kstep; const char* b3 = b2 + kstep;
;             if (last && has_next) S.a_ready(nxt);
;             if constexpr (SP2) {
;             PG8_LDB(B0, 0, 0); PG8_LDB(B1, 0, 1); PG8_SCHED; PG8_LDA(At, 0, 0); PG8_STAGE(PG8_SA(1, 1), a1 + hstep, voffA);
;             PG8_WAIT_V(8); PG8_WAIT_L(0); PG8_BAR; PG8_MMA(0, 0, At, B0); PG8_MMA(0, 1, At, B1); PG8_BAR; PG8_SCHED;
;             PG8_LDA(At, 0, 1); PG8_STAGE(PG8_SB(0, 0), b2, voffB); PG8_STAGE(PG8_SB(0, 1), b2 + hstep, voffB); PG8_STAGE(PG8_SA(0, 0), a2, voffA);
;             PG8_WAIT_V(8); PG8_WAIT_L(0); PG8_BAR; PG8_MMA(1, 0, At, B0); PG8_MMA(1, 1, At, B1); PG8_BAR; PG8_SCHED;
.Labo_peel:
	ds_read_b128 v[68:71], v254
	ds_read_b128 v[72:75], v254 offset:1024
	ds_read_b128 v[76:79], v254 offset:2048
	ds_read_b128 v[80:83], v254 offset:3072
	ds_read_b128 v[174:177], v254 offset:16384
	ds_read_b128 v[182:185], v254 offset:17408
	ds_read_b128 v[186:189], v254 offset:18432
	ds_read_b128 v[210:213], v254 offset:19456
	s_add_u32 s2, s0, 0xfffc0080
	s_addc_u32 s3, s1, -1
	s_cmp_eq_u32 s56, 12
	s_cselect_b32 s5, s27, s3
	s_cselect_b32 s4, s52, s2
	s_cselect_b32 s3, s25, s55
	s_cselect_b32 s2, s53, s54
	s_add_i32 m0, s29, 0xc000
	ds_read_b128 v[214:217], v179
	ds_read_b128 v[218:221], v179 offset:1024
	ds_read_b128 v[222:225], v179 offset:2048
	ds_read_b128 v[226:229], v179 offset:3072
	ds_read_b128 v[230:233], v179 offset:4096
	ds_read_b128 v[234:237], v179 offset:5120
	ds_read_b128 v[238:241], v179 offset:6144
	ds_read_b128 v[242:245], v179 offset:7168
	global_load_lds_dwordx4 v170, s[0:1]
	s_add_i32 m0, s29, 0xe000
	s_nop 0
	global_load_lds_dwordx4 v172, s[0:1]
	s_waitcnt vmcnt(8)
	s_waitcnt lgkmcnt(0)
	s_barrier
	s_setprio 1
	v_mfma_f32_16x16x32_bf16 v[140:143], v[68:71], v[214:217], 0
	v_mfma_f32_16x16x32_bf16 v[136:139], v[76:79], v[214:217], 0
	v_mfma_f32_16x16x32_bf16 v[120:123], v[76:79], v[222:225], 0
	v_mfma_f32_16x16x32_bf16 v[124:127], v[68:71], v[222:225], 0
	v_mfma_f32_16x16x32_bf16 v[108:111], v[68:71], v[230:233], 0
	v_mfma_f32_16x16x32_bf16 v[104:107], v[76:79], v[230:233], 0
	v_mfma_f32_16x16x32_bf16 v[88:91], v[76:79], v[238:241], 0
	v_mfma_f32_16x16x32_bf16 v[92:95], v[68:71], v[238:241], 0
	v_mfma_f32_16x16x32_bf16 v[140:143], v[72:75], v[218:221], v[140:143]
	v_mfma_f32_16x16x32_bf16 v[136:139], v[80:83], v[218:221], v[136:139]
	v_mfma_f32_16x16x32_bf16 v[120:123], v[80:83], v[226:229], v[120:123]
	v_mfma_f32_16x16x32_bf16 v[124:127], v[72:75], v[226:229], v[124:127]
	v_mfma_f32_16x16x32_bf16 v[108:111], v[72:75], v[234:237], v[108:111]
	v_mfma_f32_16x16x32_bf16 v[104:107], v[80:83], v[234:237], v[104:107]
	v_mfma_f32_16x16x32_bf16 v[88:91], v[80:83], v[242:245], v[88:91]
	v_mfma_f32_16x16x32_bf16 v[92:95], v[72:75], v[242:245], v[92:95]
	v_mfma_f32_16x16x32_bf16 v[132:135], v[174:177], v[214:217], 0
	v_mfma_f32_16x16x32_bf16 v[128:131], v[186:189], v[214:217], 0
	v_mfma_f32_16x16x32_bf16 v[112:115], v[186:189], v[222:225], 0
	v_mfma_f32_16x16x32_bf16 v[116:119], v[174:177], v[222:225], 0
	v_mfma_f32_16x16x32_bf16 v[100:103], v[174:177], v[230:233], 0
	v_mfma_f32_16x16x32_bf16 v[96:99], v[186:189], v[230:233], 0
	v_mfma_f32_16x16x32_bf16 v[64:67], v[186:189], v[238:241], 0
	v_mfma_f32_16x16x32_bf16 v[84:87], v[174:177], v[238:241], 0
	v_mfma_f32_16x16x32_bf16 v[132:135], v[182:185], v[218:221], v[132:135]
	v_mfma_f32_16x16x32_bf16 v[128:131], v[210:213], v[218:221], v[128:131]
	v_mfma_f32_16x16x32_bf16 v[112:115], v[210:213], v[226:229], v[112:115]
	v_mfma_f32_16x16x32_bf16 v[116:119], v[182:185], v[226:229], v[116:119]
	v_mfma_f32_16x16x32_bf16 v[100:103], v[182:185], v[234:237], v[100:103]
	v_mfma_f32_16x16x32_bf16 v[96:99], v[210:213], v[234:237], v[96:99]
	v_mfma_f32_16x16x32_bf16 v[64:67], v[210:213], v[242:245], v[64:67]
	v_mfma_f32_16x16x32_bf16 v[84:87], v[182:185], v[242:245], v[84:87]
	s_setprio 0
	s_barrier
	s_mov_b32 m0, s30
	s_add_u32 s58, s2, 0x40000
	s_addc_u32 s59, s3, 0
	ds_read_b128 v[214:217], v179 offset:16384
	ds_read_b128 v[218:221], v179 offset:17408
	ds_read_b128 v[222:225], v179 offset:18432
	ds_read_b128 v[226:229], v179 offset:19456
	ds_read_b128 v[230:233], v179 offset:20480
	ds_read_b128 v[234:237], v179 offset:21504
	ds_read_b128 v[238:241], v179 offset:22528
	ds_read_b128 v[242:245], v179 offset:23552
	global_load_lds_dwordx4 v166, s[2:3]
	s_mov_b32 m0, s31
	s_nop 0
	global_load_lds_dwordx4 v162, s[2:3]
	s_mov_b32 m0, s33
	s_nop 0
	global_load_lds_dwordx4 v166, s[58:59]
	s_mov_b32 m0, s34
	s_nop 0
	global_load_lds_dwordx4 v162, s[58:59]
	s_mov_b32 m0, s29
	s_nop 0
	global_load_lds_dwordx4 v168, s[4:5]
	s_mov_b32 m0, s35
	s_nop 0
	global_load_lds_dwordx4 v164, s[4:5]
	s_waitcnt vmcnt(8)
	s_waitcnt lgkmcnt(0)
	s_barrier
	s_setprio 1
	v_mfma_f32_16x16x32_bf16 v[60:63], v[68:71], v[214:217], 0
	v_mfma_f32_16x16x32_bf16 v[56:59], v[76:79], v[214:217], 0
	v_mfma_f32_16x16x32_bf16 v[40:43], v[76:79], v[222:225], 0
	v_mfma_f32_16x16x32_bf16 v[44:47], v[68:71], v[222:225], 0
	v_mfma_f32_16x16x32_bf16 v[28:31], v[68:71], v[230:233], 0
	v_mfma_f32_16x16x32_bf16 v[24:27], v[76:79], v[230:233], 0
	v_mfma_f32_16x16x32_bf16 v[8:11], v[76:79], v[238:241], 0
	v_mfma_f32_16x16x32_bf16 v[12:15], v[68:71], v[238:241], 0
	v_mfma_f32_16x16x32_bf16 v[60:63], v[72:75], v[218:221], v[60:63]
	v_mfma_f32_16x16x32_bf16 v[56:59], v[80:83], v[218:221], v[56:59]
	v_mfma_f32_16x16x32_bf16 v[40:43], v[80:83], v[226:229], v[40:43]
	v_mfma_f32_16x16x32_bf16 v[44:47], v[72:75], v[226:229], v[44:47]
	v_mfma_f32_16x16x32_bf16 v[28:31], v[72:75], v[234:237], v[28:31]
	v_mfma_f32_16x16x32_bf16 v[24:27], v[80:83], v[234:237], v[24:27]
	v_mfma_f32_16x16x32_bf16 v[8:11], v[80:83], v[242:245], v[8:11]
	v_mfma_f32_16x16x32_bf16 v[12:15], v[72:75], v[242:245], v[12:15]
	v_mfma_f32_16x16x32_bf16 v[52:55], v[174:177], v[214:217], 0
	v_mfma_f32_16x16x32_bf16 v[48:51], v[186:189], v[214:217], 0
	v_mfma_f32_16x16x32_bf16 v[32:35], v[186:189], v[222:225], 0
	v_mfma_f32_16x16x32_bf16 v[36:39], v[174:177], v[222:225], 0
	v_mfma_f32_16x16x32_bf16 v[20:23], v[174:177], v[230:233], 0
	v_mfma_f32_16x16x32_bf16 v[16:19], v[186:189], v[230:233], 0
	v_mfma_f32_16x16x32_bf16 v[0:3], v[186:189], v[238:241], 0
	v_mfma_f32_16x16x32_bf16 v[4:7], v[174:177], v[238:241], 0
	v_mfma_f32_16x16x32_bf16 v[52:55], v[182:185], v[218:221], v[52:55]
	v_mfma_f32_16x16x32_bf16 v[48:51], v[210:213], v[218:221], v[48:51]
	v_mfma_f32_16x16x32_bf16 v[32:35], v[210:213], v[226:229], v[32:35]
	v_mfma_f32_16x16x32_bf16 v[36:39], v[182:185], v[226:229], v[36:39]
	v_mfma_f32_16x16x32_bf16 v[20:23], v[182:185], v[234:237], v[20:23]
	v_mfma_f32_16x16x32_bf16 v[16:19], v[210:213], v[234:237], v[16:19]
	v_mfma_f32_16x16x32_bf16 v[0:3], v[210:213], v[242:245], v[0:3]
	v_mfma_f32_16x16x32_bf16 v[4:7], v[182:185], v[242:245], v[4:7]
	s_setprio 0
	s_barrier
; #define PG8_STAGE(bufoff, gbase, voff) do { _Pragma("unroll") for (int _i = 0; _i < 2; ++_i) \
;         __builtin_amdgcn_global_load_lds((const unsigned*)((const char*)(gbase) + (voff)[_i]), (PG8_LAS unsigned*)(lds + (bufoff) + ldsw + _i * 8192), 16, 0, 0); } while (0)
; #define PG8_LDA(dst, b, h) do { _Pragma("unroll") for (int m = 0; m < 4; ++m) _Pragma("unroll") for (int k = 0; k < 2; ++k) dst[m][k] = *(const PG8_LAS bf16x8*)(lds + PG8_SA(b, h) + aoff + m * 2048 + k * 1024); } while (0)
; #define PG8_LDB(dst, b, h) do { _Pragma("unroll") for (int n = 0; n < 2; ++n) _Pragma("unroll") for (int k = 0; k < 2; ++k) dst[n][k] = *(const PG8_LAS bf16x8*)(lds + PG8_SB(b, h) + boff + n * 2048 + k * 1024); } while (0)
; #define PG8_MMA(ai, bj, At, Bt) do { __builtin_amdgcn_s_setprio(1); _Pragma("unroll") for (int m = 0; m < 4; ++m) _Pragma("unroll") for (int n = 0; n < 2; ++n) _Pragma("unroll") for (int k = 0; k < 2; ++k) \
;         acc[ai][bj][m][n] = __builtin_amdgcn_mfma_f32_16x16x32_bf16(Bt[n][k], At[m][k], acc[ai][bj][m][n], 0, 0, 0); __builtin_amdgcn_s_setprio(0); } while (0)
; #define PG8_WAIT_V(n) asm volatile("s_waitcnt vmcnt(" #n ")" ::: "memory")
; #define PG8_WAIT_L(n) asm volatile("s_waitcnt lgkmcnt(" #n ")" ::: "memory")
; #define PG8_BAR __builtin_amdgcn_s_barrier()
; #define PG8_SCHED __builtin_amdgcn_sched_barrier(0)
; template <class Epi, class Sched, bool ALIGN_EPI = false, bool SP2 = false>
; __device__ __forceinline__ void gemm_phase(PG8_LAS unsigned char* lds, const Gemm g, const Sched& S, const Epi& E) {
;     ...
;             PG8_LDB(B0, 1, 0); PG8_LDB(B1, 1, 1); PG8_SCHED; PG8_LDA(At, 1, 0); PG8_STAGE(PG8_SA(0, 1), a2 + hstep, voffA);
;             PG8_WAIT_V(8); PG8_WAIT_L(0); PG8_BAR; PG8_MMA(0, 0, At, B0); PG8_MMA(0, 1, At, B1); PG8_BAR; PG8_SCHED;
;             PG8_LDA(At, 1, 1); PG8_STAGE(PG8_SB(1, 0), b3, voffB); PG8_STAGE(PG8_SB(1, 1), b3 + hstep, voffB); PG8_STAGE(PG8_SA(1, 0), a3, voffA);
;             PG8_WAIT_V(8); PG8_WAIT_L(0); PG8_BAR; PG8_MMA(1, 0, At, B0); PG8_MMA(1, 1, At, B1); PG8_BAR; PG8_SCHED;
	ds_read_b128 v[68:71], v254 offset:32768
	ds_read_b128 v[72:75], v254 offset:33792
	ds_read_b128 v[76:79], v254 offset:34816
	ds_read_b128 v[80:83], v254 offset:35840
	ds_read_b128 v[174:177], v254 offset:49152
	ds_read_b128 v[182:185], v254 offset:50176
	ds_read_b128 v[186:189], v254 offset:51200
	ds_read_b128 v[210:213], v254 offset:52224
	s_add_u32 s4, s4, 0x40000
	s_addc_u32 s5, s5, 0
	s_mov_b32 m0, s40
	ds_read_b128 v[214:217], v179 offset:32768
	ds_read_b128 v[218:221], v179 offset:33792
	ds_read_b128 v[222:225], v179 offset:34816
	ds_read_b128 v[226:229], v179 offset:35840
	ds_read_b128 v[230:233], v179 offset:36864
	ds_read_b128 v[234:237], v179 offset:37888
	ds_read_b128 v[238:241], v179 offset:38912
	ds_read_b128 v[242:245], v179 offset:39936
	global_load_lds_dwordx4 v168, s[4:5]
	s_mov_b32 m0, s41
	s_nop 0
	global_load_lds_dwordx4 v164, s[4:5]
	s_waitcnt vmcnt(8)
	s_waitcnt lgkmcnt(0)
	s_barrier
	s_setprio 1
	v_mfma_f32_16x16x32_bf16 v[140:143], v[68:71], v[214:217], v[140:143]
	v_mfma_f32_16x16x32_bf16 v[136:139], v[76:79], v[214:217], v[136:139]
	v_mfma_f32_16x16x32_bf16 v[120:123], v[76:79], v[222:225], v[120:123]
	v_mfma_f32_16x16x32_bf16 v[124:127], v[68:71], v[222:225], v[124:127]
	v_mfma_f32_16x16x32_bf16 v[108:111], v[68:71], v[230:233], v[108:111]
	v_mfma_f32_16x16x32_bf16 v[104:107], v[76:79], v[230:233], v[104:107]
	v_mfma_f32_16x16x32_bf16 v[88:91], v[76:79], v[238:241], v[88:91]
	v_mfma_f32_16x16x32_bf16 v[92:95], v[68:71], v[238:241], v[92:95]
	v_mfma_f32_16x16x32_bf16 v[140:143], v[72:75], v[218:221], v[140:143]
	v_mfma_f32_16x16x32_bf16 v[136:139], v[80:83], v[218:221], v[136:139]
	v_mfma_f32_16x16x32_bf16 v[120:123], v[80:83], v[226:229], v[120:123]
	v_mfma_f32_16x16x32_bf16 v[124:127], v[72:75], v[226:229], v[124:127]
	v_mfma_f32_16x16x32_bf16 v[108:111], v[72:75], v[234:237], v[108:111]
	v_mfma_f32_16x16x32_bf16 v[104:107], v[80:83], v[234:237], v[104:107]
	v_mfma_f32_16x16x32_bf16 v[88:91], v[80:83], v[242:245], v[88:91]
	v_mfma_f32_16x16x32_bf16 v[92:95], v[72:75], v[242:245], v[92:95]
	v_mfma_f32_16x16x32_bf16 v[132:135], v[174:177], v[214:217], v[132:135]
	v_mfma_f32_16x16x32_bf16 v[128:131], v[186:189], v[214:217], v[128:131]
	v_mfma_f32_16x16x32_bf16 v[112:115], v[186:189], v[222:225], v[112:115]
	v_mfma_f32_16x16x32_bf16 v[116:119], v[174:177], v[222:225], v[116:119]
	v_mfma_f32_16x16x32_bf16 v[100:103], v[174:177], v[230:233], v[100:103]
	v_mfma_f32_16x16x32_bf16 v[96:99], v[186:189], v[230:233], v[96:99]
	v_mfma_f32_16x16x32_bf16 v[64:67], v[186:189], v[238:241], v[64:67]
	v_mfma_f32_16x16x32_bf16 v[84:87], v[174:177], v[238:241], v[84:87]
	v_mfma_f32_16x16x32_bf16 v[132:135], v[182:185], v[218:221], v[132:135]
	v_mfma_f32_16x16x32_bf16 v[128:131], v[210:213], v[218:221], v[128:131]
	v_mfma_f32_16x16x32_bf16 v[112:115], v[210:213], v[226:229], v[112:115]
	v_mfma_f32_16x16x32_bf16 v[116:119], v[182:185], v[226:229], v[116:119]
	v_mfma_f32_16x16x32_bf16 v[100:103], v[182:185], v[234:237], v[100:103]
	v_mfma_f32_16x16x32_bf16 v[96:99], v[210:213], v[234:237], v[96:99]
	v_mfma_f32_16x16x32_bf16 v[64:67], v[210:213], v[242:245], v[64:67]
	v_mfma_f32_16x16x32_bf16 v[84:87], v[182:185], v[242:245], v[84:87]
	s_setprio 0
	s_barrier
	s_mov_b32 m0, s45
	s_add_u32 s2, s2, 0x40080
	s_addc_u32 s3, s3, 0
	ds_read_b128 v[214:217], v179 offset:49152
	ds_read_b128 v[218:221], v179 offset:50176
	ds_read_b128 v[222:225], v179 offset:51200
	ds_read_b128 v[226:229], v179 offset:52224
	ds_read_b128 v[230:233], v179 offset:53248
	ds_read_b128 v[234:237], v179 offset:54272
	ds_read_b128 v[238:241], v179 offset:55296
	ds_read_b128 v[242:245], v179 offset:56320
	s_add_u32 s98, s2, 0xfffc0000
	s_addc_u32 s99, s3, -1
	global_load_lds_dwordx4 v166, s[98:99]
	s_mov_b32 m0, s46
	s_nop 0
	global_load_lds_dwordx4 v162, s[98:99]
	s_mov_b32 m0, s49
	s_nop 0
	global_load_lds_dwordx4 v166, s[2:3]
	s_mov_b32 m0, s50
	s_nop 0
	global_load_lds_dwordx4 v162, s[2:3]
	s_mov_b32 m0, s47
	s_nop 0
	s_add_u32 s100, s4, 0xfffc0080
	s_addc_u32 s101, s5, -1
	global_load_lds_dwordx4 v168, s[100:101]
	s_mov_b32 m0, s48
	s_nop 0
	global_load_lds_dwordx4 v164, s[100:101]
	s_waitcnt vmcnt(8)
	s_waitcnt lgkmcnt(0)
	s_barrier
	s_setprio 1
	v_mfma_f32_16x16x32_bf16 v[60:63], v[68:71], v[214:217], v[60:63]
	v_mfma_f32_16x16x32_bf16 v[56:59], v[76:79], v[214:217], v[56:59]
	v_mfma_f32_16x16x32_bf16 v[40:43], v[76:79], v[222:225], v[40:43]
	v_mfma_f32_16x16x32_bf16 v[44:47], v[68:71], v[222:225], v[44:47]
	v_mfma_f32_16x16x32_bf16 v[28:31], v[68:71], v[230:233], v[28:31]
	v_mfma_f32_16x16x32_bf16 v[24:27], v[76:79], v[230:233], v[24:27]
	v_mfma_f32_16x16x32_bf16 v[8:11], v[76:79], v[238:241], v[8:11]
	v_mfma_f32_16x16x32_bf16 v[12:15], v[68:71], v[238:241], v[12:15]
	v_mfma_f32_16x16x32_bf16 v[60:63], v[72:75], v[218:221], v[60:63]
	v_mfma_f32_16x16x32_bf16 v[56:59], v[80:83], v[218:221], v[56:59]
	v_mfma_f32_16x16x32_bf16 v[40:43], v[80:83], v[226:229], v[40:43]
	v_mfma_f32_16x16x32_bf16 v[44:47], v[72:75], v[226:229], v[44:47]
	v_mfma_f32_16x16x32_bf16 v[28:31], v[72:75], v[234:237], v[28:31]
	v_mfma_f32_16x16x32_bf16 v[24:27], v[80:83], v[234:237], v[24:27]
	v_mfma_f32_16x16x32_bf16 v[8:11], v[80:83], v[242:245], v[8:11]
	v_mfma_f32_16x16x32_bf16 v[12:15], v[72:75], v[242:245], v[12:15]
	v_mfma_f32_16x16x32_bf16 v[52:55], v[174:177], v[214:217], v[52:55]
	v_mfma_f32_16x16x32_bf16 v[48:51], v[186:189], v[214:217], v[48:51]
	v_mfma_f32_16x16x32_bf16 v[32:35], v[186:189], v[222:225], v[32:35]
	v_mfma_f32_16x16x32_bf16 v[36:39], v[174:177], v[222:225], v[36:39]
	v_mfma_f32_16x16x32_bf16 v[20:23], v[174:177], v[230:233], v[20:23]
	v_mfma_f32_16x16x32_bf16 v[16:19], v[186:189], v[230:233], v[16:19]
	v_mfma_f32_16x16x32_bf16 v[0:3], v[186:189], v[238:241], v[0:3]
	v_mfma_f32_16x16x32_bf16 v[4:7], v[174:177], v[238:241], v[4:7]
	v_mfma_f32_16x16x32_bf16 v[52:55], v[182:185], v[218:221], v[52:55]
	v_mfma_f32_16x16x32_bf16 v[48:51], v[210:213], v[218:221], v[48:51]
	v_mfma_f32_16x16x32_bf16 v[32:35], v[210:213], v[226:229], v[32:35]
	v_mfma_f32_16x16x32_bf16 v[36:39], v[182:185], v[226:229], v[36:39]
	v_mfma_f32_16x16x32_bf16 v[20:23], v[182:185], v[234:237], v[20:23]
	v_mfma_f32_16x16x32_bf16 v[16:19], v[210:213], v[234:237], v[16:19]
	v_mfma_f32_16x16x32_bf16 v[0:3], v[210:213], v[242:245], v[0:3]
	v_mfma_f32_16x16x32_bf16 v[4:7], v[182:185], v[242:245], v[4:7]
	s_setprio 0
	s_barrier
	s_add_i32 s56, s56, 2
	s_add_u32 s0, s0, 0x100
	s_addc_u32 s1, s1, 0
	s_add_u32 s54, s54, 0x100
	s_addc_u32 s55, s55, 0
	s_cmp_gt_u32 s56, 13
; #define PG8_STAGE(bufoff, gbase, voff) do { _Pragma("unroll") for (int _i = 0; _i < 2; ++_i) \
;         __builtin_amdgcn_global_load_lds((const unsigned*)((const char*)(gbase) + (voff)[_i]), (PG8_LAS unsigned*)(lds + (bufoff) + ldsw + _i * 8192), 16, 0, 0); } while (0)
; #define PG8_LDA(dst, b, h) do { _Pragma("unroll") for (int m = 0; m < 4; ++m) _Pragma("unroll") for (int k = 0; k < 2; ++k) dst[m][k] = *(const PG8_LAS bf16x8*)(lds + PG8_SA(b, h) + aoff + m * 2048 + k * 1024); } while (0)
; #define PG8_LDB(dst, b, h) do { _Pragma("unroll") for (int n = 0; n < 2; ++n) _Pragma("unroll") for (int k = 0; k < 2; ++k) dst[n][k] = *(const PG8_LAS bf16x8*)(lds + PG8_SB(b, h) + boff + n * 2048 + k * 1024); } while (0)
; #define PG8_MMA(ai, bj, At, Bt) do { __builtin_amdgcn_s_setprio(1); _Pragma("unroll") for (int m = 0; m < 4; ++m) _Pragma("unroll") for (int n = 0; n < 2; ++n) _Pragma("unroll") for (int k = 0; k < 2; ++k) \
;         acc[ai][bj][m][n] = __builtin_amdgcn_mfma_f32_16x16x32_bf16(Bt[n][k], At[m][k], acc[ai][bj][m][n], 0, 0, 0); __builtin_amdgcn_s_setprio(0); } while (0)
; #define PG8_WAIT_V(n) asm volatile("s_waitcnt vmcnt(" #n ")" ::: "memory")
; #define PG8_BAR __builtin_amdgcn_s_barrier()
; template <class Epi, class Sched, bool ALIGN_EPI = false, bool SP2 = false>
; __device__ __forceinline__ void gemm_phase(PG8_LAS unsigned char* lds, const Gemm g, const Sched& S, const Epi& E) {
;     ...
;         for (int t = 0; t < nt; t += 2) {
;             const bool last = (t == nt - 2);
;             const char* a1 = cA + (size_t)(t + 1) * kstep;
;             const char* a2 = last ? nA : cA + (size_t)(t + 2) * kstep; const char* b2 = last ? nB : cB + (size_t)(t + 2) * kstep;
;             const char* a3 = a2 + kstep; const char* b3 = b2 + kstep;
;             if (last && has_next) S.a_ready(nxt);
;             if constexpr (SP2) {
;             PG8_LDB(B0, 0, 0); PG8_LDB(B1, 0, 1); PG8_SCHED; PG8_LDA(At, 0, 0); PG8_STAGE(PG8_SA(1, 1), a1 + hstep, voffA);
;             PG8_WAIT_V(8); PG8_WAIT_L(0); PG8_BAR; PG8_MMA(0, 0, At, B0); PG8_MMA(0, 1, At, B1); PG8_BAR; PG8_SCHED;
;             PG8_LDA(At, 0, 1); PG8_STAGE(PG8_SB(0, 0), b2, voffB); PG8_STAGE(PG8_SB(0, 1), b2 + hstep, voffB); PG8_STAGE(PG8_SA(0, 0), a2, voffA);
;             PG8_WAIT_V(8); PG8_WAIT_L(0); PG8_BAR; PG8_MMA(1, 0, At, B0); PG8_MMA(1, 1, At, B1); PG8_BAR; PG8_SCHED;
.LBB0_327:
	ds_read_b128 v[68:71], v254
	ds_read_b128 v[72:75], v254 offset:1024
	ds_read_b128 v[76:79], v254 offset:2048
	ds_read_b128 v[80:83], v254 offset:3072
	ds_read_b128 v[174:177], v254 offset:16384
	ds_read_b128 v[182:185], v254 offset:17408
	ds_read_b128 v[186:189], v254 offset:18432
	ds_read_b128 v[210:213], v254 offset:19456
	s_add_u32 s2, s0, 0xfffc0080
	s_addc_u32 s3, s1, -1
	s_cmp_eq_u32 s56, 12
	s_cselect_b32 s5, s27, s3
	s_cselect_b32 s4, s52, s2
	s_cselect_b32 s3, s25, s55
	s_cselect_b32 s2, s53, s54
	s_add_i32 m0, s29, 0xc000
	ds_read_b128 v[214:217], v179
	ds_read_b128 v[218:221], v179 offset:1024
	ds_read_b128 v[222:225], v179 offset:2048
	ds_read_b128 v[226:229], v179 offset:3072
	ds_read_b128 v[230:233], v179 offset:4096
	ds_read_b128 v[234:237], v179 offset:5120
	ds_read_b128 v[238:241], v179 offset:6144
	ds_read_b128 v[242:245], v179 offset:7168
	global_load_lds_dwordx4 v170, s[0:1]
	s_add_i32 m0, s29, 0xe000
	s_nop 0
	global_load_lds_dwordx4 v172, s[0:1]
	s_waitcnt vmcnt(8)
	s_waitcnt lgkmcnt(0)
	s_barrier
	s_setprio 1
	v_mfma_f32_16x16x32_bf16 v[140:143], v[68:71], v[214:217], v[140:143]
	v_mfma_f32_16x16x32_bf16 v[136:139], v[76:79], v[214:217], v[136:139]
	v_mfma_f32_16x16x32_bf16 v[120:123], v[76:79], v[222:225], v[120:123]
	v_mfma_f32_16x16x32_bf16 v[124:127], v[68:71], v[222:225], v[124:127]
	v_mfma_f32_16x16x32_bf16 v[108:111], v[68:71], v[230:233], v[108:111]
	v_mfma_f32_16x16x32_bf16 v[104:107], v[76:79], v[230:233], v[104:107]
	v_mfma_f32_16x16x32_bf16 v[88:91], v[76:79], v[238:241], v[88:91]
	v_mfma_f32_16x16x32_bf16 v[92:95], v[68:71], v[238:241], v[92:95]
	v_mfma_f32_16x16x32_bf16 v[140:143], v[72:75], v[218:221], v[140:143]
	v_mfma_f32_16x16x32_bf16 v[136:139], v[80:83], v[218:221], v[136:139]
	v_mfma_f32_16x16x32_bf16 v[120:123], v[80:83], v[226:229], v[120:123]
	v_mfma_f32_16x16x32_bf16 v[124:127], v[72:75], v[226:229], v[124:127]
	v_mfma_f32_16x16x32_bf16 v[108:111], v[72:75], v[234:237], v[108:111]
	v_mfma_f32_16x16x32_bf16 v[104:107], v[80:83], v[234:237], v[104:107]
	v_mfma_f32_16x16x32_bf16 v[88:91], v[80:83], v[242:245], v[88:91]
	v_mfma_f32_16x16x32_bf16 v[92:95], v[72:75], v[242:245], v[92:95]
	v_mfma_f32_16x16x32_bf16 v[132:135], v[174:177], v[214:217], v[132:135]
	v_mfma_f32_16x16x32_bf16 v[128:131], v[186:189], v[214:217], v[128:131]
	v_mfma_f32_16x16x32_bf16 v[112:115], v[186:189], v[222:225], v[112:115]
	v_mfma_f32_16x16x32_bf16 v[116:119], v[174:177], v[222:225], v[116:119]
	v_mfma_f32_16x16x32_bf16 v[100:103], v[174:177], v[230:233], v[100:103]
	v_mfma_f32_16x16x32_bf16 v[96:99], v[186:189], v[230:233], v[96:99]
	v_mfma_f32_16x16x32_bf16 v[64:67], v[186:189], v[238:241], v[64:67]
	v_mfma_f32_16x16x32_bf16 v[84:87], v[174:177], v[238:241], v[84:87]
	v_mfma_f32_16x16x32_bf16 v[132:135], v[182:185], v[218:221], v[132:135]
	v_mfma_f32_16x16x32_bf16 v[128:131], v[210:213], v[218:221], v[128:131]
	v_mfma_f32_16x16x32_bf16 v[112:115], v[210:213], v[226:229], v[112:115]
	v_mfma_f32_16x16x32_bf16 v[116:119], v[182:185], v[226:229], v[116:119]
	v_mfma_f32_16x16x32_bf16 v[100:103], v[182:185], v[234:237], v[100:103]
	v_mfma_f32_16x16x32_bf16 v[96:99], v[210:213], v[234:237], v[96:99]
	v_mfma_f32_16x16x32_bf16 v[64:67], v[210:213], v[242:245], v[64:67]
	v_mfma_f32_16x16x32_bf16 v[84:87], v[182:185], v[242:245], v[84:87]
	s_setprio 0
	s_barrier
	s_mov_b32 m0, s30
	s_add_u32 s58, s2, 0x40000
	s_addc_u32 s59, s3, 0
	ds_read_b128 v[214:217], v179 offset:16384
	ds_read_b128 v[218:221], v179 offset:17408
	ds_read_b128 v[222:225], v179 offset:18432
	ds_read_b128 v[226:229], v179 offset:19456
	ds_read_b128 v[230:233], v179 offset:20480
	ds_read_b128 v[234:237], v179 offset:21504
	ds_read_b128 v[238:241], v179 offset:22528
	ds_read_b128 v[242:245], v179 offset:23552
	global_load_lds_dwordx4 v166, s[2:3]
	s_mov_b32 m0, s31
	s_nop 0
	global_load_lds_dwordx4 v162, s[2:3]
	s_mov_b32 m0, s33
	s_nop 0
	global_load_lds_dwordx4 v166, s[58:59]
	s_mov_b32 m0, s34
	s_nop 0
	global_load_lds_dwordx4 v162, s[58:59]
	s_mov_b32 m0, s29
	s_nop 0
	global_load_lds_dwordx4 v168, s[4:5]
	s_mov_b32 m0, s35
	s_nop 0
	global_load_lds_dwordx4 v164, s[4:5]
	s_waitcnt vmcnt(8)
	s_waitcnt lgkmcnt(0)
	s_barrier
	s_setprio 1
	v_mfma_f32_16x16x32_bf16 v[60:63], v[68:71], v[214:217], v[60:63]
	v_mfma_f32_16x16x32_bf16 v[56:59], v[76:79], v[214:217], v[56:59]
	v_mfma_f32_16x16x32_bf16 v[40:43], v[76:79], v[222:225], v[40:43]
	v_mfma_f32_16x16x32_bf16 v[44:47], v[68:71], v[222:225], v[44:47]
	v_mfma_f32_16x16x32_bf16 v[28:31], v[68:71], v[230:233], v[28:31]
	v_mfma_f32_16x16x32_bf16 v[24:27], v[76:79], v[230:233], v[24:27]
	v_mfma_f32_16x16x32_bf16 v[8:11], v[76:79], v[238:241], v[8:11]
	v_mfma_f32_16x16x32_bf16 v[12:15], v[68:71], v[238:241], v[12:15]
	v_mfma_f32_16x16x32_bf16 v[60:63], v[72:75], v[218:221], v[60:63]
	v_mfma_f32_16x16x32_bf16 v[56:59], v[80:83], v[218:221], v[56:59]
	v_mfma_f32_16x16x32_bf16 v[40:43], v[80:83], v[226:229], v[40:43]
	v_mfma_f32_16x16x32_bf16 v[44:47], v[72:75], v[226:229], v[44:47]
	v_mfma_f32_16x16x32_bf16 v[28:31], v[72:75], v[234:237], v[28:31]
	v_mfma_f32_16x16x32_bf16 v[24:27], v[80:83], v[234:237], v[24:27]
	v_mfma_f32_16x16x32_bf16 v[8:11], v[80:83], v[242:245], v[8:11]
	v_mfma_f32_16x16x32_bf16 v[12:15], v[72:75], v[242:245], v[12:15]
	v_mfma_f32_16x16x32_bf16 v[52:55], v[174:177], v[214:217], v[52:55]
	v_mfma_f32_16x16x32_bf16 v[48:51], v[186:189], v[214:217], v[48:51]
	v_mfma_f32_16x16x32_bf16 v[32:35], v[186:189], v[222:225], v[32:35]
	v_mfma_f32_16x16x32_bf16 v[36:39], v[174:177], v[222:225], v[36:39]
	v_mfma_f32_16x16x32_bf16 v[20:23], v[174:177], v[230:233], v[20:23]
	v_mfma_f32_16x16x32_bf16 v[16:19], v[186:189], v[230:233], v[16:19]
	v_mfma_f32_16x16x32_bf16 v[0:3], v[186:189], v[238:241], v[0:3]
	v_mfma_f32_16x16x32_bf16 v[4:7], v[174:177], v[238:241], v[4:7]
	v_mfma_f32_16x16x32_bf16 v[52:55], v[182:185], v[218:221], v[52:55]
	v_mfma_f32_16x16x32_bf16 v[48:51], v[210:213], v[218:221], v[48:51]
	v_mfma_f32_16x16x32_bf16 v[32:35], v[210:213], v[226:229], v[32:35]
	v_mfma_f32_16x16x32_bf16 v[36:39], v[182:185], v[226:229], v[36:39]
	v_mfma_f32_16x16x32_bf16 v[20:23], v[182:185], v[234:237], v[20:23]
	v_mfma_f32_16x16x32_bf16 v[16:19], v[210:213], v[234:237], v[16:19]
	v_mfma_f32_16x16x32_bf16 v[0:3], v[210:213], v[242:245], v[0:3]
	v_mfma_f32_16x16x32_bf16 v[4:7], v[182:185], v[242:245], v[4:7]
	s_setprio 0
	s_barrier
; #define PG8_STAGE(bufoff, gbase, voff) do { _Pragma("unroll") for (int _i = 0; _i < 2; ++_i) \
;         __builtin_amdgcn_global_load_lds((const unsigned*)((const char*)(gbase) + (voff)[_i]), (PG8_LAS unsigned*)(lds + (bufoff) + ldsw + _i * 8192), 16, 0, 0); } while (0)
; #define PG8_LDA(dst, b, h) do { _Pragma("unroll") for (int m = 0; m < 4; ++m) _Pragma("unroll") for (int k = 0; k < 2; ++k) dst[m][k] = *(const PG8_LAS bf16x8*)(lds + PG8_SA(b, h) + aoff + m * 2048 + k * 1024); } while (0)
; #define PG8_LDB(dst, b, h) do { _Pragma("unroll") for (int n = 0; n < 2; ++n) _Pragma("unroll") for (int k = 0; k < 2; ++k) dst[n][k] = *(const PG8_LAS bf16x8*)(lds + PG8_SB(b, h) + boff + n * 2048 + k * 1024); } while (0)
; #define PG8_MMA(ai, bj, At, Bt) do { __builtin_amdgcn_s_setprio(1); _Pragma("unroll") for (int m = 0; m < 4; ++m) _Pragma("unroll") for (int n = 0; n < 2; ++n) _Pragma("unroll") for (int k = 0; k < 2; ++k) \
;         acc[ai][bj][m][n] = __builtin_amdgcn_mfma_f32_16x16x32_bf16(Bt[n][k], At[m][k], acc[ai][bj][m][n], 0, 0, 0); __builtin_amdgcn_s_setprio(0); } while (0)
; #define PG8_WAIT_V(n) asm volatile("s_waitcnt vmcnt(" #n ")" ::: "memory")
; #define PG8_WAIT_L(n) asm volatile("s_waitcnt lgkmcnt(" #n ")" ::: "memory")
; #define PG8_BAR __builtin_amdgcn_s_barrier()
; #define PG8_SCHED __builtin_amdgcn_sched_barrier(0)
; template <class Epi, class Sched, bool ALIGN_EPI = false, bool SP2 = false>
; __device__ __forceinline__ void gemm_phase(PG8_LAS unsigned char* lds, const Gemm g, const Sched& S, const Epi& E) {
;     ...
;             PG8_LDB(B0, 1, 0); PG8_LDB(B1, 1, 1); PG8_SCHED; PG8_LDA(At, 1, 0); PG8_STAGE(PG8_SA(0, 1), a2 + hstep, voffA);
;             PG8_WAIT_V(8); PG8_WAIT_L(0); PG8_BAR; PG8_MMA(0, 0, At, B0); PG8_MMA(0, 1, At, B1); PG8_BAR; PG8_SCHED;
;             PG8_LDA(At, 1, 1); PG8_STAGE(PG8_SB(1, 0), b3, voffB); PG8_STAGE(PG8_SB(1, 1), b3 + hstep, voffB); PG8_STAGE(PG8_SA(1, 0), a3, voffA);
;             PG8_WAIT_V(8); PG8_WAIT_L(0); PG8_BAR; PG8_MMA(1, 0, At, B0); PG8_MMA(1, 1, At, B1); PG8_BAR; PG8_SCHED;
	ds_read_b128 v[68:71], v254 offset:32768
	ds_read_b128 v[72:75], v254 offset:33792
	ds_read_b128 v[76:79], v254 offset:34816
	ds_read_b128 v[80:83], v254 offset:35840
	ds_read_b128 v[174:177], v254 offset:49152
	ds_read_b128 v[182:185], v254 offset:50176
	ds_read_b128 v[186:189], v254 offset:51200
	ds_read_b128 v[210:213], v254 offset:52224
	s_add_u32 s4, s4, 0x40000
	s_addc_u32 s5, s5, 0
	s_mov_b32 m0, s40
	ds_read_b128 v[214:217], v179 offset:32768
	ds_read_b128 v[218:221], v179 offset:33792
	ds_read_b128 v[222:225], v179 offset:34816
	ds_read_b128 v[226:229], v179 offset:35840
	ds_read_b128 v[230:233], v179 offset:36864
	ds_read_b128 v[234:237], v179 offset:37888
	ds_read_b128 v[238:241], v179 offset:38912
	ds_read_b128 v[242:245], v179 offset:39936
	global_load_lds_dwordx4 v168, s[4:5]
	s_mov_b32 m0, s41
	s_nop 0
	global_load_lds_dwordx4 v164, s[4:5]
	s_waitcnt vmcnt(8)
	s_waitcnt lgkmcnt(0)
	s_barrier
	s_setprio 1
	v_mfma_f32_16x16x32_bf16 v[140:143], v[68:71], v[214:217], v[140:143]
	v_mfma_f32_16x16x32_bf16 v[136:139], v[76:79], v[214:217], v[136:139]
	v_mfma_f32_16x16x32_bf16 v[120:123], v[76:79], v[222:225], v[120:123]
	v_mfma_f32_16x16x32_bf16 v[124:127], v[68:71], v[222:225], v[124:127]
	v_mfma_f32_16x16x32_bf16 v[108:111], v[68:71], v[230:233], v[108:111]
	v_mfma_f32_16x16x32_bf16 v[104:107], v[76:79], v[230:233], v[104:107]
	v_mfma_f32_16x16x32_bf16 v[88:91], v[76:79], v[238:241], v[88:91]
	v_mfma_f32_16x16x32_bf16 v[92:95], v[68:71], v[238:241], v[92:95]
	v_mfma_f32_16x16x32_bf16 v[140:143], v[72:75], v[218:221], v[140:143]
	v_mfma_f32_16x16x32_bf16 v[136:139], v[80:83], v[218:221], v[136:139]
	v_mfma_f32_16x16x32_bf16 v[120:123], v[80:83], v[226:229], v[120:123]
	v_mfma_f32_16x16x32_bf16 v[124:127], v[72:75], v[226:229], v[124:127]
	v_mfma_f32_16x16x32_bf16 v[108:111], v[72:75], v[234:237], v[108:111]
	v_mfma_f32_16x16x32_bf16 v[104:107], v[80:83], v[234:237], v[104:107]
	v_mfma_f32_16x16x32_bf16 v[88:91], v[80:83], v[242:245], v[88:91]
	v_mfma_f32_16x16x32_bf16 v[92:95], v[72:75], v[242:245], v[92:95]
	v_mfma_f32_16x16x32_bf16 v[132:135], v[174:177], v[214:217], v[132:135]
	v_mfma_f32_16x16x32_bf16 v[128:131], v[186:189], v[214:217], v[128:131]
	v_mfma_f32_16x16x32_bf16 v[112:115], v[186:189], v[222:225], v[112:115]
	v_mfma_f32_16x16x32_bf16 v[116:119], v[174:177], v[222:225], v[116:119]
	v_mfma_f32_16x16x32_bf16 v[100:103], v[174:177], v[230:233], v[100:103]
	v_mfma_f32_16x16x32_bf16 v[96:99], v[186:189], v[230:233], v[96:99]
	v_mfma_f32_16x16x32_bf16 v[64:67], v[186:189], v[238:241], v[64:67]
	v_mfma_f32_16x16x32_bf16 v[84:87], v[174:177], v[238:241], v[84:87]
	v_mfma_f32_16x16x32_bf16 v[132:135], v[182:185], v[218:221], v[132:135]
	v_mfma_f32_16x16x32_bf16 v[128:131], v[210:213], v[218:221], v[128:131]
	v_mfma_f32_16x16x32_bf16 v[112:115], v[210:213], v[226:229], v[112:115]
	v_mfma_f32_16x16x32_bf16 v[116:119], v[182:185], v[226:229], v[116:119]
	v_mfma_f32_16x16x32_bf16 v[100:103], v[182:185], v[234:237], v[100:103]
	v_mfma_f32_16x16x32_bf16 v[96:99], v[210:213], v[234:237], v[96:99]
	v_mfma_f32_16x16x32_bf16 v[64:67], v[210:213], v[242:245], v[64:67]
	v_mfma_f32_16x16x32_bf16 v[84:87], v[182:185], v[242:245], v[84:87]
	s_setprio 0
	s_barrier
	s_mov_b32 m0, s45
	s_add_u32 s2, s2, 0x40080
	s_addc_u32 s3, s3, 0
	ds_read_b128 v[214:217], v179 offset:49152
	ds_read_b128 v[218:221], v179 offset:50176
	ds_read_b128 v[222:225], v179 offset:51200
	ds_read_b128 v[226:229], v179 offset:52224
	ds_read_b128 v[230:233], v179 offset:53248
	ds_read_b128 v[234:237], v179 offset:54272
	ds_read_b128 v[238:241], v179 offset:55296
	ds_read_b128 v[242:245], v179 offset:56320
	s_add_u32 s98, s2, 0xfffc0000
	s_addc_u32 s99, s3, -1
	global_load_lds_dwordx4 v166, s[98:99]
	s_mov_b32 m0, s46
	s_nop 0
	global_load_lds_dwordx4 v162, s[98:99]
	s_mov_b32 m0, s49
	s_nop 0
	global_load_lds_dwordx4 v166, s[2:3]
	s_mov_b32 m0, s50
	s_nop 0
	global_load_lds_dwordx4 v162, s[2:3]
	s_mov_b32 m0, s47
	s_nop 0
	s_add_u32 s100, s4, 0xfffc0080
	s_addc_u32 s101, s5, -1
	global_load_lds_dwordx4 v168, s[100:101]
	s_mov_b32 m0, s48
	s_nop 0
	global_load_lds_dwordx4 v164, s[100:101]
	s_waitcnt vmcnt(8)
	s_waitcnt lgkmcnt(0)
	s_barrier
	s_setprio 1
	v_mfma_f32_16x16x32_bf16 v[60:63], v[68:71], v[214:217], v[60:63]
	v_mfma_f32_16x16x32_bf16 v[56:59], v[76:79], v[214:217], v[56:59]
	v_mfma_f32_16x16x32_bf16 v[40:43], v[76:79], v[222:225], v[40:43]
	v_mfma_f32_16x16x32_bf16 v[44:47], v[68:71], v[222:225], v[44:47]
	v_mfma_f32_16x16x32_bf16 v[28:31], v[68:71], v[230:233], v[28:31]
	v_mfma_f32_16x16x32_bf16 v[24:27], v[76:79], v[230:233], v[24:27]
	v_mfma_f32_16x16x32_bf16 v[8:11], v[76:79], v[238:241], v[8:11]
	v_mfma_f32_16x16x32_bf16 v[12:15], v[68:71], v[238:241], v[12:15]
	v_mfma_f32_16x16x32_bf16 v[60:63], v[72:75], v[218:221], v[60:63]
	v_mfma_f32_16x16x32_bf16 v[56:59], v[80:83], v[218:221], v[56:59]
	v_mfma_f32_16x16x32_bf16 v[40:43], v[80:83], v[226:229], v[40:43]
	v_mfma_f32_16x16x32_bf16 v[44:47], v[72:75], v[226:229], v[44:47]
	v_mfma_f32_16x16x32_bf16 v[28:31], v[72:75], v[234:237], v[28:31]
	v_mfma_f32_16x16x32_bf16 v[24:27], v[80:83], v[234:237], v[24:27]
	v_mfma_f32_16x16x32_bf16 v[8:11], v[80:83], v[242:245], v[8:11]
	v_mfma_f32_16x16x32_bf16 v[12:15], v[72:75], v[242:245], v[12:15]
	v_mfma_f32_16x16x32_bf16 v[52:55], v[174:177], v[214:217], v[52:55]
	v_mfma_f32_16x16x32_bf16 v[48:51], v[186:189], v[214:217], v[48:51]
	v_mfma_f32_16x16x32_bf16 v[32:35], v[186:189], v[222:225], v[32:35]
	v_mfma_f32_16x16x32_bf16 v[36:39], v[174:177], v[222:225], v[36:39]
	v_mfma_f32_16x16x32_bf16 v[20:23], v[174:177], v[230:233], v[20:23]
	v_mfma_f32_16x16x32_bf16 v[16:19], v[186:189], v[230:233], v[16:19]
	v_mfma_f32_16x16x32_bf16 v[0:3], v[186:189], v[238:241], v[0:3]
	v_mfma_f32_16x16x32_bf16 v[4:7], v[174:177], v[238:241], v[4:7]
	v_mfma_f32_16x16x32_bf16 v[52:55], v[182:185], v[218:221], v[52:55]
	v_mfma_f32_16x16x32_bf16 v[48:51], v[210:213], v[218:221], v[48:51]
	v_mfma_f32_16x16x32_bf16 v[32:35], v[210:213], v[226:229], v[32:35]
	v_mfma_f32_16x16x32_bf16 v[36:39], v[182:185], v[226:229], v[36:39]
	v_mfma_f32_16x16x32_bf16 v[20:23], v[182:185], v[234:237], v[20:23]
	v_mfma_f32_16x16x32_bf16 v[16:19], v[210:213], v[234:237], v[16:19]
	v_mfma_f32_16x16x32_bf16 v[0:3], v[210:213], v[242:245], v[0:3]
	v_mfma_f32_16x16x32_bf16 v[4:7], v[182:185], v[242:245], v[4:7]
	s_setprio 0
	s_barrier
	s_add_i32 s56, s56, 2
	s_add_u32 s0, s0, 0x100
	s_addc_u32 s1, s1, 0
	s_add_u32 s54, s54, 0x100
	s_addc_u32 s55, s55, 0
	s_cmp_gt_u32 s56, 13
	s_cbranch_scc0 .LBB0_327
	s_and_b64 vcc, exec, s[22:23]
	s_cbranch_vccz .LBB0_330
	s_barrier

; #define PG8_STAGE(bufoff, gbase, voff) do { _Pragma("unroll") for (int _i = 0; _i < 2; ++_i) \
;         __builtin_amdgcn_global_load_lds((const unsigned*)((const char*)(gbase) + (voff)[_i]), (PG8_LAS unsigned*)(lds + (bufoff) + ldsw + _i * 8192), 16, 0, 0); } while (0)
; #define PG8_LDA(dst, b, h) do { _Pragma("unroll") for (int m = 0; m < 4; ++m) _Pragma("unroll") for (int k = 0; k < 2; ++k) dst[m][k] = *(const PG8_LAS bf16x8*)(lds + PG8_SA(b, h) + aoff + m * 2048 + k * 1024); } while (0)
; #define PG8_LDB(dst, b, h) do { _Pragma("unroll") for (int n = 0; n < 2; ++n) _Pragma("unroll") for (int k = 0; k < 2; ++k) dst[n][k] = *(const PG8_LAS bf16x8*)(lds + PG8_SB(b, h) + boff + n * 2048 + k * 1024); } while (0)
; #define PG8_MMA(ai, bj, At, Bt) do { __builtin_amdgcn_s_setprio(1); _Pragma("unroll") for (int m = 0; m < 4; ++m) _Pragma("unroll") for (int n = 0; n < 2; ++n) _Pragma("unroll") for (int k = 0; k < 2; ++k) \
;         acc[ai][bj][m][n] = __builtin_amdgcn_mfma_f32_16x16x32_bf16(Bt[n][k], At[m][k], acc[ai][bj][m][n], 0, 0, 0); __builtin_amdgcn_s_setprio(0); } while (0)
; #define PG8_WAIT_V(n) asm volatile("s_waitcnt vmcnt(" #n ")" ::: "memory")
; #define PG8_WAIT_L(n) asm volatile("s_waitcnt lgkmcnt(" #n ")" ::: "memory")
; #define PG8_BAR __builtin_amdgcn_s_barrier()
; template <class Epi, class Sched, bool ALIGN_EPI = false, bool SP2 = false>
; __device__ __forceinline__ void gemm_phase(PG8_LAS unsigned char* lds, const Gemm g, const Sched& S, const Epi& E) {
;     ...
;             const char* a1 = cA + (size_t)(t + 1) * kstep;
;             const char* a2 = last ? nA : cA + (size_t)(t + 2) * kstep; const char* b2 = last ? nB : cB + (size_t)(t + 2) * kstep;
;             const char* a3 = a2 + kstep; const char* b3 = b2 + kstep;
;             if (last && has_next) S.a_ready(nxt);
;             if constexpr (SP2) {
;             PG8_LDB(B0, 0, 0); PG8_LDB(B1, 0, 1); PG8_SCHED; PG8_LDA(At, 0, 0); PG8_STAGE(PG8_SA(1, 1), a1 + hstep, voffA);
;             PG8_WAIT_V(8); PG8_WAIT_L(0); PG8_BAR; PG8_MMA(0, 0, At, B0); PG8_MMA(0, 1, At, B1); PG8_BAR; PG8_SCHED;
;             PG8_LDA(At, 0, 1); PG8_STAGE(PG8_SB(0, 0), b2, voffB); PG8_STAGE(PG8_SB(0, 1), b2 + hstep, voffB); PG8_STAGE(PG8_SA(0, 0), a2, voffA);
;             PG8_WAIT_V(8); PG8_WAIT_L(0); PG8_BAR; PG8_MMA(1, 0, At, B0); PG8_MMA(1, 1, At, B1); PG8_BAR; PG8_SCHED;
.Lup_peel:
	ds_read_b128 v[140:143], v254
	ds_read_b128 v[168:171], v254 offset:1024
	ds_read_b128 v[172:175], v254 offset:2048
	ds_read_b128 v[176:179], v254 offset:3072
	ds_read_b128 v[180:183], v254 offset:16384
	ds_read_b128 v[184:187], v254 offset:17408
	ds_read_b128 v[188:191], v254 offset:18432
	ds_read_b128 v[210:213], v254 offset:19456
	s_add_u32 s16, s14, 0xfffc0080
	s_addc_u32 s17, s15, -1
	s_cmp_eq_u32 s53, 12
	s_cselect_b32 s19, s7, s17
	s_cselect_b32 s18, s49, s16
	s_cselect_b32 s17, s5, s52
	s_cselect_b32 s16, s50, s51
	s_mov_b32 m0, s43
	ds_read_b128 v[214:217], v165
	ds_read_b128 v[218:221], v165 offset:1024
	ds_read_b128 v[222:225], v165 offset:2048
	ds_read_b128 v[226:229], v165 offset:3072
	ds_read_b128 v[230:233], v165 offset:4096
	ds_read_b128 v[234:237], v165 offset:5120
	ds_read_b128 v[238:241], v165 offset:6144
	ds_read_b128 v[242:245], v165 offset:7168
	global_load_lds_dwordx4 v136, s[14:15]
	s_mov_b32 m0, s44
	s_nop 0
	global_load_lds_dwordx4 v138, s[14:15]
	s_waitcnt vmcnt(8)
	s_waitcnt lgkmcnt(0)
	s_barrier
	s_setprio 1
	v_mfma_f32_16x16x32_bf16 v[124:127], v[140:143], v[214:217], 0
	v_mfma_f32_16x16x32_bf16 v[116:119], v[172:175], v[214:217], 0
	v_mfma_f32_16x16x32_bf16 v[100:103], v[172:175], v[222:225], 0
	v_mfma_f32_16x16x32_bf16 v[108:111], v[140:143], v[222:225], 0
	v_mfma_f32_16x16x32_bf16 v[92:95], v[140:143], v[230:233], 0
	v_mfma_f32_16x16x32_bf16 v[84:87], v[172:175], v[230:233], 0
	v_mfma_f32_16x16x32_bf16 v[68:71], v[172:175], v[238:241], 0
	v_mfma_f32_16x16x32_bf16 v[76:79], v[140:143], v[238:241], 0
	v_mfma_f32_16x16x32_bf16 v[124:127], v[168:171], v[218:221], v[124:127]
	v_mfma_f32_16x16x32_bf16 v[116:119], v[176:179], v[218:221], v[116:119]
	v_mfma_f32_16x16x32_bf16 v[100:103], v[176:179], v[226:229], v[100:103]
	v_mfma_f32_16x16x32_bf16 v[108:111], v[168:171], v[226:229], v[108:111]
	v_mfma_f32_16x16x32_bf16 v[92:95], v[168:171], v[234:237], v[92:95]
	v_mfma_f32_16x16x32_bf16 v[84:87], v[176:179], v[234:237], v[84:87]
	v_mfma_f32_16x16x32_bf16 v[68:71], v[176:179], v[242:245], v[68:71]
	v_mfma_f32_16x16x32_bf16 v[76:79], v[168:171], v[242:245], v[76:79]
	v_mfma_f32_16x16x32_bf16 v[120:123], v[180:183], v[214:217], 0
	v_mfma_f32_16x16x32_bf16 v[112:115], v[188:191], v[214:217], 0
	v_mfma_f32_16x16x32_bf16 v[96:99], v[188:191], v[222:225], 0
	v_mfma_f32_16x16x32_bf16 v[104:107], v[180:183], v[222:225], 0
	v_mfma_f32_16x16x32_bf16 v[88:91], v[180:183], v[230:233], 0
	v_mfma_f32_16x16x32_bf16 v[80:83], v[188:191], v[230:233], 0
	v_mfma_f32_16x16x32_bf16 v[64:67], v[188:191], v[238:241], 0
	v_mfma_f32_16x16x32_bf16 v[72:75], v[180:183], v[238:241], 0
	v_mfma_f32_16x16x32_bf16 v[120:123], v[184:187], v[218:221], v[120:123]
	v_mfma_f32_16x16x32_bf16 v[112:115], v[210:213], v[218:221], v[112:115]
	v_mfma_f32_16x16x32_bf16 v[96:99], v[210:213], v[226:229], v[96:99]
	v_mfma_f32_16x16x32_bf16 v[104:107], v[184:187], v[226:229], v[104:107]
	v_mfma_f32_16x16x32_bf16 v[88:91], v[184:187], v[234:237], v[88:91]
	v_mfma_f32_16x16x32_bf16 v[80:83], v[210:213], v[234:237], v[80:83]
	v_mfma_f32_16x16x32_bf16 v[64:67], v[210:213], v[242:245], v[64:67]
	v_mfma_f32_16x16x32_bf16 v[72:75], v[184:187], v[242:245], v[72:75]
	s_setprio 0
	s_barrier
	s_mov_b32 m0, s27
	s_add_u32 s54, s16, 0x40000
	s_addc_u32 s55, s17, 0
	ds_read_b128 v[214:217], v165 offset:16384
	ds_read_b128 v[218:221], v165 offset:17408
	ds_read_b128 v[222:225], v165 offset:18432
	ds_read_b128 v[226:229], v165 offset:19456
	ds_read_b128 v[230:233], v165 offset:20480
	ds_read_b128 v[234:237], v165 offset:21504
	ds_read_b128 v[238:241], v165 offset:22528
	ds_read_b128 v[242:245], v165 offset:23552
	global_load_lds_dwordx4 v132, s[16:17]
	s_mov_b32 m0, s28
	s_nop 0
	global_load_lds_dwordx4 v128, s[16:17]
	s_mov_b32 m0, s29
	s_nop 0
	global_load_lds_dwordx4 v132, s[54:55]
	s_mov_b32 m0, s30
	s_nop 0
	global_load_lds_dwordx4 v128, s[54:55]
	s_mov_b32 m0, s22
	s_nop 0
	global_load_lds_dwordx4 v134, s[18:19]
	s_mov_b32 m0, s31
	s_nop 0
	global_load_lds_dwordx4 v130, s[18:19]
	s_waitcnt vmcnt(8)
	s_waitcnt lgkmcnt(0)
	s_barrier
	s_setprio 1
	v_mfma_f32_16x16x32_bf16 v[60:63], v[140:143], v[214:217], 0
	v_mfma_f32_16x16x32_bf16 v[52:55], v[172:175], v[214:217], 0
	v_mfma_f32_16x16x32_bf16 v[36:39], v[172:175], v[222:225], 0
	v_mfma_f32_16x16x32_bf16 v[44:47], v[140:143], v[222:225], 0
	v_mfma_f32_16x16x32_bf16 v[28:31], v[140:143], v[230:233], 0
	v_mfma_f32_16x16x32_bf16 v[20:23], v[172:175], v[230:233], 0
	v_mfma_f32_16x16x32_bf16 v[4:7], v[172:175], v[238:241], 0
	v_mfma_f32_16x16x32_bf16 v[12:15], v[140:143], v[238:241], 0
	v_mfma_f32_16x16x32_bf16 v[60:63], v[168:171], v[218:221], v[60:63]
	v_mfma_f32_16x16x32_bf16 v[52:55], v[176:179], v[218:221], v[52:55]
	v_mfma_f32_16x16x32_bf16 v[36:39], v[176:179], v[226:229], v[36:39]
	v_mfma_f32_16x16x32_bf16 v[44:47], v[168:171], v[226:229], v[44:47]
	v_mfma_f32_16x16x32_bf16 v[28:31], v[168:171], v[234:237], v[28:31]
	v_mfma_f32_16x16x32_bf16 v[20:23], v[176:179], v[234:237], v[20:23]
	v_mfma_f32_16x16x32_bf16 v[4:7], v[176:179], v[242:245], v[4:7]
	v_mfma_f32_16x16x32_bf16 v[12:15], v[168:171], v[242:245], v[12:15]
	v_mfma_f32_16x16x32_bf16 v[56:59], v[180:183], v[214:217], 0
	v_mfma_f32_16x16x32_bf16 v[48:51], v[188:191], v[214:217], 0
	v_mfma_f32_16x16x32_bf16 v[32:35], v[188:191], v[222:225], 0
	v_mfma_f32_16x16x32_bf16 v[40:43], v[180:183], v[222:225], 0
	v_mfma_f32_16x16x32_bf16 v[24:27], v[180:183], v[230:233], 0
	v_mfma_f32_16x16x32_bf16 v[16:19], v[188:191], v[230:233], 0
	v_mfma_f32_16x16x32_bf16 v[0:3], v[188:191], v[238:241], 0
	v_mfma_f32_16x16x32_bf16 v[8:11], v[180:183], v[238:241], 0
	v_mfma_f32_16x16x32_bf16 v[56:59], v[184:187], v[218:221], v[56:59]
	v_mfma_f32_16x16x32_bf16 v[48:51], v[210:213], v[218:221], v[48:51]
	v_mfma_f32_16x16x32_bf16 v[32:35], v[210:213], v[226:229], v[32:35]
	v_mfma_f32_16x16x32_bf16 v[40:43], v[184:187], v[226:229], v[40:43]
	v_mfma_f32_16x16x32_bf16 v[24:27], v[184:187], v[234:237], v[24:27]
	v_mfma_f32_16x16x32_bf16 v[16:19], v[210:213], v[234:237], v[16:19]
	v_mfma_f32_16x16x32_bf16 v[0:3], v[210:213], v[242:245], v[0:3]
	v_mfma_f32_16x16x32_bf16 v[8:11], v[184:187], v[242:245], v[8:11]
	s_setprio 0
	s_barrier
; #define PG8_STAGE(bufoff, gbase, voff) do { _Pragma("unroll") for (int _i = 0; _i < 2; ++_i) \
;         __builtin_amdgcn_global_load_lds((const unsigned*)((const char*)(gbase) + (voff)[_i]), (PG8_LAS unsigned*)(lds + (bufoff) + ldsw + _i * 8192), 16, 0, 0); } while (0)
; #define PG8_LDA(dst, b, h) do { _Pragma("unroll") for (int m = 0; m < 4; ++m) _Pragma("unroll") for (int k = 0; k < 2; ++k) dst[m][k] = *(const PG8_LAS bf16x8*)(lds + PG8_SA(b, h) + aoff + m * 2048 + k * 1024); } while (0)
; #define PG8_LDB(dst, b, h) do { _Pragma("unroll") for (int n = 0; n < 2; ++n) _Pragma("unroll") for (int k = 0; k < 2; ++k) dst[n][k] = *(const PG8_LAS bf16x8*)(lds + PG8_SB(b, h) + boff + n * 2048 + k * 1024); } while (0)
; #define PG8_MMA(ai, bj, At, Bt) do { __builtin_amdgcn_s_setprio(1); _Pragma("unroll") for (int m = 0; m < 4; ++m) _Pragma("unroll") for (int n = 0; n < 2; ++n) _Pragma("unroll") for (int k = 0; k < 2; ++k) \
;         acc[ai][bj][m][n] = __builtin_amdgcn_mfma_f32_16x16x32_bf16(Bt[n][k], At[m][k], acc[ai][bj][m][n], 0, 0, 0); __builtin_amdgcn_s_setprio(0); } while (0)
; #define PG8_WAIT_V(n) asm volatile("s_waitcnt vmcnt(" #n ")" ::: "memory")
; #define PG8_WAIT_L(n) asm volatile("s_waitcnt lgkmcnt(" #n ")" ::: "memory")
; #define PG8_BAR __builtin_amdgcn_s_barrier()
; #define PG8_SCHED __builtin_amdgcn_sched_barrier(0)
; template <class Epi, class Sched, bool ALIGN_EPI = false, bool SP2 = false>
; __device__ __forceinline__ void gemm_phase(PG8_LAS unsigned char* lds, const Gemm g, const Sched& S, const Epi& E) {
;     ...
;             PG8_LDB(B0, 1, 0); PG8_LDB(B1, 1, 1); PG8_SCHED; PG8_LDA(At, 1, 0); PG8_STAGE(PG8_SA(0, 1), a2 + hstep, voffA);
;             PG8_WAIT_V(8); PG8_WAIT_L(0); PG8_BAR; PG8_MMA(0, 0, At, B0); PG8_MMA(0, 1, At, B1); PG8_BAR; PG8_SCHED;
;             PG8_LDA(At, 1, 1); PG8_STAGE(PG8_SB(1, 0), b3, voffB); PG8_STAGE(PG8_SB(1, 1), b3 + hstep, voffB); PG8_STAGE(PG8_SA(1, 0), a3, voffA);
;             PG8_WAIT_V(8); PG8_WAIT_L(0); PG8_BAR; PG8_MMA(1, 0, At, B0); PG8_MMA(1, 1, At, B1); PG8_BAR; PG8_SCHED;
	ds_read_b128 v[140:143], v254 offset:32768
	ds_read_b128 v[168:171], v254 offset:33792
	ds_read_b128 v[172:175], v254 offset:34816
	ds_read_b128 v[176:179], v254 offset:35840
	ds_read_b128 v[180:183], v254 offset:49152
	ds_read_b128 v[184:187], v254 offset:50176
	ds_read_b128 v[188:191], v254 offset:51200
	ds_read_b128 v[210:213], v254 offset:52224
	s_add_u32 s18, s18, 0x40000
	s_addc_u32 s19, s19, 0
	s_mov_b32 m0, s33
	ds_read_b128 v[214:217], v165 offset:32768
	ds_read_b128 v[218:221], v165 offset:33792
	ds_read_b128 v[222:225], v165 offset:34816
	ds_read_b128 v[226:229], v165 offset:35840
	ds_read_b128 v[230:233], v165 offset:36864
	ds_read_b128 v[234:237], v165 offset:37888
	ds_read_b128 v[238:241], v165 offset:38912
	ds_read_b128 v[242:245], v165 offset:39936
	global_load_lds_dwordx4 v134, s[18:19]
	s_mov_b32 m0, s34
	s_nop 0
	global_load_lds_dwordx4 v130, s[18:19]
	s_waitcnt vmcnt(8)
	s_waitcnt lgkmcnt(0)
	s_barrier
	s_setprio 1
	v_mfma_f32_16x16x32_bf16 v[124:127], v[140:143], v[214:217], v[124:127]
	v_mfma_f32_16x16x32_bf16 v[116:119], v[172:175], v[214:217], v[116:119]
	v_mfma_f32_16x16x32_bf16 v[100:103], v[172:175], v[222:225], v[100:103]
	v_mfma_f32_16x16x32_bf16 v[108:111], v[140:143], v[222:225], v[108:111]
	v_mfma_f32_16x16x32_bf16 v[92:95], v[140:143], v[230:233], v[92:95]
	v_mfma_f32_16x16x32_bf16 v[84:87], v[172:175], v[230:233], v[84:87]
	v_mfma_f32_16x16x32_bf16 v[68:71], v[172:175], v[238:241], v[68:71]
	v_mfma_f32_16x16x32_bf16 v[76:79], v[140:143], v[238:241], v[76:79]
	v_mfma_f32_16x16x32_bf16 v[124:127], v[168:171], v[218:221], v[124:127]
	v_mfma_f32_16x16x32_bf16 v[116:119], v[176:179], v[218:221], v[116:119]
	v_mfma_f32_16x16x32_bf16 v[100:103], v[176:179], v[226:229], v[100:103]
	v_mfma_f32_16x16x32_bf16 v[108:111], v[168:171], v[226:229], v[108:111]
	v_mfma_f32_16x16x32_bf16 v[92:95], v[168:171], v[234:237], v[92:95]
	v_mfma_f32_16x16x32_bf16 v[84:87], v[176:179], v[234:237], v[84:87]
	v_mfma_f32_16x16x32_bf16 v[68:71], v[176:179], v[242:245], v[68:71]
	v_mfma_f32_16x16x32_bf16 v[76:79], v[168:171], v[242:245], v[76:79]
	v_mfma_f32_16x16x32_bf16 v[120:123], v[180:183], v[214:217], v[120:123]
	v_mfma_f32_16x16x32_bf16 v[112:115], v[188:191], v[214:217], v[112:115]
	v_mfma_f32_16x16x32_bf16 v[96:99], v[188:191], v[222:225], v[96:99]
	v_mfma_f32_16x16x32_bf16 v[104:107], v[180:183], v[222:225], v[104:107]
	v_mfma_f32_16x16x32_bf16 v[88:91], v[180:183], v[230:233], v[88:91]
	v_mfma_f32_16x16x32_bf16 v[80:83], v[188:191], v[230:233], v[80:83]
	v_mfma_f32_16x16x32_bf16 v[64:67], v[188:191], v[238:241], v[64:67]
	v_mfma_f32_16x16x32_bf16 v[72:75], v[180:183], v[238:241], v[72:75]
	v_mfma_f32_16x16x32_bf16 v[120:123], v[184:187], v[218:221], v[120:123]
	v_mfma_f32_16x16x32_bf16 v[112:115], v[210:213], v[218:221], v[112:115]
	v_mfma_f32_16x16x32_bf16 v[96:99], v[210:213], v[226:229], v[96:99]
	v_mfma_f32_16x16x32_bf16 v[104:107], v[184:187], v[226:229], v[104:107]
	v_mfma_f32_16x16x32_bf16 v[88:91], v[184:187], v[234:237], v[88:91]
	v_mfma_f32_16x16x32_bf16 v[80:83], v[210:213], v[234:237], v[80:83]
	v_mfma_f32_16x16x32_bf16 v[64:67], v[210:213], v[242:245], v[64:67]
	v_mfma_f32_16x16x32_bf16 v[72:75], v[184:187], v[242:245], v[72:75]
	s_setprio 0
	s_barrier
	s_mov_b32 m0, s37
	s_add_u32 s16, s16, 0x40080
	s_addc_u32 s17, s17, 0
	ds_read_b128 v[214:217], v165 offset:49152
	ds_read_b128 v[218:221], v165 offset:50176
	ds_read_b128 v[222:225], v165 offset:51200
	ds_read_b128 v[226:229], v165 offset:52224
	ds_read_b128 v[230:233], v165 offset:53248
	ds_read_b128 v[234:237], v165 offset:54272
	ds_read_b128 v[238:241], v165 offset:55296
	ds_read_b128 v[242:245], v165 offset:56320
	s_add_u32 s98, s16, 0xfffc0000
	s_addc_u32 s99, s17, -1
	global_load_lds_dwordx4 v132, s[98:99]
	s_mov_b32 m0, s38
	s_nop 0
	global_load_lds_dwordx4 v128, s[98:99]
	s_mov_b32 m0, s41
	s_nop 0
	global_load_lds_dwordx4 v132, s[16:17]
	s_mov_b32 m0, s42
	s_nop 0
	global_load_lds_dwordx4 v128, s[16:17]
	s_mov_b32 m0, s39
	s_nop 0
	s_add_u32 s100, s18, 0xfffc0080
	s_addc_u32 s101, s19, -1
	global_load_lds_dwordx4 v134, s[100:101]
	s_mov_b32 m0, s40
	s_nop 0
	global_load_lds_dwordx4 v130, s[100:101]
	s_waitcnt vmcnt(8)
	s_waitcnt lgkmcnt(0)
	s_barrier
	s_setprio 1
	v_mfma_f32_16x16x32_bf16 v[60:63], v[140:143], v[214:217], v[60:63]
	v_mfma_f32_16x16x32_bf16 v[52:55], v[172:175], v[214:217], v[52:55]
	v_mfma_f32_16x16x32_bf16 v[36:39], v[172:175], v[222:225], v[36:39]
	v_mfma_f32_16x16x32_bf16 v[44:47], v[140:143], v[222:225], v[44:47]
	v_mfma_f32_16x16x32_bf16 v[28:31], v[140:143], v[230:233], v[28:31]
	v_mfma_f32_16x16x32_bf16 v[20:23], v[172:175], v[230:233], v[20:23]
	v_mfma_f32_16x16x32_bf16 v[4:7], v[172:175], v[238:241], v[4:7]
	v_mfma_f32_16x16x32_bf16 v[12:15], v[140:143], v[238:241], v[12:15]
	v_mfma_f32_16x16x32_bf16 v[60:63], v[168:171], v[218:221], v[60:63]
	v_mfma_f32_16x16x32_bf16 v[52:55], v[176:179], v[218:221], v[52:55]
	v_mfma_f32_16x16x32_bf16 v[36:39], v[176:179], v[226:229], v[36:39]
	v_mfma_f32_16x16x32_bf16 v[44:47], v[168:171], v[226:229], v[44:47]
	v_mfma_f32_16x16x32_bf16 v[28:31], v[168:171], v[234:237], v[28:31]
	v_mfma_f32_16x16x32_bf16 v[20:23], v[176:179], v[234:237], v[20:23]
	v_mfma_f32_16x16x32_bf16 v[4:7], v[176:179], v[242:245], v[4:7]
	v_mfma_f32_16x16x32_bf16 v[12:15], v[168:171], v[242:245], v[12:15]
	v_mfma_f32_16x16x32_bf16 v[56:59], v[180:183], v[214:217], v[56:59]
	v_mfma_f32_16x16x32_bf16 v[48:51], v[188:191], v[214:217], v[48:51]
	v_mfma_f32_16x16x32_bf16 v[32:35], v[188:191], v[222:225], v[32:35]
	v_mfma_f32_16x16x32_bf16 v[40:43], v[180:183], v[222:225], v[40:43]
	v_mfma_f32_16x16x32_bf16 v[24:27], v[180:183], v[230:233], v[24:27]
	v_mfma_f32_16x16x32_bf16 v[16:19], v[188:191], v[230:233], v[16:19]
	v_mfma_f32_16x16x32_bf16 v[0:3], v[188:191], v[238:241], v[0:3]
	v_mfma_f32_16x16x32_bf16 v[8:11], v[180:183], v[238:241], v[8:11]
	v_mfma_f32_16x16x32_bf16 v[56:59], v[184:187], v[218:221], v[56:59]
	v_mfma_f32_16x16x32_bf16 v[48:51], v[210:213], v[218:221], v[48:51]
	v_mfma_f32_16x16x32_bf16 v[32:35], v[210:213], v[226:229], v[32:35]
	v_mfma_f32_16x16x32_bf16 v[40:43], v[184:187], v[226:229], v[40:43]
	v_mfma_f32_16x16x32_bf16 v[24:27], v[184:187], v[234:237], v[24:27]
	v_mfma_f32_16x16x32_bf16 v[16:19], v[210:213], v[234:237], v[16:19]
	v_mfma_f32_16x16x32_bf16 v[0:3], v[210:213], v[242:245], v[0:3]
	v_mfma_f32_16x16x32_bf16 v[8:11], v[184:187], v[242:245], v[8:11]
	s_setprio 0
	s_barrier
	s_add_i32 s53, s53, 2
	s_add_u32 s14, s14, 0x100
	s_addc_u32 s15, s15, 0
	s_add_u32 s51, s51, 0x100
	s_addc_u32 s52, s52, 0
	s_cmp_gt_u32 s53, 13
; #define PG8_STAGE(bufoff, gbase, voff) do { _Pragma("unroll") for (int _i = 0; _i < 2; ++_i) \
;         __builtin_amdgcn_global_load_lds((const unsigned*)((const char*)(gbase) + (voff)[_i]), (PG8_LAS unsigned*)(lds + (bufoff) + ldsw + _i * 8192), 16, 0, 0); } while (0)
; #define PG8_LDA(dst, b, h) do { _Pragma("unroll") for (int m = 0; m < 4; ++m) _Pragma("unroll") for (int k = 0; k < 2; ++k) dst[m][k] = *(const PG8_LAS bf16x8*)(lds + PG8_SA(b, h) + aoff + m * 2048 + k * 1024); } while (0)
; #define PG8_LDB(dst, b, h) do { _Pragma("unroll") for (int n = 0; n < 2; ++n) _Pragma("unroll") for (int k = 0; k < 2; ++k) dst[n][k] = *(const PG8_LAS bf16x8*)(lds + PG8_SB(b, h) + boff + n * 2048 + k * 1024); } while (0)
; #define PG8_MMA(ai, bj, At, Bt) do { __builtin_amdgcn_s_setprio(1); _Pragma("unroll") for (int m = 0; m < 4; ++m) _Pragma("unroll") for (int n = 0; n < 2; ++n) _Pragma("unroll") for (int k = 0; k < 2; ++k) \
;         acc[ai][bj][m][n] = __builtin_amdgcn_mfma_f32_16x16x32_bf16(Bt[n][k], At[m][k], acc[ai][bj][m][n], 0, 0, 0); __builtin_amdgcn_s_setprio(0); } while (0)
; #define PG8_WAIT_V(n) asm volatile("s_waitcnt vmcnt(" #n ")" ::: "memory")
; #define PG8_BAR __builtin_amdgcn_s_barrier()
; template <class Epi, class Sched, bool ALIGN_EPI = false, bool SP2 = false>
; __device__ __forceinline__ void gemm_phase(PG8_LAS unsigned char* lds, const Gemm g, const Sched& S, const Epi& E) {
;     ...
;         for (int t = 0; t < nt; t += 2) {
;             const bool last = (t == nt - 2);
;             const char* a1 = cA + (size_t)(t + 1) * kstep;
;             const char* a2 = last ? nA : cA + (size_t)(t + 2) * kstep; const char* b2 = last ? nB : cB + (size_t)(t + 2) * kstep;
;             const char* a3 = a2 + kstep; const char* b3 = b2 + kstep;
;             if (last && has_next) S.a_ready(nxt);
;             if constexpr (SP2) {
;             PG8_LDB(B0, 0, 0); PG8_LDB(B1, 0, 1); PG8_SCHED; PG8_LDA(At, 0, 0); PG8_STAGE(PG8_SA(1, 1), a1 + hstep, voffA);
;             PG8_WAIT_V(8); PG8_WAIT_L(0); PG8_BAR; PG8_MMA(0, 0, At, B0); PG8_MMA(0, 1, At, B1); PG8_BAR; PG8_SCHED;
;             PG8_LDA(At, 0, 1); PG8_STAGE(PG8_SB(0, 0), b2, voffB); PG8_STAGE(PG8_SB(0, 1), b2 + hstep, voffB); PG8_STAGE(PG8_SA(0, 0), a2, voffA);
;             PG8_WAIT_V(8); PG8_WAIT_L(0); PG8_BAR; PG8_MMA(1, 0, At, B0); PG8_MMA(1, 1, At, B1); PG8_BAR; PG8_SCHED;
.LBB0_446:
	ds_read_b128 v[140:143], v254
	ds_read_b128 v[168:171], v254 offset:1024
	ds_read_b128 v[172:175], v254 offset:2048
	ds_read_b128 v[176:179], v254 offset:3072
	ds_read_b128 v[180:183], v254 offset:16384
	ds_read_b128 v[184:187], v254 offset:17408
	ds_read_b128 v[188:191], v254 offset:18432
	ds_read_b128 v[210:213], v254 offset:19456
	s_add_u32 s16, s14, 0xfffc0080
	s_addc_u32 s17, s15, -1
	s_cmp_eq_u32 s53, 12
	s_cselect_b32 s19, s7, s17
	s_cselect_b32 s18, s49, s16
	s_cselect_b32 s17, s5, s52
	s_cselect_b32 s16, s50, s51
	s_mov_b32 m0, s43
	ds_read_b128 v[214:217], v165
	ds_read_b128 v[218:221], v165 offset:1024
	ds_read_b128 v[222:225], v165 offset:2048
	ds_read_b128 v[226:229], v165 offset:3072
	ds_read_b128 v[230:233], v165 offset:4096
	ds_read_b128 v[234:237], v165 offset:5120
	ds_read_b128 v[238:241], v165 offset:6144
	ds_read_b128 v[242:245], v165 offset:7168
	global_load_lds_dwordx4 v136, s[14:15]
	s_mov_b32 m0, s44
	s_nop 0
	global_load_lds_dwordx4 v138, s[14:15]
	s_waitcnt vmcnt(8)
	s_waitcnt lgkmcnt(0)
	s_barrier
	s_setprio 1
	v_mfma_f32_16x16x32_bf16 v[124:127], v[140:143], v[214:217], v[124:127]
	v_mfma_f32_16x16x32_bf16 v[116:119], v[172:175], v[214:217], v[116:119]
	v_mfma_f32_16x16x32_bf16 v[100:103], v[172:175], v[222:225], v[100:103]
	v_mfma_f32_16x16x32_bf16 v[108:111], v[140:143], v[222:225], v[108:111]
	v_mfma_f32_16x16x32_bf16 v[92:95], v[140:143], v[230:233], v[92:95]
	v_mfma_f32_16x16x32_bf16 v[84:87], v[172:175], v[230:233], v[84:87]
	v_mfma_f32_16x16x32_bf16 v[68:71], v[172:175], v[238:241], v[68:71]
	v_mfma_f32_16x16x32_bf16 v[76:79], v[140:143], v[238:241], v[76:79]
	v_mfma_f32_16x16x32_bf16 v[124:127], v[168:171], v[218:221], v[124:127]
	v_mfma_f32_16x16x32_bf16 v[116:119], v[176:179], v[218:221], v[116:119]
	v_mfma_f32_16x16x32_bf16 v[100:103], v[176:179], v[226:229], v[100:103]
	v_mfma_f32_16x16x32_bf16 v[108:111], v[168:171], v[226:229], v[108:111]
	v_mfma_f32_16x16x32_bf16 v[92:95], v[168:171], v[234:237], v[92:95]
	v_mfma_f32_16x16x32_bf16 v[84:87], v[176:179], v[234:237], v[84:87]
	v_mfma_f32_16x16x32_bf16 v[68:71], v[176:179], v[242:245], v[68:71]
	v_mfma_f32_16x16x32_bf16 v[76:79], v[168:171], v[242:245], v[76:79]
	v_mfma_f32_16x16x32_bf16 v[120:123], v[180:183], v[214:217], v[120:123]
	v_mfma_f32_16x16x32_bf16 v[112:115], v[188:191], v[214:217], v[112:115]
	v_mfma_f32_16x16x32_bf16 v[96:99], v[188:191], v[222:225], v[96:99]
	v_mfma_f32_16x16x32_bf16 v[104:107], v[180:183], v[222:225], v[104:107]
	v_mfma_f32_16x16x32_bf16 v[88:91], v[180:183], v[230:233], v[88:91]
	v_mfma_f32_16x16x32_bf16 v[80:83], v[188:191], v[230:233], v[80:83]
	v_mfma_f32_16x16x32_bf16 v[64:67], v[188:191], v[238:241], v[64:67]
	v_mfma_f32_16x16x32_bf16 v[72:75], v[180:183], v[238:241], v[72:75]
	v_mfma_f32_16x16x32_bf16 v[120:123], v[184:187], v[218:221], v[120:123]
	v_mfma_f32_16x16x32_bf16 v[112:115], v[210:213], v[218:221], v[112:115]
	v_mfma_f32_16x16x32_bf16 v[96:99], v[210:213], v[226:229], v[96:99]
	v_mfma_f32_16x16x32_bf16 v[104:107], v[184:187], v[226:229], v[104:107]
	v_mfma_f32_16x16x32_bf16 v[88:91], v[184:187], v[234:237], v[88:91]
	v_mfma_f32_16x16x32_bf16 v[80:83], v[210:213], v[234:237], v[80:83]
	v_mfma_f32_16x16x32_bf16 v[64:67], v[210:213], v[242:245], v[64:67]
	v_mfma_f32_16x16x32_bf16 v[72:75], v[184:187], v[242:245], v[72:75]
	s_setprio 0
	s_barrier
	s_mov_b32 m0, s27
	s_add_u32 s54, s16, 0x40000
	s_addc_u32 s55, s17, 0
	ds_read_b128 v[214:217], v165 offset:16384
	ds_read_b128 v[218:221], v165 offset:17408
	ds_read_b128 v[222:225], v165 offset:18432
	ds_read_b128 v[226:229], v165 offset:19456
	ds_read_b128 v[230:233], v165 offset:20480
	ds_read_b128 v[234:237], v165 offset:21504
	ds_read_b128 v[238:241], v165 offset:22528
	ds_read_b128 v[242:245], v165 offset:23552
	global_load_lds_dwordx4 v132, s[16:17]
	s_mov_b32 m0, s28
	s_nop 0
	global_load_lds_dwordx4 v128, s[16:17]
	s_mov_b32 m0, s29
	s_nop 0
	global_load_lds_dwordx4 v132, s[54:55]
	s_mov_b32 m0, s30
	s_nop 0
	global_load_lds_dwordx4 v128, s[54:55]
	s_mov_b32 m0, s22
	s_nop 0
	global_load_lds_dwordx4 v134, s[18:19]
	s_mov_b32 m0, s31
	s_nop 0
	global_load_lds_dwordx4 v130, s[18:19]
	s_waitcnt vmcnt(8)
	s_waitcnt lgkmcnt(0)
	s_barrier
	s_setprio 1
	v_mfma_f32_16x16x32_bf16 v[60:63], v[140:143], v[214:217], v[60:63]
	v_mfma_f32_16x16x32_bf16 v[52:55], v[172:175], v[214:217], v[52:55]
	v_mfma_f32_16x16x32_bf16 v[36:39], v[172:175], v[222:225], v[36:39]
	v_mfma_f32_16x16x32_bf16 v[44:47], v[140:143], v[222:225], v[44:47]
	v_mfma_f32_16x16x32_bf16 v[28:31], v[140:143], v[230:233], v[28:31]
	v_mfma_f32_16x16x32_bf16 v[20:23], v[172:175], v[230:233], v[20:23]
	v_mfma_f32_16x16x32_bf16 v[4:7], v[172:175], v[238:241], v[4:7]
	v_mfma_f32_16x16x32_bf16 v[12:15], v[140:143], v[238:241], v[12:15]
	v_mfma_f32_16x16x32_bf16 v[60:63], v[168:171], v[218:221], v[60:63]
	v_mfma_f32_16x16x32_bf16 v[52:55], v[176:179], v[218:221], v[52:55]
	v_mfma_f32_16x16x32_bf16 v[36:39], v[176:179], v[226:229], v[36:39]
	v_mfma_f32_16x16x32_bf16 v[44:47], v[168:171], v[226:229], v[44:47]
	v_mfma_f32_16x16x32_bf16 v[28:31], v[168:171], v[234:237], v[28:31]
	v_mfma_f32_16x16x32_bf16 v[20:23], v[176:179], v[234:237], v[20:23]
	v_mfma_f32_16x16x32_bf16 v[4:7], v[176:179], v[242:245], v[4:7]
	v_mfma_f32_16x16x32_bf16 v[12:15], v[168:171], v[242:245], v[12:15]
	v_mfma_f32_16x16x32_bf16 v[56:59], v[180:183], v[214:217], v[56:59]
	v_mfma_f32_16x16x32_bf16 v[48:51], v[188:191], v[214:217], v[48:51]
	v_mfma_f32_16x16x32_bf16 v[32:35], v[188:191], v[222:225], v[32:35]
	v_mfma_f32_16x16x32_bf16 v[40:43], v[180:183], v[222:225], v[40:43]
	v_mfma_f32_16x16x32_bf16 v[24:27], v[180:183], v[230:233], v[24:27]
	v_mfma_f32_16x16x32_bf16 v[16:19], v[188:191], v[230:233], v[16:19]
	v_mfma_f32_16x16x32_bf16 v[0:3], v[188:191], v[238:241], v[0:3]
	v_mfma_f32_16x16x32_bf16 v[8:11], v[180:183], v[238:241], v[8:11]
	v_mfma_f32_16x16x32_bf16 v[56:59], v[184:187], v[218:221], v[56:59]
	v_mfma_f32_16x16x32_bf16 v[48:51], v[210:213], v[218:221], v[48:51]
	v_mfma_f32_16x16x32_bf16 v[32:35], v[210:213], v[226:229], v[32:35]
	v_mfma_f32_16x16x32_bf16 v[40:43], v[184:187], v[226:229], v[40:43]
	v_mfma_f32_16x16x32_bf16 v[24:27], v[184:187], v[234:237], v[24:27]
	v_mfma_f32_16x16x32_bf16 v[16:19], v[210:213], v[234:237], v[16:19]
	v_mfma_f32_16x16x32_bf16 v[0:3], v[210:213], v[242:245], v[0:3]
	v_mfma_f32_16x16x32_bf16 v[8:11], v[184:187], v[242:245], v[8:11]
	s_setprio 0
	s_barrier
; #define PG8_STAGE(bufoff, gbase, voff) do { _Pragma("unroll") for (int _i = 0; _i < 2; ++_i) \
;         __builtin_amdgcn_global_load_lds((const unsigned*)((const char*)(gbase) + (voff)[_i]), (PG8_LAS unsigned*)(lds + (bufoff) + ldsw + _i * 8192), 16, 0, 0); } while (0)
; #define PG8_LDA(dst, b, h) do { _Pragma("unroll") for (int m = 0; m < 4; ++m) _Pragma("unroll") for (int k = 0; k < 2; ++k) dst[m][k] = *(const PG8_LAS bf16x8*)(lds + PG8_SA(b, h) + aoff + m * 2048 + k * 1024); } while (0)
; #define PG8_LDB(dst, b, h) do { _Pragma("unroll") for (int n = 0; n < 2; ++n) _Pragma("unroll") for (int k = 0; k < 2; ++k) dst[n][k] = *(const PG8_LAS bf16x8*)(lds + PG8_SB(b, h) + boff + n * 2048 + k * 1024); } while (0)
; template <class Epi, class Sched, bool ALIGN_EPI = false, bool SP2 = false>
; __device__ __forceinline__ void gemm_phase(PG8_LAS unsigned char* lds, const Gemm g, const Sched& S, const Epi& E) {
;     ...
;         for (int t = 0; t < nt; t += 2) {
;             const bool last = (t == nt - 2);
;             const char* a1 = cA + (size_t)(t + 1) * kstep;
;             const char* a2 = last ? nA : cA + (size_t)(t + 2) * kstep; const char* b2 = last ? nB : cB + (size_t)(t + 2) * kstep;
;             const char* a3 = a2 + kstep; const char* b3 = b2 + kstep;
;             if (last && has_next) S.a_ready(nxt);
;             if constexpr (SP2) {
;             PG8_LDB(B0, 0, 0); PG8_LDB(B1, 0, 1); PG8_SCHED; PG8_LDA(At, 0, 0); PG8_STAGE(PG8_SA(1, 1), a1 + hstep, voffA);
;             PG8_WAIT_V(8); PG8_WAIT_L(0); PG8_BAR; PG8_MMA(0, 0, At, B0); PG8_MMA(0, 1, At, B1); PG8_BAR; PG8_SCHED;
;             PG8_LDA(At, 0, 1); PG8_STAGE(PG8_SB(0, 0), b2, voffB); PG8_STAGE(PG8_SB(0, 1), b2 + hstep, voffB); PG8_STAGE(PG8_SA(0, 0), a2, voffA);
;             PG8_WAIT_V(8); PG8_WAIT_L(0); PG8_BAR; PG8_MMA(1, 0, At, B0); PG8_MMA(1, 1, At, B1); PG8_BAR; PG8_SCHED;
;             PG8_LDB(B0, 1, 0); PG8_LDB(B1, 1, 1); PG8_SCHED; PG8_LDA(At, 1, 0); PG8_STAGE(PG8_SA(0, 1), a2 + hstep, voffA);
;             PG8_WAIT_V(8); PG8_WAIT_L(0); PG8_BAR; PG8_MMA(0, 0, At, B0); PG8_MMA(0, 1, At, B1); PG8_BAR; PG8_SCHED;
;             PG8_LDA(At, 1, 1); PG8_STAGE(PG8_SB(1, 0), b3, voffB); PG8_STAGE(PG8_SB(1, 1), b3 + hstep, voffB); PG8_STAGE(PG8_SA(1, 0), a3, voffA);
;             PG8_WAIT_V(8); PG8_WAIT_L(0); PG8_BAR; PG8_MMA(1, 0, At, B0); PG8_MMA(1, 1, At, B1); PG8_BAR; PG8_SCHED;
	ds_read_b128 v[140:143], v254 offset:32768
	ds_read_b128 v[168:171], v254 offset:33792
	ds_read_b128 v[172:175], v254 offset:34816
	ds_read_b128 v[176:179], v254 offset:35840
	ds_read_b128 v[180:183], v254 offset:49152
	ds_read_b128 v[184:187], v254 offset:50176
	ds_read_b128 v[188:191], v254 offset:51200
	ds_read_b128 v[210:213], v254 offset:52224
	s_add_u32 s18, s18, 0x40000
	s_addc_u32 s19, s19, 0
	s_mov_b32 m0, s33
	ds_read_b128 v[214:217], v165 offset:32768
	ds_read_b128 v[218:221], v165 offset:33792
	ds_read_b128 v[222:225], v165 offset:34816
	ds_read_b128 v[226:229], v165 offset:35840
	ds_read_b128 v[230:233], v165 offset:36864
	ds_read_b128 v[234:237], v165 offset:37888
	ds_read_b128 v[238:241], v165 offset:38912
	ds_read_b128 v[242:245], v165 offset:39936
	global_load_lds_dwordx4 v134, s[18:19]
	s_mov_b32 m0, s34
	s_nop 0
	global_load_lds_dwordx4 v130, s[18:19]
	s_waitcnt vmcnt(8)
	s_waitcnt lgkmcnt(0)
	s_barrier
	s_setprio 1
	v_mfma_f32_16x16x32_bf16 v[124:127], v[140:143], v[214:217], v[124:127]
	v_mfma_f32_16x16x32_bf16 v[116:119], v[172:175], v[214:217], v[116:119]
	v_mfma_f32_16x16x32_bf16 v[100:103], v[172:175], v[222:225], v[100:103]
	v_mfma_f32_16x16x32_bf16 v[108:111], v[140:143], v[222:225], v[108:111]
	v_mfma_f32_16x16x32_bf16 v[92:95], v[140:143], v[230:233], v[92:95]
	v_mfma_f32_16x16x32_bf16 v[84:87], v[172:175], v[230:233], v[84:87]
	v_mfma_f32_16x16x32_bf16 v[68:71], v[172:175], v[238:241], v[68:71]
	v_mfma_f32_16x16x32_bf16 v[76:79], v[140:143], v[238:241], v[76:79]
	v_mfma_f32_16x16x32_bf16 v[124:127], v[168:171], v[218:221], v[124:127]
	v_mfma_f32_16x16x32_bf16 v[116:119], v[176:179], v[218:221], v[116:119]
	v_mfma_f32_16x16x32_bf16 v[100:103], v[176:179], v[226:229], v[100:103]
	v_mfma_f32_16x16x32_bf16 v[108:111], v[168:171], v[226:229], v[108:111]
	v_mfma_f32_16x16x32_bf16 v[92:95], v[168:171], v[234:237], v[92:95]
	v_mfma_f32_16x16x32_bf16 v[84:87], v[176:179], v[234:237], v[84:87]
	v_mfma_f32_16x16x32_bf16 v[68:71], v[176:179], v[242:245], v[68:71]
	v_mfma_f32_16x16x32_bf16 v[76:79], v[168:171], v[242:245], v[76:79]
	v_mfma_f32_16x16x32_bf16 v[120:123], v[180:183], v[214:217], v[120:123]
	v_mfma_f32_16x16x32_bf16 v[112:115], v[188:191], v[214:217], v[112:115]
	v_mfma_f32_16x16x32_bf16 v[96:99], v[188:191], v[222:225], v[96:99]
	v_mfma_f32_16x16x32_bf16 v[104:107], v[180:183], v[222:225], v[104:107]
	v_mfma_f32_16x16x32_bf16 v[88:91], v[180:183], v[230:233], v[88:91]
	v_mfma_f32_16x16x32_bf16 v[80:83], v[188:191], v[230:233], v[80:83]
	v_mfma_f32_16x16x32_bf16 v[64:67], v[188:191], v[238:241], v[64:67]
	v_mfma_f32_16x16x32_bf16 v[72:75], v[180:183], v[238:241], v[72:75]
	v_mfma_f32_16x16x32_bf16 v[120:123], v[184:187], v[218:221], v[120:123]
	v_mfma_f32_16x16x32_bf16 v[112:115], v[210:213], v[218:221], v[112:115]
	v_mfma_f32_16x16x32_bf16 v[96:99], v[210:213], v[226:229], v[96:99]
	v_mfma_f32_16x16x32_bf16 v[104:107], v[184:187], v[226:229], v[104:107]
	v_mfma_f32_16x16x32_bf16 v[88:91], v[184:187], v[234:237], v[88:91]
	v_mfma_f32_16x16x32_bf16 v[80:83], v[210:213], v[234:237], v[80:83]
	v_mfma_f32_16x16x32_bf16 v[64:67], v[210:213], v[242:245], v[64:67]
	v_mfma_f32_16x16x32_bf16 v[72:75], v[184:187], v[242:245], v[72:75]
	s_setprio 0
	s_barrier
	s_mov_b32 m0, s37
	s_add_u32 s16, s16, 0x40080
	s_addc_u32 s17, s17, 0
	ds_read_b128 v[214:217], v165 offset:49152
	ds_read_b128 v[218:221], v165 offset:50176
	ds_read_b128 v[222:225], v165 offset:51200
	ds_read_b128 v[226:229], v165 offset:52224
	ds_read_b128 v[230:233], v165 offset:53248
	ds_read_b128 v[234:237], v165 offset:54272
	ds_read_b128 v[238:241], v165 offset:55296
	ds_read_b128 v[242:245], v165 offset:56320
	s_add_u32 s98, s16, 0xfffc0000
	s_addc_u32 s99, s17, -1
	global_load_lds_dwordx4 v132, s[98:99]
	s_mov_b32 m0, s38
	s_nop 0
	global_load_lds_dwordx4 v128, s[98:99]
	s_mov_b32 m0, s41
	s_nop 0
	global_load_lds_dwordx4 v132, s[16:17]
	s_mov_b32 m0, s42
	s_nop 0
	global_load_lds_dwordx4 v128, s[16:17]
	s_mov_b32 m0, s39
	s_nop 0
	s_add_u32 s100, s18, 0xfffc0080
	s_addc_u32 s101, s19, -1
	global_load_lds_dwordx4 v134, s[100:101]
	s_mov_b32 m0, s40
	s_nop 0
	global_load_lds_dwordx4 v130, s[100:101]
	s_waitcnt vmcnt(8)
	s_waitcnt lgkmcnt(0)
	s_barrier
	s_setprio 1
	v_mfma_f32_16x16x32_bf16 v[60:63], v[140:143], v[214:217], v[60:63]
	v_mfma_f32_16x16x32_bf16 v[52:55], v[172:175], v[214:217], v[52:55]
	v_mfma_f32_16x16x32_bf16 v[36:39], v[172:175], v[222:225], v[36:39]
	v_mfma_f32_16x16x32_bf16 v[44:47], v[140:143], v[222:225], v[44:47]
	v_mfma_f32_16x16x32_bf16 v[28:31], v[140:143], v[230:233], v[28:31]
	v_mfma_f32_16x16x32_bf16 v[20:23], v[172:175], v[230:233], v[20:23]
	v_mfma_f32_16x16x32_bf16 v[4:7], v[172:175], v[238:241], v[4:7]
	v_mfma_f32_16x16x32_bf16 v[12:15], v[140:143], v[238:241], v[12:15]
	v_mfma_f32_16x16x32_bf16 v[60:63], v[168:171], v[218:221], v[60:63]
	v_mfma_f32_16x16x32_bf16 v[52:55], v[176:179], v[218:221], v[52:55]
	v_mfma_f32_16x16x32_bf16 v[36:39], v[176:179], v[226:229], v[36:39]
	v_mfma_f32_16x16x32_bf16 v[44:47], v[168:171], v[226:229], v[44:47]
	v_mfma_f32_16x16x32_bf16 v[28:31], v[168:171], v[234:237], v[28:31]
	v_mfma_f32_16x16x32_bf16 v[20:23], v[176:179], v[234:237], v[20:23]
	v_mfma_f32_16x16x32_bf16 v[4:7], v[176:179], v[242:245], v[4:7]
	v_mfma_f32_16x16x32_bf16 v[12:15], v[168:171], v[242:245], v[12:15]
	v_mfma_f32_16x16x32_bf16 v[56:59], v[180:183], v[214:217], v[56:59]
	v_mfma_f32_16x16x32_bf16 v[48:51], v[188:191], v[214:217], v[48:51]
	v_mfma_f32_16x16x32_bf16 v[32:35], v[188:191], v[222:225], v[32:35]
	v_mfma_f32_16x16x32_bf16 v[40:43], v[180:183], v[222:225], v[40:43]
	v_mfma_f32_16x16x32_bf16 v[24:27], v[180:183], v[230:233], v[24:27]
	v_mfma_f32_16x16x32_bf16 v[16:19], v[188:191], v[230:233], v[16:19]
	v_mfma_f32_16x16x32_bf16 v[0:3], v[188:191], v[238:241], v[0:3]
	v_mfma_f32_16x16x32_bf16 v[8:11], v[180:183], v[238:241], v[8:11]
	v_mfma_f32_16x16x32_bf16 v[56:59], v[184:187], v[218:221], v[56:59]
	v_mfma_f32_16x16x32_bf16 v[48:51], v[210:213], v[218:221], v[48:51]
	v_mfma_f32_16x16x32_bf16 v[32:35], v[210:213], v[226:229], v[32:35]
	v_mfma_f32_16x16x32_bf16 v[40:43], v[184:187], v[226:229], v[40:43]
	v_mfma_f32_16x16x32_bf16 v[24:27], v[184:187], v[234:237], v[24:27]
	v_mfma_f32_16x16x32_bf16 v[16:19], v[210:213], v[234:237], v[16:19]
	v_mfma_f32_16x16x32_bf16 v[0:3], v[210:213], v[242:245], v[0:3]
	v_mfma_f32_16x16x32_bf16 v[8:11], v[184:187], v[242:245], v[8:11]
	s_setprio 0
	s_barrier
	s_add_i32 s53, s53, 2
	s_add_u32 s14, s14, 0x100
	s_addc_u32 s15, s15, 0
	s_add_u32 s51, s51, 0x100
	s_addc_u32 s52, s52, 0
	s_cmp_gt_u32 s53, 13
	s_cbranch_scc0 .LBB0_446
	s_and_b64 vcc, exec, s[2:3]
	s_cbranch_vccz .LBB0_449
	s_barrier

; #define PG8_STAGE(bufoff, gbase, voff) do { _Pragma("unroll") for (int _i = 0; _i < 2; ++_i) \
;         __builtin_amdgcn_global_load_lds((const unsigned*)((const char*)(gbase) + (voff)[_i]), (PG8_LAS unsigned*)(lds + (bufoff) + ldsw + _i * 8192), 16, 0, 0); } while (0)
; #define PG8_LDA(dst, b, h) do { _Pragma("unroll") for (int m = 0; m < 4; ++m) _Pragma("unroll") for (int k = 0; k < 2; ++k) dst[m][k] = *(const PG8_LAS bf16x8*)(lds + PG8_SA(b, h) + aoff + m * 2048 + k * 1024); } while (0)
; #define PG8_LDB(dst, b, h) do { _Pragma("unroll") for (int n = 0; n < 2; ++n) _Pragma("unroll") for (int k = 0; k < 2; ++k) dst[n][k] = *(const PG8_LAS bf16x8*)(lds + PG8_SB(b, h) + boff + n * 2048 + k * 1024); } while (0)
; #define PG8_MMA(ai, bj, At, Bt) do { __builtin_amdgcn_s_setprio(1); _Pragma("unroll") for (int m = 0; m < 4; ++m) _Pragma("unroll") for (int n = 0; n < 2; ++n) _Pragma("unroll") for (int k = 0; k < 2; ++k) \
;         acc[ai][bj][m][n] = __builtin_amdgcn_mfma_f32_16x16x32_bf16(Bt[n][k], At[m][k], acc[ai][bj][m][n], 0, 0, 0); __builtin_amdgcn_s_setprio(0); } while (0)
; #define PG8_WAIT_V(n) asm volatile("s_waitcnt vmcnt(" #n ")" ::: "memory")
; #define PG8_BAR __builtin_amdgcn_s_barrier()
; template <class Epi, class Sched, bool ALIGN_EPI = false, bool SP2 = false>
; __device__ __forceinline__ void gemm_phase(PG8_LAS unsigned char* lds, const Gemm g, const Sched& S, const Epi& E) {
;     ...
;         for (int t = 0; t < nt; t += 2) {
;             const bool last = (t == nt - 2);
;             const char* a1 = cA + (size_t)(t + 1) * kstep;
;             const char* a2 = last ? nA : cA + (size_t)(t + 2) * kstep; const char* b2 = last ? nB : cB + (size_t)(t + 2) * kstep;
;             const char* a3 = a2 + kstep; const char* b3 = b2 + kstep;
;             if (last && has_next) S.a_ready(nxt);
;             if constexpr (SP2) {
;             PG8_LDB(B0, 0, 0); PG8_LDB(B1, 0, 1); PG8_SCHED; PG8_LDA(At, 0, 0); PG8_STAGE(PG8_SA(1, 1), a1 + hstep, voffA);
;             PG8_WAIT_V(8); PG8_WAIT_L(0); PG8_BAR; PG8_MMA(0, 0, At, B0); PG8_MMA(0, 1, At, B1); PG8_BAR; PG8_SCHED;
;             PG8_LDA(At, 0, 1); PG8_STAGE(PG8_SB(0, 0), b2, voffB); PG8_STAGE(PG8_SB(0, 1), b2 + hstep, voffB); PG8_STAGE(PG8_SA(0, 0), a2, voffA);
;             PG8_WAIT_V(8); PG8_WAIT_L(0); PG8_BAR; PG8_MMA(1, 0, At, B0); PG8_MMA(1, 1, At, B1); PG8_BAR; PG8_SCHED;
.Ldn_peel:
	ds_read_b128 v[128:131], v254
	ds_read_b128 v[132:135], v254 offset:1024
	ds_read_b128 v[136:139], v254 offset:2048
	ds_read_b128 v[140:143], v254 offset:3072
	ds_read_b128 v[174:177], v254 offset:16384
	ds_read_b128 v[184:187], v254 offset:17408
	ds_read_b128 v[188:191], v254 offset:18432
	ds_read_b128 v[210:213], v254 offset:19456
	s_add_u32 s2, s0, 0x100
	s_addc_u32 s3, s1, 0
	s_cmp_eq_u32 s13, 40
	s_cselect_b32 s7, s27, s3
	s_cselect_b32 s6, s26, s2
	s_cselect_b32 s5, s37, s11
	s_cselect_b32 s4, s36, s10
	s_add_i32 m0, s29, 0xc000
	ds_read_b128 v[214:217], v181
	ds_read_b128 v[218:221], v181 offset:1024
	ds_read_b128 v[222:225], v181 offset:2048
	ds_read_b128 v[226:229], v181 offset:3072
	ds_read_b128 v[230:233], v181 offset:4096
	ds_read_b128 v[234:237], v181 offset:5120
	ds_read_b128 v[238:241], v181 offset:6144
	ds_read_b128 v[242:245], v181 offset:7168
	global_load_lds_dwordx4 v170, s[0:1]
	s_add_i32 m0, s29, 0xe000
	s_nop 0
	global_load_lds_dwordx4 v172, s[0:1]
	s_waitcnt vmcnt(8)
	s_waitcnt lgkmcnt(0)
	s_barrier
	s_setprio 1
	v_mfma_f32_16x16x32_bf16 v[124:127], v[128:131], v[214:217], 0
	v_mfma_f32_16x16x32_bf16 v[120:123], v[136:139], v[214:217], 0
	v_mfma_f32_16x16x32_bf16 v[104:107], v[136:139], v[222:225], 0
	v_mfma_f32_16x16x32_bf16 v[108:111], v[128:131], v[222:225], 0
	v_mfma_f32_16x16x32_bf16 v[92:95], v[128:131], v[230:233], 0
	v_mfma_f32_16x16x32_bf16 v[88:91], v[136:139], v[230:233], 0
	v_mfma_f32_16x16x32_bf16 v[72:75], v[136:139], v[238:241], 0
	v_mfma_f32_16x16x32_bf16 v[76:79], v[128:131], v[238:241], 0
	v_mfma_f32_16x16x32_bf16 v[124:127], v[132:135], v[218:221], v[124:127]
	v_mfma_f32_16x16x32_bf16 v[120:123], v[140:143], v[218:221], v[120:123]
	v_mfma_f32_16x16x32_bf16 v[104:107], v[140:143], v[226:229], v[104:107]
	v_mfma_f32_16x16x32_bf16 v[108:111], v[132:135], v[226:229], v[108:111]
	v_mfma_f32_16x16x32_bf16 v[92:95], v[132:135], v[234:237], v[92:95]
	v_mfma_f32_16x16x32_bf16 v[88:91], v[140:143], v[234:237], v[88:91]
	v_mfma_f32_16x16x32_bf16 v[72:75], v[140:143], v[242:245], v[72:75]
	v_mfma_f32_16x16x32_bf16 v[76:79], v[132:135], v[242:245], v[76:79]
	v_mfma_f32_16x16x32_bf16 v[116:119], v[174:177], v[214:217], 0
	v_mfma_f32_16x16x32_bf16 v[112:115], v[188:191], v[214:217], 0
	v_mfma_f32_16x16x32_bf16 v[96:99], v[188:191], v[222:225], 0
	v_mfma_f32_16x16x32_bf16 v[100:103], v[174:177], v[222:225], 0
	v_mfma_f32_16x16x32_bf16 v[84:87], v[174:177], v[230:233], 0
	v_mfma_f32_16x16x32_bf16 v[80:83], v[188:191], v[230:233], 0
	v_mfma_f32_16x16x32_bf16 v[64:67], v[188:191], v[238:241], 0
	v_mfma_f32_16x16x32_bf16 v[68:71], v[174:177], v[238:241], 0
	v_mfma_f32_16x16x32_bf16 v[116:119], v[184:187], v[218:221], v[116:119]
	v_mfma_f32_16x16x32_bf16 v[112:115], v[210:213], v[218:221], v[112:115]
	v_mfma_f32_16x16x32_bf16 v[96:99], v[210:213], v[226:229], v[96:99]
	v_mfma_f32_16x16x32_bf16 v[100:103], v[184:187], v[226:229], v[100:103]
	v_mfma_f32_16x16x32_bf16 v[84:87], v[184:187], v[234:237], v[84:87]
	v_mfma_f32_16x16x32_bf16 v[80:83], v[210:213], v[234:237], v[80:83]
	v_mfma_f32_16x16x32_bf16 v[64:67], v[210:213], v[242:245], v[64:67]
	v_mfma_f32_16x16x32_bf16 v[68:71], v[184:187], v[242:245], v[68:71]
	s_setprio 0
	s_barrier
	s_mov_b32 m0, s35
	s_add_u32 s0, s4, 0xb0000
	s_addc_u32 s1, s5, 0
	ds_read_b128 v[214:217], v181 offset:16384
	ds_read_b128 v[218:221], v181 offset:17408
	ds_read_b128 v[222:225], v181 offset:18432
	ds_read_b128 v[226:229], v181 offset:19456
	ds_read_b128 v[230:233], v181 offset:20480
	ds_read_b128 v[234:237], v181 offset:21504
	ds_read_b128 v[238:241], v181 offset:22528
	ds_read_b128 v[242:245], v181 offset:23552
	global_load_lds_dwordx4 v166, s[4:5]
	s_mov_b32 m0, s38
	s_nop 0
	global_load_lds_dwordx4 v162, s[4:5]
	s_mov_b32 m0, s39
	s_nop 0
	global_load_lds_dwordx4 v166, s[0:1]
	s_mov_b32 m0, s40
	s_nop 0
	global_load_lds_dwordx4 v162, s[0:1]
	s_mov_b32 m0, s29
	s_nop 0
	global_load_lds_dwordx4 v168, s[6:7]
	s_mov_b32 m0, s41
	s_nop 0
	global_load_lds_dwordx4 v164, s[6:7]
	s_waitcnt vmcnt(8)
	s_waitcnt lgkmcnt(0)
	s_barrier
	s_setprio 1
	v_mfma_f32_16x16x32_bf16 v[60:63], v[128:131], v[214:217], 0
	v_mfma_f32_16x16x32_bf16 v[56:59], v[136:139], v[214:217], 0
	v_mfma_f32_16x16x32_bf16 v[40:43], v[136:139], v[222:225], 0
	v_mfma_f32_16x16x32_bf16 v[44:47], v[128:131], v[222:225], 0
	v_mfma_f32_16x16x32_bf16 v[28:31], v[128:131], v[230:233], 0
	v_mfma_f32_16x16x32_bf16 v[24:27], v[136:139], v[230:233], 0
	v_mfma_f32_16x16x32_bf16 v[8:11], v[136:139], v[238:241], 0
	v_mfma_f32_16x16x32_bf16 v[12:15], v[128:131], v[238:241], 0
	v_mfma_f32_16x16x32_bf16 v[60:63], v[132:135], v[218:221], v[60:63]
	v_mfma_f32_16x16x32_bf16 v[56:59], v[140:143], v[218:221], v[56:59]
	v_mfma_f32_16x16x32_bf16 v[40:43], v[140:143], v[226:229], v[40:43]
	v_mfma_f32_16x16x32_bf16 v[44:47], v[132:135], v[226:229], v[44:47]
	v_mfma_f32_16x16x32_bf16 v[28:31], v[132:135], v[234:237], v[28:31]
	v_mfma_f32_16x16x32_bf16 v[24:27], v[140:143], v[234:237], v[24:27]
	v_mfma_f32_16x16x32_bf16 v[8:11], v[140:143], v[242:245], v[8:11]
	v_mfma_f32_16x16x32_bf16 v[12:15], v[132:135], v[242:245], v[12:15]
	v_mfma_f32_16x16x32_bf16 v[52:55], v[174:177], v[214:217], 0
	v_mfma_f32_16x16x32_bf16 v[48:51], v[188:191], v[214:217], 0
	v_mfma_f32_16x16x32_bf16 v[32:35], v[188:191], v[222:225], 0
	v_mfma_f32_16x16x32_bf16 v[36:39], v[174:177], v[222:225], 0
	v_mfma_f32_16x16x32_bf16 v[20:23], v[174:177], v[230:233], 0
	v_mfma_f32_16x16x32_bf16 v[16:19], v[188:191], v[230:233], 0
	v_mfma_f32_16x16x32_bf16 v[0:3], v[188:191], v[238:241], 0
	v_mfma_f32_16x16x32_bf16 v[4:7], v[174:177], v[238:241], 0
	v_mfma_f32_16x16x32_bf16 v[52:55], v[184:187], v[218:221], v[52:55]
	v_mfma_f32_16x16x32_bf16 v[48:51], v[210:213], v[218:221], v[48:51]
	v_mfma_f32_16x16x32_bf16 v[32:35], v[210:213], v[226:229], v[32:35]
	v_mfma_f32_16x16x32_bf16 v[36:39], v[184:187], v[226:229], v[36:39]
	v_mfma_f32_16x16x32_bf16 v[20:23], v[184:187], v[234:237], v[20:23]
	v_mfma_f32_16x16x32_bf16 v[16:19], v[210:213], v[234:237], v[16:19]
	v_mfma_f32_16x16x32_bf16 v[0:3], v[210:213], v[242:245], v[0:3]
	v_mfma_f32_16x16x32_bf16 v[4:7], v[184:187], v[242:245], v[4:7]
	s_setprio 0
	s_barrier
; #define PG8_STAGE(bufoff, gbase, voff) do { _Pragma("unroll") for (int _i = 0; _i < 2; ++_i) \
;         __builtin_amdgcn_global_load_lds((const unsigned*)((const char*)(gbase) + (voff)[_i]), (PG8_LAS unsigned*)(lds + (bufoff) + ldsw + _i * 8192), 16, 0, 0); } while (0)
; #define PG8_LDA(dst, b, h) do { _Pragma("unroll") for (int m = 0; m < 4; ++m) _Pragma("unroll") for (int k = 0; k < 2; ++k) dst[m][k] = *(const PG8_LAS bf16x8*)(lds + PG8_SA(b, h) + aoff + m * 2048 + k * 1024); } while (0)
; #define PG8_LDB(dst, b, h) do { _Pragma("unroll") for (int n = 0; n < 2; ++n) _Pragma("unroll") for (int k = 0; k < 2; ++k) dst[n][k] = *(const PG8_LAS bf16x8*)(lds + PG8_SB(b, h) + boff + n * 2048 + k * 1024); } while (0)
; #define PG8_MMA(ai, bj, At, Bt) do { __builtin_amdgcn_s_setprio(1); _Pragma("unroll") for (int m = 0; m < 4; ++m) _Pragma("unroll") for (int n = 0; n < 2; ++n) _Pragma("unroll") for (int k = 0; k < 2; ++k) \
;         acc[ai][bj][m][n] = __builtin_amdgcn_mfma_f32_16x16x32_bf16(Bt[n][k], At[m][k], acc[ai][bj][m][n], 0, 0, 0); __builtin_amdgcn_s_setprio(0); } while (0)
; #define PG8_WAIT_V(n) asm volatile("s_waitcnt vmcnt(" #n ")" ::: "memory")
; #define PG8_WAIT_L(n) asm volatile("s_waitcnt lgkmcnt(" #n ")" ::: "memory")
; #define PG8_BAR __builtin_amdgcn_s_barrier()
; #define PG8_SCHED __builtin_amdgcn_sched_barrier(0)
; template <class Epi, class Sched, bool ALIGN_EPI = false, bool SP2 = false>
; __device__ __forceinline__ void gemm_phase(PG8_LAS unsigned char* lds, const Gemm g, const Sched& S, const Epi& E) {
;     ...
;             PG8_LDB(B0, 1, 0); PG8_LDB(B1, 1, 1); PG8_SCHED; PG8_LDA(At, 1, 0); PG8_STAGE(PG8_SA(0, 1), a2 + hstep, voffA);
;             PG8_WAIT_V(8); PG8_WAIT_L(0); PG8_BAR; PG8_MMA(0, 0, At, B0); PG8_MMA(0, 1, At, B1); PG8_BAR; PG8_SCHED;
;             PG8_LDA(At, 1, 1); PG8_STAGE(PG8_SB(1, 0), b3, voffB); PG8_STAGE(PG8_SB(1, 1), b3 + hstep, voffB); PG8_STAGE(PG8_SA(1, 0), a3, voffA);
;             PG8_WAIT_V(8); PG8_WAIT_L(0); PG8_BAR; PG8_MMA(1, 0, At, B0); PG8_MMA(1, 1, At, B1); PG8_BAR; PG8_SCHED;
	ds_read_b128 v[128:131], v254 offset:32768
	ds_read_b128 v[132:135], v254 offset:33792
	ds_read_b128 v[136:139], v254 offset:34816
	ds_read_b128 v[140:143], v254 offset:35840
	ds_read_b128 v[174:177], v254 offset:49152
	ds_read_b128 v[184:187], v254 offset:50176
	ds_read_b128 v[188:191], v254 offset:51200
	ds_read_b128 v[210:213], v254 offset:52224
	s_add_u32 s0, s6, 0xb0000
	s_addc_u32 s1, s7, 0
	s_mov_b32 m0, s42
	ds_read_b128 v[214:217], v181 offset:32768
	ds_read_b128 v[218:221], v181 offset:33792
	ds_read_b128 v[222:225], v181 offset:34816
	ds_read_b128 v[226:229], v181 offset:35840
	ds_read_b128 v[230:233], v181 offset:36864
	ds_read_b128 v[234:237], v181 offset:37888
	ds_read_b128 v[238:241], v181 offset:38912
	ds_read_b128 v[242:245], v181 offset:39936
	global_load_lds_dwordx4 v168, s[0:1]
	s_mov_b32 m0, s43
	s_nop 0
	global_load_lds_dwordx4 v164, s[0:1]
	s_waitcnt vmcnt(8)
	s_waitcnt lgkmcnt(0)
	s_barrier
	s_setprio 1
	v_mfma_f32_16x16x32_bf16 v[124:127], v[128:131], v[214:217], v[124:127]
	v_mfma_f32_16x16x32_bf16 v[120:123], v[136:139], v[214:217], v[120:123]
	v_mfma_f32_16x16x32_bf16 v[104:107], v[136:139], v[222:225], v[104:107]
	v_mfma_f32_16x16x32_bf16 v[108:111], v[128:131], v[222:225], v[108:111]
	v_mfma_f32_16x16x32_bf16 v[92:95], v[128:131], v[230:233], v[92:95]
	v_mfma_f32_16x16x32_bf16 v[88:91], v[136:139], v[230:233], v[88:91]
	v_mfma_f32_16x16x32_bf16 v[72:75], v[136:139], v[238:241], v[72:75]
	v_mfma_f32_16x16x32_bf16 v[76:79], v[128:131], v[238:241], v[76:79]
	v_mfma_f32_16x16x32_bf16 v[124:127], v[132:135], v[218:221], v[124:127]
	v_mfma_f32_16x16x32_bf16 v[120:123], v[140:143], v[218:221], v[120:123]
	v_mfma_f32_16x16x32_bf16 v[104:107], v[140:143], v[226:229], v[104:107]
	v_mfma_f32_16x16x32_bf16 v[108:111], v[132:135], v[226:229], v[108:111]
	v_mfma_f32_16x16x32_bf16 v[92:95], v[132:135], v[234:237], v[92:95]
	v_mfma_f32_16x16x32_bf16 v[88:91], v[140:143], v[234:237], v[88:91]
	v_mfma_f32_16x16x32_bf16 v[72:75], v[140:143], v[242:245], v[72:75]
	v_mfma_f32_16x16x32_bf16 v[76:79], v[132:135], v[242:245], v[76:79]
	v_mfma_f32_16x16x32_bf16 v[116:119], v[174:177], v[214:217], v[116:119]
	v_mfma_f32_16x16x32_bf16 v[112:115], v[188:191], v[214:217], v[112:115]
	v_mfma_f32_16x16x32_bf16 v[96:99], v[188:191], v[222:225], v[96:99]
	v_mfma_f32_16x16x32_bf16 v[100:103], v[174:177], v[222:225], v[100:103]
	v_mfma_f32_16x16x32_bf16 v[84:87], v[174:177], v[230:233], v[84:87]
	v_mfma_f32_16x16x32_bf16 v[80:83], v[188:191], v[230:233], v[80:83]
	v_mfma_f32_16x16x32_bf16 v[64:67], v[188:191], v[238:241], v[64:67]
	v_mfma_f32_16x16x32_bf16 v[68:71], v[174:177], v[238:241], v[68:71]
	v_mfma_f32_16x16x32_bf16 v[116:119], v[184:187], v[218:221], v[116:119]
	v_mfma_f32_16x16x32_bf16 v[112:115], v[210:213], v[218:221], v[112:115]
	v_mfma_f32_16x16x32_bf16 v[96:99], v[210:213], v[226:229], v[96:99]
	v_mfma_f32_16x16x32_bf16 v[100:103], v[184:187], v[226:229], v[100:103]
	v_mfma_f32_16x16x32_bf16 v[84:87], v[184:187], v[234:237], v[84:87]
	v_mfma_f32_16x16x32_bf16 v[80:83], v[210:213], v[234:237], v[80:83]
	v_mfma_f32_16x16x32_bf16 v[64:67], v[210:213], v[242:245], v[64:67]
	v_mfma_f32_16x16x32_bf16 v[68:71], v[184:187], v[242:245], v[68:71]
	s_setprio 0
	s_barrier
	s_mov_b32 m0, s47
	s_add_u32 s0, s4, 0xb0080
	s_addc_u32 s1, s5, 0
	ds_read_b128 v[214:217], v181 offset:49152
	ds_read_b128 v[218:221], v181 offset:50176
	ds_read_b128 v[222:225], v181 offset:51200
	ds_read_b128 v[226:229], v181 offset:52224
	ds_read_b128 v[230:233], v181 offset:53248
	ds_read_b128 v[234:237], v181 offset:54272
	ds_read_b128 v[238:241], v181 offset:55296
	ds_read_b128 v[242:245], v181 offset:56320
	s_add_u32 s98, s4, 0x80
	s_addc_u32 s99, s5, 0
	global_load_lds_dwordx4 v166, s[98:99]
	s_mov_b32 m0, s48
	s_nop 0
	global_load_lds_dwordx4 v162, s[98:99]
	s_mov_b32 m0, s51
	s_nop 0
	global_load_lds_dwordx4 v166, s[0:1]
	s_mov_b32 m0, s52
	s_nop 0
	global_load_lds_dwordx4 v162, s[0:1]
	s_mov_b32 m0, s49
	s_nop 0
	s_add_u32 s100, s6, 0x80
	s_addc_u32 s101, s7, 0
	global_load_lds_dwordx4 v168, s[100:101]
	s_mov_b32 m0, s50
	s_nop 0
	global_load_lds_dwordx4 v164, s[100:101]
	s_waitcnt vmcnt(8)
	s_waitcnt lgkmcnt(0)
	s_barrier
	s_setprio 1
	v_mfma_f32_16x16x32_bf16 v[60:63], v[128:131], v[214:217], v[60:63]
	v_mfma_f32_16x16x32_bf16 v[56:59], v[136:139], v[214:217], v[56:59]
	v_mfma_f32_16x16x32_bf16 v[40:43], v[136:139], v[222:225], v[40:43]
	v_mfma_f32_16x16x32_bf16 v[44:47], v[128:131], v[222:225], v[44:47]
	v_mfma_f32_16x16x32_bf16 v[28:31], v[128:131], v[230:233], v[28:31]
	v_mfma_f32_16x16x32_bf16 v[24:27], v[136:139], v[230:233], v[24:27]
	v_mfma_f32_16x16x32_bf16 v[8:11], v[136:139], v[238:241], v[8:11]
	v_mfma_f32_16x16x32_bf16 v[12:15], v[128:131], v[238:241], v[12:15]
	v_mfma_f32_16x16x32_bf16 v[60:63], v[132:135], v[218:221], v[60:63]
	v_mfma_f32_16x16x32_bf16 v[56:59], v[140:143], v[218:221], v[56:59]
	v_mfma_f32_16x16x32_bf16 v[40:43], v[140:143], v[226:229], v[40:43]
	v_mfma_f32_16x16x32_bf16 v[44:47], v[132:135], v[226:229], v[44:47]
	v_mfma_f32_16x16x32_bf16 v[28:31], v[132:135], v[234:237], v[28:31]
	v_mfma_f32_16x16x32_bf16 v[24:27], v[140:143], v[234:237], v[24:27]
	v_mfma_f32_16x16x32_bf16 v[8:11], v[140:143], v[242:245], v[8:11]
	v_mfma_f32_16x16x32_bf16 v[12:15], v[132:135], v[242:245], v[12:15]
	v_mfma_f32_16x16x32_bf16 v[52:55], v[174:177], v[214:217], v[52:55]
	v_mfma_f32_16x16x32_bf16 v[48:51], v[188:191], v[214:217], v[48:51]
	v_mfma_f32_16x16x32_bf16 v[32:35], v[188:191], v[222:225], v[32:35]
	v_mfma_f32_16x16x32_bf16 v[36:39], v[174:177], v[222:225], v[36:39]
	v_mfma_f32_16x16x32_bf16 v[20:23], v[174:177], v[230:233], v[20:23]
	v_mfma_f32_16x16x32_bf16 v[16:19], v[188:191], v[230:233], v[16:19]
	v_mfma_f32_16x16x32_bf16 v[0:3], v[188:191], v[238:241], v[0:3]
	v_mfma_f32_16x16x32_bf16 v[4:7], v[174:177], v[238:241], v[4:7]
	v_mfma_f32_16x16x32_bf16 v[52:55], v[184:187], v[218:221], v[52:55]
	v_mfma_f32_16x16x32_bf16 v[48:51], v[210:213], v[218:221], v[48:51]
	v_mfma_f32_16x16x32_bf16 v[32:35], v[210:213], v[226:229], v[32:35]
	v_mfma_f32_16x16x32_bf16 v[36:39], v[184:187], v[226:229], v[36:39]
	v_mfma_f32_16x16x32_bf16 v[20:23], v[184:187], v[234:237], v[20:23]
	v_mfma_f32_16x16x32_bf16 v[16:19], v[210:213], v[234:237], v[16:19]
	v_mfma_f32_16x16x32_bf16 v[0:3], v[210:213], v[242:245], v[0:3]
	v_mfma_f32_16x16x32_bf16 v[4:7], v[184:187], v[242:245], v[4:7]
	s_setprio 0
	s_barrier
	s_add_i32 s13, s13, 2
	s_add_u32 s10, s10, 0x100
	s_addc_u32 s11, s11, 0
	s_cmp_gt_u32 s13, 41
	s_mov_b64 s[0:1], s[2:3]
; #define PG8_STAGE(bufoff, gbase, voff) do { _Pragma("unroll") for (int _i = 0; _i < 2; ++_i) \
;         __builtin_amdgcn_global_load_lds((const unsigned*)((const char*)(gbase) + (voff)[_i]), (PG8_LAS unsigned*)(lds + (bufoff) + ldsw + _i * 8192), 16, 0, 0); } while (0)
; #define PG8_LDA(dst, b, h) do { _Pragma("unroll") for (int m = 0; m < 4; ++m) _Pragma("unroll") for (int k = 0; k < 2; ++k) dst[m][k] = *(const PG8_LAS bf16x8*)(lds + PG8_SA(b, h) + aoff + m * 2048 + k * 1024); } while (0)
; #define PG8_LDB(dst, b, h) do { _Pragma("unroll") for (int n = 0; n < 2; ++n) _Pragma("unroll") for (int k = 0; k < 2; ++k) dst[n][k] = *(const PG8_LAS bf16x8*)(lds + PG8_SB(b, h) + boff + n * 2048 + k * 1024); } while (0)
; #define PG8_MMA(ai, bj, At, Bt) do { __builtin_amdgcn_s_setprio(1); _Pragma("unroll") for (int m = 0; m < 4; ++m) _Pragma("unroll") for (int n = 0; n < 2; ++n) _Pragma("unroll") for (int k = 0; k < 2; ++k) \
;         acc[ai][bj][m][n] = __builtin_amdgcn_mfma_f32_16x16x32_bf16(Bt[n][k], At[m][k], acc[ai][bj][m][n], 0, 0, 0); __builtin_amdgcn_s_setprio(0); } while (0)
; #define PG8_WAIT_V(n) asm volatile("s_waitcnt vmcnt(" #n ")" ::: "memory")
; #define PG8_BAR __builtin_amdgcn_s_barrier()
; template <class Epi, class Sched, bool ALIGN_EPI = false, bool SP2 = false>
; __device__ __forceinline__ void gemm_phase(PG8_LAS unsigned char* lds, const Gemm g, const Sched& S, const Epi& E) {
;     ...
;         for (int t = 0; t < nt; t += 2) {
;             const bool last = (t == nt - 2);
;             const char* a1 = cA + (size_t)(t + 1) * kstep;
;             const char* a2 = last ? nA : cA + (size_t)(t + 2) * kstep; const char* b2 = last ? nB : cB + (size_t)(t + 2) * kstep;
;             const char* a3 = a2 + kstep; const char* b3 = b2 + kstep;
;             if (last && has_next) S.a_ready(nxt);
;             if constexpr (SP2) {
;             PG8_LDB(B0, 0, 0); PG8_LDB(B1, 0, 1); PG8_SCHED; PG8_LDA(At, 0, 0); PG8_STAGE(PG8_SA(1, 1), a1 + hstep, voffA);
;             PG8_WAIT_V(8); PG8_WAIT_L(0); PG8_BAR; PG8_MMA(0, 0, At, B0); PG8_MMA(0, 1, At, B1); PG8_BAR; PG8_SCHED;
;             PG8_LDA(At, 0, 1); PG8_STAGE(PG8_SB(0, 0), b2, voffB); PG8_STAGE(PG8_SB(0, 1), b2 + hstep, voffB); PG8_STAGE(PG8_SA(0, 0), a2, voffA);
;             PG8_WAIT_V(8); PG8_WAIT_L(0); PG8_BAR; PG8_MMA(1, 0, At, B0); PG8_MMA(1, 1, At, B1); PG8_BAR; PG8_SCHED;
.LBB0_545:
	ds_read_b128 v[128:131], v254
	ds_read_b128 v[132:135], v254 offset:1024
	ds_read_b128 v[136:139], v254 offset:2048
	ds_read_b128 v[140:143], v254 offset:3072
	ds_read_b128 v[174:177], v254 offset:16384
	ds_read_b128 v[184:187], v254 offset:17408
	ds_read_b128 v[188:191], v254 offset:18432
	ds_read_b128 v[210:213], v254 offset:19456
	s_add_u32 s2, s0, 0x100
	s_addc_u32 s3, s1, 0
	s_cmp_eq_u32 s13, 40
	s_cselect_b32 s7, s27, s3
	s_cselect_b32 s6, s26, s2
	s_cselect_b32 s5, s37, s11
	s_cselect_b32 s4, s36, s10
	s_add_i32 m0, s29, 0xc000
	ds_read_b128 v[214:217], v181
	ds_read_b128 v[218:221], v181 offset:1024
	ds_read_b128 v[222:225], v181 offset:2048
	ds_read_b128 v[226:229], v181 offset:3072
	ds_read_b128 v[230:233], v181 offset:4096
	ds_read_b128 v[234:237], v181 offset:5120
	ds_read_b128 v[238:241], v181 offset:6144
	ds_read_b128 v[242:245], v181 offset:7168
	global_load_lds_dwordx4 v170, s[0:1]
	s_add_i32 m0, s29, 0xe000
	s_nop 0
	global_load_lds_dwordx4 v172, s[0:1]
	s_waitcnt vmcnt(8)
	s_waitcnt lgkmcnt(0)
	s_barrier
	s_setprio 1
	v_mfma_f32_16x16x32_bf16 v[124:127], v[128:131], v[214:217], v[124:127]
	v_mfma_f32_16x16x32_bf16 v[120:123], v[136:139], v[214:217], v[120:123]
	v_mfma_f32_16x16x32_bf16 v[104:107], v[136:139], v[222:225], v[104:107]
	v_mfma_f32_16x16x32_bf16 v[108:111], v[128:131], v[222:225], v[108:111]
	v_mfma_f32_16x16x32_bf16 v[92:95], v[128:131], v[230:233], v[92:95]
	v_mfma_f32_16x16x32_bf16 v[88:91], v[136:139], v[230:233], v[88:91]
	v_mfma_f32_16x16x32_bf16 v[72:75], v[136:139], v[238:241], v[72:75]
	v_mfma_f32_16x16x32_bf16 v[76:79], v[128:131], v[238:241], v[76:79]
	v_mfma_f32_16x16x32_bf16 v[124:127], v[132:135], v[218:221], v[124:127]
	v_mfma_f32_16x16x32_bf16 v[120:123], v[140:143], v[218:221], v[120:123]
	v_mfma_f32_16x16x32_bf16 v[104:107], v[140:143], v[226:229], v[104:107]
	v_mfma_f32_16x16x32_bf16 v[108:111], v[132:135], v[226:229], v[108:111]
	v_mfma_f32_16x16x32_bf16 v[92:95], v[132:135], v[234:237], v[92:95]
	v_mfma_f32_16x16x32_bf16 v[88:91], v[140:143], v[234:237], v[88:91]
	v_mfma_f32_16x16x32_bf16 v[72:75], v[140:143], v[242:245], v[72:75]
	v_mfma_f32_16x16x32_bf16 v[76:79], v[132:135], v[242:245], v[76:79]
	v_mfma_f32_16x16x32_bf16 v[116:119], v[174:177], v[214:217], v[116:119]
	v_mfma_f32_16x16x32_bf16 v[112:115], v[188:191], v[214:217], v[112:115]
	v_mfma_f32_16x16x32_bf16 v[96:99], v[188:191], v[222:225], v[96:99]
	v_mfma_f32_16x16x32_bf16 v[100:103], v[174:177], v[222:225], v[100:103]
	v_mfma_f32_16x16x32_bf16 v[84:87], v[174:177], v[230:233], v[84:87]
	v_mfma_f32_16x16x32_bf16 v[80:83], v[188:191], v[230:233], v[80:83]
	v_mfma_f32_16x16x32_bf16 v[64:67], v[188:191], v[238:241], v[64:67]
	v_mfma_f32_16x16x32_bf16 v[68:71], v[174:177], v[238:241], v[68:71]
	v_mfma_f32_16x16x32_bf16 v[116:119], v[184:187], v[218:221], v[116:119]
	v_mfma_f32_16x16x32_bf16 v[112:115], v[210:213], v[218:221], v[112:115]
	v_mfma_f32_16x16x32_bf16 v[96:99], v[210:213], v[226:229], v[96:99]
	v_mfma_f32_16x16x32_bf16 v[100:103], v[184:187], v[226:229], v[100:103]
	v_mfma_f32_16x16x32_bf16 v[84:87], v[184:187], v[234:237], v[84:87]
	v_mfma_f32_16x16x32_bf16 v[80:83], v[210:213], v[234:237], v[80:83]
	v_mfma_f32_16x16x32_bf16 v[64:67], v[210:213], v[242:245], v[64:67]
	v_mfma_f32_16x16x32_bf16 v[68:71], v[184:187], v[242:245], v[68:71]
	s_setprio 0
	s_barrier
	s_mov_b32 m0, s35
	s_add_u32 s0, s4, 0xb0000
	s_addc_u32 s1, s5, 0
	ds_read_b128 v[214:217], v181 offset:16384
	ds_read_b128 v[218:221], v181 offset:17408
	ds_read_b128 v[222:225], v181 offset:18432
	ds_read_b128 v[226:229], v181 offset:19456
	ds_read_b128 v[230:233], v181 offset:20480
	ds_read_b128 v[234:237], v181 offset:21504
	ds_read_b128 v[238:241], v181 offset:22528
	ds_read_b128 v[242:245], v181 offset:23552
	global_load_lds_dwordx4 v166, s[4:5]
	s_mov_b32 m0, s38
	s_nop 0
	global_load_lds_dwordx4 v162, s[4:5]
	s_mov_b32 m0, s39
	s_nop 0
	global_load_lds_dwordx4 v166, s[0:1]
	s_mov_b32 m0, s40
	s_nop 0
	global_load_lds_dwordx4 v162, s[0:1]
	s_mov_b32 m0, s29
	s_nop 0
	global_load_lds_dwordx4 v168, s[6:7]
	s_mov_b32 m0, s41
	s_nop 0
	global_load_lds_dwordx4 v164, s[6:7]
	s_waitcnt vmcnt(8)
	s_waitcnt lgkmcnt(0)
	s_barrier
	s_setprio 1
	v_mfma_f32_16x16x32_bf16 v[60:63], v[128:131], v[214:217], v[60:63]
	v_mfma_f32_16x16x32_bf16 v[56:59], v[136:139], v[214:217], v[56:59]
	v_mfma_f32_16x16x32_bf16 v[40:43], v[136:139], v[222:225], v[40:43]
	v_mfma_f32_16x16x32_bf16 v[44:47], v[128:131], v[222:225], v[44:47]
	v_mfma_f32_16x16x32_bf16 v[28:31], v[128:131], v[230:233], v[28:31]
	v_mfma_f32_16x16x32_bf16 v[24:27], v[136:139], v[230:233], v[24:27]
	v_mfma_f32_16x16x32_bf16 v[8:11], v[136:139], v[238:241], v[8:11]
	v_mfma_f32_16x16x32_bf16 v[12:15], v[128:131], v[238:241], v[12:15]
	v_mfma_f32_16x16x32_bf16 v[60:63], v[132:135], v[218:221], v[60:63]
	v_mfma_f32_16x16x32_bf16 v[56:59], v[140:143], v[218:221], v[56:59]
	v_mfma_f32_16x16x32_bf16 v[40:43], v[140:143], v[226:229], v[40:43]
	v_mfma_f32_16x16x32_bf16 v[44:47], v[132:135], v[226:229], v[44:47]
	v_mfma_f32_16x16x32_bf16 v[28:31], v[132:135], v[234:237], v[28:31]
	v_mfma_f32_16x16x32_bf16 v[24:27], v[140:143], v[234:237], v[24:27]
	v_mfma_f32_16x16x32_bf16 v[8:11], v[140:143], v[242:245], v[8:11]
	v_mfma_f32_16x16x32_bf16 v[12:15], v[132:135], v[242:245], v[12:15]
	v_mfma_f32_16x16x32_bf16 v[52:55], v[174:177], v[214:217], v[52:55]
	v_mfma_f32_16x16x32_bf16 v[48:51], v[188:191], v[214:217], v[48:51]
	v_mfma_f32_16x16x32_bf16 v[32:35], v[188:191], v[222:225], v[32:35]
	v_mfma_f32_16x16x32_bf16 v[36:39], v[174:177], v[222:225], v[36:39]
	v_mfma_f32_16x16x32_bf16 v[20:23], v[174:177], v[230:233], v[20:23]
	v_mfma_f32_16x16x32_bf16 v[16:19], v[188:191], v[230:233], v[16:19]
	v_mfma_f32_16x16x32_bf16 v[0:3], v[188:191], v[238:241], v[0:3]
	v_mfma_f32_16x16x32_bf16 v[4:7], v[174:177], v[238:241], v[4:7]
	v_mfma_f32_16x16x32_bf16 v[52:55], v[184:187], v[218:221], v[52:55]
	v_mfma_f32_16x16x32_bf16 v[48:51], v[210:213], v[218:221], v[48:51]
	v_mfma_f32_16x16x32_bf16 v[32:35], v[210:213], v[226:229], v[32:35]
	v_mfma_f32_16x16x32_bf16 v[36:39], v[184:187], v[226:229], v[36:39]
	v_mfma_f32_16x16x32_bf16 v[20:23], v[184:187], v[234:237], v[20:23]
	v_mfma_f32_16x16x32_bf16 v[16:19], v[210:213], v[234:237], v[16:19]
	v_mfma_f32_16x16x32_bf16 v[0:3], v[210:213], v[242:245], v[0:3]
	v_mfma_f32_16x16x32_bf16 v[4:7], v[184:187], v[242:245], v[4:7]
	s_setprio 0
	s_barrier
; #define PG8_STAGE(bufoff, gbase, voff) do { _Pragma("unroll") for (int _i = 0; _i < 2; ++_i) \
;         __builtin_amdgcn_global_load_lds((const unsigned*)((const char*)(gbase) + (voff)[_i]), (PG8_LAS unsigned*)(lds + (bufoff) + ldsw + _i * 8192), 16, 0, 0); } while (0)
; #define PG8_LDA(dst, b, h) do { _Pragma("unroll") for (int m = 0; m < 4; ++m) _Pragma("unroll") for (int k = 0; k < 2; ++k) dst[m][k] = *(const PG8_LAS bf16x8*)(lds + PG8_SA(b, h) + aoff + m * 2048 + k * 1024); } while (0)
; #define PG8_LDB(dst, b, h) do { _Pragma("unroll") for (int n = 0; n < 2; ++n) _Pragma("unroll") for (int k = 0; k < 2; ++k) dst[n][k] = *(const PG8_LAS bf16x8*)(lds + PG8_SB(b, h) + boff + n * 2048 + k * 1024); } while (0)
; #define PG8_MMA(ai, bj, At, Bt) do { __builtin_amdgcn_s_setprio(1); _Pragma("unroll") for (int m = 0; m < 4; ++m) _Pragma("unroll") for (int n = 0; n < 2; ++n) _Pragma("unroll") for (int k = 0; k < 2; ++k) \
;         acc[ai][bj][m][n] = __builtin_amdgcn_mfma_f32_16x16x32_bf16(Bt[n][k], At[m][k], acc[ai][bj][m][n], 0, 0, 0); __builtin_amdgcn_s_setprio(0); } while (0)
; #define PG8_WAIT_V(n) asm volatile("s_waitcnt vmcnt(" #n ")" ::: "memory")
; #define PG8_WAIT_L(n) asm volatile("s_waitcnt lgkmcnt(" #n ")" ::: "memory")
; #define PG8_BAR __builtin_amdgcn_s_barrier()
; #define PG8_SCHED __builtin_amdgcn_sched_barrier(0)
; template <class Epi, class Sched, bool ALIGN_EPI = false, bool SP2 = false>
; __device__ __forceinline__ void gemm_phase(PG8_LAS unsigned char* lds, const Gemm g, const Sched& S, const Epi& E) {
;     ...
;             PG8_LDB(B0, 1, 0); PG8_LDB(B1, 1, 1); PG8_SCHED; PG8_LDA(At, 1, 0); PG8_STAGE(PG8_SA(0, 1), a2 + hstep, voffA);
;             PG8_WAIT_V(8); PG8_WAIT_L(0); PG8_BAR; PG8_MMA(0, 0, At, B0); PG8_MMA(0, 1, At, B1); PG8_BAR; PG8_SCHED;
;             PG8_LDA(At, 1, 1); PG8_STAGE(PG8_SB(1, 0), b3, voffB); PG8_STAGE(PG8_SB(1, 1), b3 + hstep, voffB); PG8_STAGE(PG8_SA(1, 0), a3, voffA);
;             PG8_WAIT_V(8); PG8_WAIT_L(0); PG8_BAR; PG8_MMA(1, 0, At, B0); PG8_MMA(1, 1, At, B1); PG8_BAR; PG8_SCHED;
	ds_read_b128 v[128:131], v254 offset:32768
	ds_read_b128 v[132:135], v254 offset:33792
	ds_read_b128 v[136:139], v254 offset:34816
	ds_read_b128 v[140:143], v254 offset:35840
	ds_read_b128 v[174:177], v254 offset:49152
	ds_read_b128 v[184:187], v254 offset:50176
	ds_read_b128 v[188:191], v254 offset:51200
	ds_read_b128 v[210:213], v254 offset:52224
	s_add_u32 s0, s6, 0xb0000
	s_addc_u32 s1, s7, 0
	s_mov_b32 m0, s42
	ds_read_b128 v[214:217], v181 offset:32768
	ds_read_b128 v[218:221], v181 offset:33792
	ds_read_b128 v[222:225], v181 offset:34816
	ds_read_b128 v[226:229], v181 offset:35840
	ds_read_b128 v[230:233], v181 offset:36864
	ds_read_b128 v[234:237], v181 offset:37888
	ds_read_b128 v[238:241], v181 offset:38912
	ds_read_b128 v[242:245], v181 offset:39936
	global_load_lds_dwordx4 v168, s[0:1]
	s_mov_b32 m0, s43
	s_nop 0
	global_load_lds_dwordx4 v164, s[0:1]
	s_waitcnt vmcnt(8)
	s_waitcnt lgkmcnt(0)
	s_barrier
	s_setprio 1
	v_mfma_f32_16x16x32_bf16 v[124:127], v[128:131], v[214:217], v[124:127]
	v_mfma_f32_16x16x32_bf16 v[120:123], v[136:139], v[214:217], v[120:123]
	v_mfma_f32_16x16x32_bf16 v[104:107], v[136:139], v[222:225], v[104:107]
	v_mfma_f32_16x16x32_bf16 v[108:111], v[128:131], v[222:225], v[108:111]
	v_mfma_f32_16x16x32_bf16 v[92:95], v[128:131], v[230:233], v[92:95]
	v_mfma_f32_16x16x32_bf16 v[88:91], v[136:139], v[230:233], v[88:91]
	v_mfma_f32_16x16x32_bf16 v[72:75], v[136:139], v[238:241], v[72:75]
	v_mfma_f32_16x16x32_bf16 v[76:79], v[128:131], v[238:241], v[76:79]
	v_mfma_f32_16x16x32_bf16 v[124:127], v[132:135], v[218:221], v[124:127]
	v_mfma_f32_16x16x32_bf16 v[120:123], v[140:143], v[218:221], v[120:123]
	v_mfma_f32_16x16x32_bf16 v[104:107], v[140:143], v[226:229], v[104:107]
	v_mfma_f32_16x16x32_bf16 v[108:111], v[132:135], v[226:229], v[108:111]
	v_mfma_f32_16x16x32_bf16 v[92:95], v[132:135], v[234:237], v[92:95]
	v_mfma_f32_16x16x32_bf16 v[88:91], v[140:143], v[234:237], v[88:91]
	v_mfma_f32_16x16x32_bf16 v[72:75], v[140:143], v[242:245], v[72:75]
	v_mfma_f32_16x16x32_bf16 v[76:79], v[132:135], v[242:245], v[76:79]
	v_mfma_f32_16x16x32_bf16 v[116:119], v[174:177], v[214:217], v[116:119]
	v_mfma_f32_16x16x32_bf16 v[112:115], v[188:191], v[214:217], v[112:115]
	v_mfma_f32_16x16x32_bf16 v[96:99], v[188:191], v[222:225], v[96:99]
	v_mfma_f32_16x16x32_bf16 v[100:103], v[174:177], v[222:225], v[100:103]
	v_mfma_f32_16x16x32_bf16 v[84:87], v[174:177], v[230:233], v[84:87]
	v_mfma_f32_16x16x32_bf16 v[80:83], v[188:191], v[230:233], v[80:83]
	v_mfma_f32_16x16x32_bf16 v[64:67], v[188:191], v[238:241], v[64:67]
	v_mfma_f32_16x16x32_bf16 v[68:71], v[174:177], v[238:241], v[68:71]
	v_mfma_f32_16x16x32_bf16 v[116:119], v[184:187], v[218:221], v[116:119]
	v_mfma_f32_16x16x32_bf16 v[112:115], v[210:213], v[218:221], v[112:115]
	v_mfma_f32_16x16x32_bf16 v[96:99], v[210:213], v[226:229], v[96:99]
	v_mfma_f32_16x16x32_bf16 v[100:103], v[184:187], v[226:229], v[100:103]
	v_mfma_f32_16x16x32_bf16 v[84:87], v[184:187], v[234:237], v[84:87]
	v_mfma_f32_16x16x32_bf16 v[80:83], v[210:213], v[234:237], v[80:83]
	v_mfma_f32_16x16x32_bf16 v[64:67], v[210:213], v[242:245], v[64:67]
	v_mfma_f32_16x16x32_bf16 v[68:71], v[184:187], v[242:245], v[68:71]
	s_setprio 0
	s_barrier
	s_mov_b32 m0, s47
	s_add_u32 s0, s4, 0xb0080
	s_addc_u32 s1, s5, 0
	ds_read_b128 v[214:217], v181 offset:49152
	ds_read_b128 v[218:221], v181 offset:50176
	ds_read_b128 v[222:225], v181 offset:51200
	ds_read_b128 v[226:229], v181 offset:52224
	ds_read_b128 v[230:233], v181 offset:53248
	ds_read_b128 v[234:237], v181 offset:54272
	ds_read_b128 v[238:241], v181 offset:55296
	ds_read_b128 v[242:245], v181 offset:56320
	s_add_u32 s98, s4, 0x80
	s_addc_u32 s99, s5, 0
	global_load_lds_dwordx4 v166, s[98:99]
	s_mov_b32 m0, s48
	s_nop 0
	global_load_lds_dwordx4 v162, s[98:99]
	s_mov_b32 m0, s51
	s_nop 0
	global_load_lds_dwordx4 v166, s[0:1]
	s_mov_b32 m0, s52
	s_nop 0
	global_load_lds_dwordx4 v162, s[0:1]
	s_mov_b32 m0, s49
	s_nop 0
	s_add_u32 s100, s6, 0x80
	s_addc_u32 s101, s7, 0
	global_load_lds_dwordx4 v168, s[100:101]
	s_mov_b32 m0, s50
	s_nop 0
	global_load_lds_dwordx4 v164, s[100:101]
	s_waitcnt vmcnt(8)
	s_waitcnt lgkmcnt(0)
	s_barrier
	s_setprio 1
	v_mfma_f32_16x16x32_bf16 v[60:63], v[128:131], v[214:217], v[60:63]
	v_mfma_f32_16x16x32_bf16 v[56:59], v[136:139], v[214:217], v[56:59]
	v_mfma_f32_16x16x32_bf16 v[40:43], v[136:139], v[222:225], v[40:43]
	v_mfma_f32_16x16x32_bf16 v[44:47], v[128:131], v[222:225], v[44:47]
	v_mfma_f32_16x16x32_bf16 v[28:31], v[128:131], v[230:233], v[28:31]
	v_mfma_f32_16x16x32_bf16 v[24:27], v[136:139], v[230:233], v[24:27]
	v_mfma_f32_16x16x32_bf16 v[8:11], v[136:139], v[238:241], v[8:11]
	v_mfma_f32_16x16x32_bf16 v[12:15], v[128:131], v[238:241], v[12:15]
	v_mfma_f32_16x16x32_bf16 v[60:63], v[132:135], v[218:221], v[60:63]
	v_mfma_f32_16x16x32_bf16 v[56:59], v[140:143], v[218:221], v[56:59]
	v_mfma_f32_16x16x32_bf16 v[40:43], v[140:143], v[226:229], v[40:43]
	v_mfma_f32_16x16x32_bf16 v[44:47], v[132:135], v[226:229], v[44:47]
	v_mfma_f32_16x16x32_bf16 v[28:31], v[132:135], v[234:237], v[28:31]
	v_mfma_f32_16x16x32_bf16 v[24:27], v[140:143], v[234:237], v[24:27]
	v_mfma_f32_16x16x32_bf16 v[8:11], v[140:143], v[242:245], v[8:11]
	v_mfma_f32_16x16x32_bf16 v[12:15], v[132:135], v[242:245], v[12:15]
	v_mfma_f32_16x16x32_bf16 v[52:55], v[174:177], v[214:217], v[52:55]
	v_mfma_f32_16x16x32_bf16 v[48:51], v[188:191], v[214:217], v[48:51]
	v_mfma_f32_16x16x32_bf16 v[32:35], v[188:191], v[222:225], v[32:35]
	v_mfma_f32_16x16x32_bf16 v[36:39], v[174:177], v[222:225], v[36:39]
	v_mfma_f32_16x16x32_bf16 v[20:23], v[174:177], v[230:233], v[20:23]
	v_mfma_f32_16x16x32_bf16 v[16:19], v[188:191], v[230:233], v[16:19]
	v_mfma_f32_16x16x32_bf16 v[0:3], v[188:191], v[238:241], v[0:3]
	v_mfma_f32_16x16x32_bf16 v[4:7], v[174:177], v[238:241], v[4:7]
	v_mfma_f32_16x16x32_bf16 v[52:55], v[184:187], v[218:221], v[52:55]
	v_mfma_f32_16x16x32_bf16 v[48:51], v[210:213], v[218:221], v[48:51]
	v_mfma_f32_16x16x32_bf16 v[32:35], v[210:213], v[226:229], v[32:35]
	v_mfma_f32_16x16x32_bf16 v[36:39], v[184:187], v[226:229], v[36:39]
	v_mfma_f32_16x16x32_bf16 v[20:23], v[184:187], v[234:237], v[20:23]
	v_mfma_f32_16x16x32_bf16 v[16:19], v[210:213], v[234:237], v[16:19]
	v_mfma_f32_16x16x32_bf16 v[0:3], v[210:213], v[242:245], v[0:3]
	v_mfma_f32_16x16x32_bf16 v[4:7], v[184:187], v[242:245], v[4:7]
	s_setprio 0
	s_barrier
	s_add_i32 s13, s13, 2
	s_add_u32 s10, s10, 0x100
	s_addc_u32 s11, s11, 0
	s_cmp_gt_u32 s13, 41
	s_mov_b64 s[0:1], s[2:3]
	s_cbranch_scc0 .LBB0_545
	s_and_b64 vcc, exec, s[22:23]
	s_cbranch_vccz .LBB0_548
	s_barrier

; #define PG8_STAGE(bufoff, gbase, voff) do { _Pragma("unroll") for (int _i = 0; _i < 2; ++_i) \
;         __builtin_amdgcn_global_load_lds((const unsigned*)((const char*)(gbase) + (voff)[_i]), (PG8_LAS unsigned*)(lds + (bufoff) + ldsw + _i * 8192), 16, 0, 0); } while (0)
; #define PG8_LDA(dst, b, h) do { _Pragma("unroll") for (int m = 0; m < 4; ++m) _Pragma("unroll") for (int k = 0; k < 2; ++k) dst[m][k] = *(const PG8_LAS bf16x8*)(lds + PG8_SA(b, h) + aoff + m * 2048 + k * 1024); } while (0)
; #define PG8_LDB(dst, b, h) do { _Pragma("unroll") for (int n = 0; n < 2; ++n) _Pragma("unroll") for (int k = 0; k < 2; ++k) dst[n][k] = *(const PG8_LAS bf16x8*)(lds + PG8_SB(b, h) + boff + n * 2048 + k * 1024); } while (0)
; #define PG8_MMA(ai, bj, At, Bt) do { __builtin_amdgcn_s_setprio(1); _Pragma("unroll") for (int m = 0; m < 4; ++m) _Pragma("unroll") for (int n = 0; n < 2; ++n) _Pragma("unroll") for (int k = 0; k < 2; ++k) \
;         acc[ai][bj][m][n] = __builtin_amdgcn_mfma_f32_16x16x32_bf16(Bt[n][k], At[m][k], acc[ai][bj][m][n], 0, 0, 0); __builtin_amdgcn_s_setprio(0); } while (0)
; #define PG8_WAIT_V(n) asm volatile("s_waitcnt vmcnt(" #n ")" ::: "memory")
; #define PG8_BAR __builtin_amdgcn_s_barrier()
; template <class Epi, class Sched, bool ALIGN_EPI = false, bool SP2 = false>
; __device__ __forceinline__ void gemm_phase(PG8_LAS unsigned char* lds, const Gemm g, const Sched& S, const Epi& E) {
;     ...
;         for (int t = 0; t < nt; t += 2) {
;             const bool last = (t == nt - 2);
;             const char* a1 = cA + (size_t)(t + 1) * kstep;
;             const char* a2 = last ? nA : cA + (size_t)(t + 2) * kstep; const char* b2 = last ? nB : cB + (size_t)(t + 2) * kstep;
;             const char* a3 = a2 + kstep; const char* b3 = b2 + kstep;
;             if (last && has_next) S.a_ready(nxt);
;             if constexpr (SP2) {
;             PG8_LDB(B0, 0, 0); PG8_LDB(B1, 0, 1); PG8_SCHED; PG8_LDA(At, 0, 0); PG8_STAGE(PG8_SA(1, 1), a1 + hstep, voffA);
;             PG8_WAIT_V(8); PG8_WAIT_L(0); PG8_BAR; PG8_MMA(0, 0, At, B0); PG8_MMA(0, 1, At, B1); PG8_BAR; PG8_SCHED;
;             PG8_LDA(At, 0, 1); PG8_STAGE(PG8_SB(0, 0), b2, voffB); PG8_STAGE(PG8_SB(0, 1), b2 + hstep, voffB); PG8_STAGE(PG8_SA(0, 0), a2, voffA);
;             PG8_WAIT_V(8); PG8_WAIT_L(0); PG8_BAR; PG8_MMA(1, 0, At, B0); PG8_MMA(1, 1, At, B1); PG8_BAR; PG8_SCHED;
.Lsgi_peel:
	ds_read_b128 v[140:143], v254
	ds_read_b128 v[162:165], v254 offset:1024
	ds_read_b128 v[166:169], v254 offset:2048
	ds_read_b128 v[170:173], v254 offset:3072
	ds_read_b128 v[180:183], v254 offset:16384
	ds_read_b128 v[184:187], v254 offset:17408
	ds_read_b128 v[188:191], v254 offset:18432
	ds_read_b128 v[210:213], v254 offset:19456
	s_add_u32 s2, s0, 0xfffc0080
	s_addc_u32 s3, s1, -1
	s_cmp_eq_u32 s55, 12
	s_cselect_b32 s5, s13, s3
	s_cselect_b32 s4, s25, s2
	s_cselect_b32 s3, s23, s39
	s_cselect_b32 s2, s33, s38
	s_add_i32 m0, s6, 0xc000
	ds_read_b128 v[214:217], v178
	ds_read_b128 v[218:221], v178 offset:1024
	ds_read_b128 v[222:225], v178 offset:2048
	ds_read_b128 v[226:229], v178 offset:3072
	ds_read_b128 v[230:233], v178 offset:4096
	ds_read_b128 v[234:237], v178 offset:5120
	ds_read_b128 v[238:241], v178 offset:6144
	ds_read_b128 v[242:245], v178 offset:7168
	global_load_lds_dwordx4 v136, s[0:1]
	s_add_i32 m0, s6, 0xe000
	s_nop 0
	global_load_lds_dwordx4 v138, s[0:1]
	s_waitcnt vmcnt(8)
	s_waitcnt lgkmcnt(0)
	s_barrier
	s_setprio 1
	v_mfma_f32_16x16x32_bf16 v[124:127], v[140:143], v[214:217], 0
	v_mfma_f32_16x16x32_bf16 v[120:123], v[166:169], v[214:217], 0
	v_mfma_f32_16x16x32_bf16 v[104:107], v[166:169], v[222:225], 0
	v_mfma_f32_16x16x32_bf16 v[108:111], v[140:143], v[222:225], 0
	v_mfma_f32_16x16x32_bf16 v[92:95], v[140:143], v[230:233], 0
	v_mfma_f32_16x16x32_bf16 v[88:91], v[166:169], v[230:233], 0
	v_mfma_f32_16x16x32_bf16 v[72:75], v[166:169], v[238:241], 0
	v_mfma_f32_16x16x32_bf16 v[76:79], v[140:143], v[238:241], 0
	v_mfma_f32_16x16x32_bf16 v[124:127], v[162:165], v[218:221], v[124:127]
	v_mfma_f32_16x16x32_bf16 v[120:123], v[170:173], v[218:221], v[120:123]
	v_mfma_f32_16x16x32_bf16 v[104:107], v[170:173], v[226:229], v[104:107]
	v_mfma_f32_16x16x32_bf16 v[108:111], v[162:165], v[226:229], v[108:111]
	v_mfma_f32_16x16x32_bf16 v[92:95], v[162:165], v[234:237], v[92:95]
	v_mfma_f32_16x16x32_bf16 v[88:91], v[170:173], v[234:237], v[88:91]
	v_mfma_f32_16x16x32_bf16 v[72:75], v[170:173], v[242:245], v[72:75]
	v_mfma_f32_16x16x32_bf16 v[76:79], v[162:165], v[242:245], v[76:79]
	v_mfma_f32_16x16x32_bf16 v[116:119], v[180:183], v[214:217], 0
	v_mfma_f32_16x16x32_bf16 v[112:115], v[188:191], v[214:217], 0
	v_mfma_f32_16x16x32_bf16 v[96:99], v[188:191], v[222:225], 0
	v_mfma_f32_16x16x32_bf16 v[100:103], v[180:183], v[222:225], 0
	v_mfma_f32_16x16x32_bf16 v[84:87], v[180:183], v[230:233], 0
	v_mfma_f32_16x16x32_bf16 v[80:83], v[188:191], v[230:233], 0
	v_mfma_f32_16x16x32_bf16 v[64:67], v[188:191], v[238:241], 0
	v_mfma_f32_16x16x32_bf16 v[68:71], v[180:183], v[238:241], 0
	v_mfma_f32_16x16x32_bf16 v[116:119], v[184:187], v[218:221], v[116:119]
	v_mfma_f32_16x16x32_bf16 v[112:115], v[210:213], v[218:221], v[112:115]
	v_mfma_f32_16x16x32_bf16 v[96:99], v[210:213], v[226:229], v[96:99]
	v_mfma_f32_16x16x32_bf16 v[100:103], v[184:187], v[226:229], v[100:103]
	v_mfma_f32_16x16x32_bf16 v[84:87], v[184:187], v[234:237], v[84:87]
	v_mfma_f32_16x16x32_bf16 v[80:83], v[210:213], v[234:237], v[80:83]
	v_mfma_f32_16x16x32_bf16 v[64:67], v[210:213], v[242:245], v[64:67]
	v_mfma_f32_16x16x32_bf16 v[68:71], v[184:187], v[242:245], v[68:71]
	s_setprio 0
	s_barrier
	s_mov_b32 m0, s31
	s_add_u32 s56, s2, 0x40000
	s_addc_u32 s57, s3, 0
	ds_read_b128 v[214:217], v178 offset:16384
	ds_read_b128 v[218:221], v178 offset:17408
	ds_read_b128 v[222:225], v178 offset:18432
	ds_read_b128 v[226:229], v178 offset:19456
	ds_read_b128 v[230:233], v178 offset:20480
	ds_read_b128 v[234:237], v178 offset:21504
	ds_read_b128 v[238:241], v178 offset:22528
	ds_read_b128 v[242:245], v178 offset:23552
	global_load_lds_dwordx4 v132, s[2:3]
	s_mov_b32 m0, s34
	s_nop 0
	global_load_lds_dwordx4 v128, s[2:3]
	s_mov_b32 m0, s35
	s_nop 0
	global_load_lds_dwordx4 v132, s[56:57]
	s_mov_b32 m0, s40
	s_nop 0
	global_load_lds_dwordx4 v128, s[56:57]
	s_mov_b32 m0, s6
	s_nop 0
	global_load_lds_dwordx4 v134, s[4:5]
	s_mov_b32 m0, s41
	s_nop 0
	global_load_lds_dwordx4 v130, s[4:5]
	s_waitcnt vmcnt(8)
	s_waitcnt lgkmcnt(0)
	s_barrier
	s_setprio 1
	v_mfma_f32_16x16x32_bf16 v[60:63], v[140:143], v[214:217], 0
	v_mfma_f32_16x16x32_bf16 v[56:59], v[166:169], v[214:217], 0
	v_mfma_f32_16x16x32_bf16 v[40:43], v[166:169], v[222:225], 0
	v_mfma_f32_16x16x32_bf16 v[44:47], v[140:143], v[222:225], 0
	v_mfma_f32_16x16x32_bf16 v[28:31], v[140:143], v[230:233], 0
	v_mfma_f32_16x16x32_bf16 v[24:27], v[166:169], v[230:233], 0
	v_mfma_f32_16x16x32_bf16 v[8:11], v[166:169], v[238:241], 0
	v_mfma_f32_16x16x32_bf16 v[12:15], v[140:143], v[238:241], 0
	v_mfma_f32_16x16x32_bf16 v[60:63], v[162:165], v[218:221], v[60:63]
	v_mfma_f32_16x16x32_bf16 v[56:59], v[170:173], v[218:221], v[56:59]
	v_mfma_f32_16x16x32_bf16 v[40:43], v[170:173], v[226:229], v[40:43]
	v_mfma_f32_16x16x32_bf16 v[44:47], v[162:165], v[226:229], v[44:47]
	v_mfma_f32_16x16x32_bf16 v[28:31], v[162:165], v[234:237], v[28:31]
	v_mfma_f32_16x16x32_bf16 v[24:27], v[170:173], v[234:237], v[24:27]
	v_mfma_f32_16x16x32_bf16 v[8:11], v[170:173], v[242:245], v[8:11]
	v_mfma_f32_16x16x32_bf16 v[12:15], v[162:165], v[242:245], v[12:15]
	v_mfma_f32_16x16x32_bf16 v[52:55], v[180:183], v[214:217], 0
	v_mfma_f32_16x16x32_bf16 v[48:51], v[188:191], v[214:217], 0
	v_mfma_f32_16x16x32_bf16 v[32:35], v[188:191], v[222:225], 0
	v_mfma_f32_16x16x32_bf16 v[36:39], v[180:183], v[222:225], 0
	v_mfma_f32_16x16x32_bf16 v[20:23], v[180:183], v[230:233], 0
	v_mfma_f32_16x16x32_bf16 v[16:19], v[188:191], v[230:233], 0
	v_mfma_f32_16x16x32_bf16 v[0:3], v[188:191], v[238:241], 0
	v_mfma_f32_16x16x32_bf16 v[4:7], v[180:183], v[238:241], 0
	v_mfma_f32_16x16x32_bf16 v[52:55], v[184:187], v[218:221], v[52:55]
	v_mfma_f32_16x16x32_bf16 v[48:51], v[210:213], v[218:221], v[48:51]
	v_mfma_f32_16x16x32_bf16 v[32:35], v[210:213], v[226:229], v[32:35]
	v_mfma_f32_16x16x32_bf16 v[36:39], v[184:187], v[226:229], v[36:39]
	v_mfma_f32_16x16x32_bf16 v[20:23], v[184:187], v[234:237], v[20:23]
	v_mfma_f32_16x16x32_bf16 v[16:19], v[210:213], v[234:237], v[16:19]
	v_mfma_f32_16x16x32_bf16 v[0:3], v[210:213], v[242:245], v[0:3]
	v_mfma_f32_16x16x32_bf16 v[4:7], v[184:187], v[242:245], v[4:7]
	s_setprio 0
	s_barrier
; #define PG8_STAGE(bufoff, gbase, voff) do { _Pragma("unroll") for (int _i = 0; _i < 2; ++_i) \
;         __builtin_amdgcn_global_load_lds((const unsigned*)((const char*)(gbase) + (voff)[_i]), (PG8_LAS unsigned*)(lds + (bufoff) + ldsw + _i * 8192), 16, 0, 0); } while (0)
; #define PG8_LDA(dst, b, h) do { _Pragma("unroll") for (int m = 0; m < 4; ++m) _Pragma("unroll") for (int k = 0; k < 2; ++k) dst[m][k] = *(const PG8_LAS bf16x8*)(lds + PG8_SA(b, h) + aoff + m * 2048 + k * 1024); } while (0)
; #define PG8_LDB(dst, b, h) do { _Pragma("unroll") for (int n = 0; n < 2; ++n) _Pragma("unroll") for (int k = 0; k < 2; ++k) dst[n][k] = *(const PG8_LAS bf16x8*)(lds + PG8_SB(b, h) + boff + n * 2048 + k * 1024); } while (0)
; #define PG8_MMA(ai, bj, At, Bt) do { __builtin_amdgcn_s_setprio(1); _Pragma("unroll") for (int m = 0; m < 4; ++m) _Pragma("unroll") for (int n = 0; n < 2; ++n) _Pragma("unroll") for (int k = 0; k < 2; ++k) \
;         acc[ai][bj][m][n] = __builtin_amdgcn_mfma_f32_16x16x32_bf16(Bt[n][k], At[m][k], acc[ai][bj][m][n], 0, 0, 0); __builtin_amdgcn_s_setprio(0); } while (0)
; #define PG8_WAIT_V(n) asm volatile("s_waitcnt vmcnt(" #n ")" ::: "memory")
; #define PG8_WAIT_L(n) asm volatile("s_waitcnt lgkmcnt(" #n ")" ::: "memory")
; #define PG8_BAR __builtin_amdgcn_s_barrier()
; #define PG8_SCHED __builtin_amdgcn_sched_barrier(0)
; template <class Epi, class Sched, bool ALIGN_EPI = false, bool SP2 = false>
; __device__ __forceinline__ void gemm_phase(PG8_LAS unsigned char* lds, const Gemm g, const Sched& S, const Epi& E) {
;     ...
;             PG8_LDB(B0, 1, 0); PG8_LDB(B1, 1, 1); PG8_SCHED; PG8_LDA(At, 1, 0); PG8_STAGE(PG8_SA(0, 1), a2 + hstep, voffA);
;             PG8_WAIT_V(8); PG8_WAIT_L(0); PG8_BAR; PG8_MMA(0, 0, At, B0); PG8_MMA(0, 1, At, B1); PG8_BAR; PG8_SCHED;
;             PG8_LDA(At, 1, 1); PG8_STAGE(PG8_SB(1, 0), b3, voffB); PG8_STAGE(PG8_SB(1, 1), b3 + hstep, voffB); PG8_STAGE(PG8_SA(1, 0), a3, voffA);
;             PG8_WAIT_V(8); PG8_WAIT_L(0); PG8_BAR; PG8_MMA(1, 0, At, B0); PG8_MMA(1, 1, At, B1); PG8_BAR; PG8_SCHED;
	ds_read_b128 v[140:143], v254 offset:32768
	ds_read_b128 v[162:165], v254 offset:33792
	ds_read_b128 v[166:169], v254 offset:34816
	ds_read_b128 v[170:173], v254 offset:35840
	ds_read_b128 v[180:183], v254 offset:49152
	ds_read_b128 v[184:187], v254 offset:50176
	ds_read_b128 v[188:191], v254 offset:51200
	ds_read_b128 v[210:213], v254 offset:52224
	s_add_u32 s4, s4, 0x40000
	s_addc_u32 s5, s5, 0
	s_mov_b32 m0, s42
	ds_read_b128 v[214:217], v178 offset:32768
	ds_read_b128 v[218:221], v178 offset:33792
	ds_read_b128 v[222:225], v178 offset:34816
	ds_read_b128 v[226:229], v178 offset:35840
	ds_read_b128 v[230:233], v178 offset:36864
	ds_read_b128 v[234:237], v178 offset:37888
	ds_read_b128 v[238:241], v178 offset:38912
	ds_read_b128 v[242:245], v178 offset:39936
	global_load_lds_dwordx4 v134, s[4:5]
	s_mov_b32 m0, s43
	s_nop 0
	global_load_lds_dwordx4 v130, s[4:5]
	s_waitcnt vmcnt(8)
	s_waitcnt lgkmcnt(0)
	s_barrier
	s_setprio 1
	v_mfma_f32_16x16x32_bf16 v[124:127], v[140:143], v[214:217], v[124:127]
	v_mfma_f32_16x16x32_bf16 v[120:123], v[166:169], v[214:217], v[120:123]
	v_mfma_f32_16x16x32_bf16 v[104:107], v[166:169], v[222:225], v[104:107]
	v_mfma_f32_16x16x32_bf16 v[108:111], v[140:143], v[222:225], v[108:111]
	v_mfma_f32_16x16x32_bf16 v[92:95], v[140:143], v[230:233], v[92:95]
	v_mfma_f32_16x16x32_bf16 v[88:91], v[166:169], v[230:233], v[88:91]
	v_mfma_f32_16x16x32_bf16 v[72:75], v[166:169], v[238:241], v[72:75]
	v_mfma_f32_16x16x32_bf16 v[76:79], v[140:143], v[238:241], v[76:79]
	v_mfma_f32_16x16x32_bf16 v[124:127], v[162:165], v[218:221], v[124:127]
	v_mfma_f32_16x16x32_bf16 v[120:123], v[170:173], v[218:221], v[120:123]
	v_mfma_f32_16x16x32_bf16 v[104:107], v[170:173], v[226:229], v[104:107]
	v_mfma_f32_16x16x32_bf16 v[108:111], v[162:165], v[226:229], v[108:111]
	v_mfma_f32_16x16x32_bf16 v[92:95], v[162:165], v[234:237], v[92:95]
	v_mfma_f32_16x16x32_bf16 v[88:91], v[170:173], v[234:237], v[88:91]
	v_mfma_f32_16x16x32_bf16 v[72:75], v[170:173], v[242:245], v[72:75]
	v_mfma_f32_16x16x32_bf16 v[76:79], v[162:165], v[242:245], v[76:79]
	v_mfma_f32_16x16x32_bf16 v[116:119], v[180:183], v[214:217], v[116:119]
	v_mfma_f32_16x16x32_bf16 v[112:115], v[188:191], v[214:217], v[112:115]
	v_mfma_f32_16x16x32_bf16 v[96:99], v[188:191], v[222:225], v[96:99]
	v_mfma_f32_16x16x32_bf16 v[100:103], v[180:183], v[222:225], v[100:103]
	v_mfma_f32_16x16x32_bf16 v[84:87], v[180:183], v[230:233], v[84:87]
	v_mfma_f32_16x16x32_bf16 v[80:83], v[188:191], v[230:233], v[80:83]
	v_mfma_f32_16x16x32_bf16 v[64:67], v[188:191], v[238:241], v[64:67]
	v_mfma_f32_16x16x32_bf16 v[68:71], v[180:183], v[238:241], v[68:71]
	v_mfma_f32_16x16x32_bf16 v[116:119], v[184:187], v[218:221], v[116:119]
	v_mfma_f32_16x16x32_bf16 v[112:115], v[210:213], v[218:221], v[112:115]
	v_mfma_f32_16x16x32_bf16 v[96:99], v[210:213], v[226:229], v[96:99]
	v_mfma_f32_16x16x32_bf16 v[100:103], v[184:187], v[226:229], v[100:103]
	v_mfma_f32_16x16x32_bf16 v[84:87], v[184:187], v[234:237], v[84:87]
	v_mfma_f32_16x16x32_bf16 v[80:83], v[210:213], v[234:237], v[80:83]
	v_mfma_f32_16x16x32_bf16 v[64:67], v[210:213], v[242:245], v[64:67]
	v_mfma_f32_16x16x32_bf16 v[68:71], v[184:187], v[242:245], v[68:71]
	s_setprio 0
	s_barrier
	s_mov_b32 m0, s48
	s_add_u32 s2, s2, 0x40080
	s_addc_u32 s3, s3, 0
	ds_read_b128 v[214:217], v178 offset:49152
	ds_read_b128 v[218:221], v178 offset:50176
	ds_read_b128 v[222:225], v178 offset:51200
	ds_read_b128 v[226:229], v178 offset:52224
	ds_read_b128 v[230:233], v178 offset:53248
	ds_read_b128 v[234:237], v178 offset:54272
	ds_read_b128 v[238:241], v178 offset:55296
	ds_read_b128 v[242:245], v178 offset:56320
	s_add_u32 s98, s2, 0xfffc0000
	s_addc_u32 s99, s3, -1
	global_load_lds_dwordx4 v132, s[98:99]
	s_mov_b32 m0, s49
	s_nop 0
	global_load_lds_dwordx4 v128, s[98:99]
	s_mov_b32 m0, s52
	s_nop 0
	global_load_lds_dwordx4 v132, s[2:3]
	s_mov_b32 m0, s53
	s_nop 0
	global_load_lds_dwordx4 v128, s[2:3]
	s_mov_b32 m0, s50
	s_nop 0
	s_add_u32 s100, s4, 0xfffc0080
	s_addc_u32 s101, s5, -1
	global_load_lds_dwordx4 v134, s[100:101]
	s_mov_b32 m0, s51
	s_nop 0
	global_load_lds_dwordx4 v130, s[100:101]
	s_waitcnt vmcnt(8)
	s_waitcnt lgkmcnt(0)
	s_barrier
	s_setprio 1
	v_mfma_f32_16x16x32_bf16 v[60:63], v[140:143], v[214:217], v[60:63]
	v_mfma_f32_16x16x32_bf16 v[56:59], v[166:169], v[214:217], v[56:59]
	v_mfma_f32_16x16x32_bf16 v[40:43], v[166:169], v[222:225], v[40:43]
	v_mfma_f32_16x16x32_bf16 v[44:47], v[140:143], v[222:225], v[44:47]
	v_mfma_f32_16x16x32_bf16 v[28:31], v[140:143], v[230:233], v[28:31]
	v_mfma_f32_16x16x32_bf16 v[24:27], v[166:169], v[230:233], v[24:27]
	v_mfma_f32_16x16x32_bf16 v[8:11], v[166:169], v[238:241], v[8:11]
	v_mfma_f32_16x16x32_bf16 v[12:15], v[140:143], v[238:241], v[12:15]
	v_mfma_f32_16x16x32_bf16 v[60:63], v[162:165], v[218:221], v[60:63]
	v_mfma_f32_16x16x32_bf16 v[56:59], v[170:173], v[218:221], v[56:59]
	v_mfma_f32_16x16x32_bf16 v[40:43], v[170:173], v[226:229], v[40:43]
	v_mfma_f32_16x16x32_bf16 v[44:47], v[162:165], v[226:229], v[44:47]
	v_mfma_f32_16x16x32_bf16 v[28:31], v[162:165], v[234:237], v[28:31]
	v_mfma_f32_16x16x32_bf16 v[24:27], v[170:173], v[234:237], v[24:27]
	v_mfma_f32_16x16x32_bf16 v[8:11], v[170:173], v[242:245], v[8:11]
	v_mfma_f32_16x16x32_bf16 v[12:15], v[162:165], v[242:245], v[12:15]
	v_mfma_f32_16x16x32_bf16 v[52:55], v[180:183], v[214:217], v[52:55]
	v_mfma_f32_16x16x32_bf16 v[48:51], v[188:191], v[214:217], v[48:51]
	v_mfma_f32_16x16x32_bf16 v[32:35], v[188:191], v[222:225], v[32:35]
	v_mfma_f32_16x16x32_bf16 v[36:39], v[180:183], v[222:225], v[36:39]
	v_mfma_f32_16x16x32_bf16 v[20:23], v[180:183], v[230:233], v[20:23]
	v_mfma_f32_16x16x32_bf16 v[16:19], v[188:191], v[230:233], v[16:19]
	v_mfma_f32_16x16x32_bf16 v[0:3], v[188:191], v[238:241], v[0:3]
	v_mfma_f32_16x16x32_bf16 v[4:7], v[180:183], v[238:241], v[4:7]
	v_mfma_f32_16x16x32_bf16 v[52:55], v[184:187], v[218:221], v[52:55]
	v_mfma_f32_16x16x32_bf16 v[48:51], v[210:213], v[218:221], v[48:51]
	v_mfma_f32_16x16x32_bf16 v[32:35], v[210:213], v[226:229], v[32:35]
	v_mfma_f32_16x16x32_bf16 v[36:39], v[184:187], v[226:229], v[36:39]
	v_mfma_f32_16x16x32_bf16 v[20:23], v[184:187], v[234:237], v[20:23]
	v_mfma_f32_16x16x32_bf16 v[16:19], v[210:213], v[234:237], v[16:19]
	v_mfma_f32_16x16x32_bf16 v[0:3], v[210:213], v[242:245], v[0:3]
	v_mfma_f32_16x16x32_bf16 v[4:7], v[184:187], v[242:245], v[4:7]
	s_setprio 0
	s_barrier
	s_add_i32 s55, s55, 2
	s_add_u32 s0, s0, 0x100
	s_addc_u32 s1, s1, 0
	s_add_u32 s38, s38, 0x100
	s_addc_u32 s39, s39, 0
	s_cmp_gt_u32 s55, 13
; #define PG8_STAGE(bufoff, gbase, voff) do { _Pragma("unroll") for (int _i = 0; _i < 2; ++_i) \
;         __builtin_amdgcn_global_load_lds((const unsigned*)((const char*)(gbase) + (voff)[_i]), (PG8_LAS unsigned*)(lds + (bufoff) + ldsw + _i * 8192), 16, 0, 0); } while (0)
; #define PG8_LDA(dst, b, h) do { _Pragma("unroll") for (int m = 0; m < 4; ++m) _Pragma("unroll") for (int k = 0; k < 2; ++k) dst[m][k] = *(const PG8_LAS bf16x8*)(lds + PG8_SA(b, h) + aoff + m * 2048 + k * 1024); } while (0)
; #define PG8_LDB(dst, b, h) do { _Pragma("unroll") for (int n = 0; n < 2; ++n) _Pragma("unroll") for (int k = 0; k < 2; ++k) dst[n][k] = *(const PG8_LAS bf16x8*)(lds + PG8_SB(b, h) + boff + n * 2048 + k * 1024); } while (0)
; #define PG8_MMA(ai, bj, At, Bt) do { __builtin_amdgcn_s_setprio(1); _Pragma("unroll") for (int m = 0; m < 4; ++m) _Pragma("unroll") for (int n = 0; n < 2; ++n) _Pragma("unroll") for (int k = 0; k < 2; ++k) \
;         acc[ai][bj][m][n] = __builtin_amdgcn_mfma_f32_16x16x32_bf16(Bt[n][k], At[m][k], acc[ai][bj][m][n], 0, 0, 0); __builtin_amdgcn_s_setprio(0); } while (0)
; #define PG8_WAIT_V(n) asm volatile("s_waitcnt vmcnt(" #n ")" ::: "memory")
; #define PG8_BAR __builtin_amdgcn_s_barrier()
; template <class Epi, class Sched, bool ALIGN_EPI = false, bool SP2 = false>
; __device__ __forceinline__ void gemm_phase(PG8_LAS unsigned char* lds, const Gemm g, const Sched& S, const Epi& E) {
;     ...
;         for (int t = 0; t < nt; t += 2) {
;             const bool last = (t == nt - 2);
;             const char* a1 = cA + (size_t)(t + 1) * kstep;
;             const char* a2 = last ? nA : cA + (size_t)(t + 2) * kstep; const char* b2 = last ? nB : cB + (size_t)(t + 2) * kstep;
;             const char* a3 = a2 + kstep; const char* b3 = b2 + kstep;
;             if (last && has_next) S.a_ready(nxt);
;             if constexpr (SP2) {
;             PG8_LDB(B0, 0, 0); PG8_LDB(B1, 0, 1); PG8_SCHED; PG8_LDA(At, 0, 0); PG8_STAGE(PG8_SA(1, 1), a1 + hstep, voffA);
;             PG8_WAIT_V(8); PG8_WAIT_L(0); PG8_BAR; PG8_MMA(0, 0, At, B0); PG8_MMA(0, 1, At, B1); PG8_BAR; PG8_SCHED;
;             PG8_LDA(At, 0, 1); PG8_STAGE(PG8_SB(0, 0), b2, voffB); PG8_STAGE(PG8_SB(0, 1), b2 + hstep, voffB); PG8_STAGE(PG8_SA(0, 0), a2, voffA);
;             PG8_WAIT_V(8); PG8_WAIT_L(0); PG8_BAR; PG8_MMA(1, 0, At, B0); PG8_MMA(1, 1, At, B1); PG8_BAR; PG8_SCHED;
.LBB0_749:
	ds_read_b128 v[140:143], v254
	ds_read_b128 v[162:165], v254 offset:1024
	ds_read_b128 v[166:169], v254 offset:2048
	ds_read_b128 v[170:173], v254 offset:3072
	ds_read_b128 v[180:183], v254 offset:16384
	ds_read_b128 v[184:187], v254 offset:17408
	ds_read_b128 v[188:191], v254 offset:18432
	ds_read_b128 v[210:213], v254 offset:19456
	s_add_u32 s2, s0, 0xfffc0080
	s_addc_u32 s3, s1, -1
	s_cmp_eq_u32 s55, 12
	s_cselect_b32 s5, s13, s3
	s_cselect_b32 s4, s25, s2
	s_cselect_b32 s3, s23, s39
	s_cselect_b32 s2, s33, s38
	s_add_i32 m0, s6, 0xc000
	ds_read_b128 v[214:217], v178
	ds_read_b128 v[218:221], v178 offset:1024
	ds_read_b128 v[222:225], v178 offset:2048
	ds_read_b128 v[226:229], v178 offset:3072
	ds_read_b128 v[230:233], v178 offset:4096
	ds_read_b128 v[234:237], v178 offset:5120
	ds_read_b128 v[238:241], v178 offset:6144
	ds_read_b128 v[242:245], v178 offset:7168
	global_load_lds_dwordx4 v136, s[0:1]
	s_add_i32 m0, s6, 0xe000
	s_nop 0
	global_load_lds_dwordx4 v138, s[0:1]
	s_waitcnt vmcnt(8)
	s_waitcnt lgkmcnt(0)
	s_barrier
	s_setprio 1
	v_mfma_f32_16x16x32_bf16 v[124:127], v[140:143], v[214:217], v[124:127]
	v_mfma_f32_16x16x32_bf16 v[120:123], v[166:169], v[214:217], v[120:123]
	v_mfma_f32_16x16x32_bf16 v[104:107], v[166:169], v[222:225], v[104:107]
	v_mfma_f32_16x16x32_bf16 v[108:111], v[140:143], v[222:225], v[108:111]
	v_mfma_f32_16x16x32_bf16 v[92:95], v[140:143], v[230:233], v[92:95]
	v_mfma_f32_16x16x32_bf16 v[88:91], v[166:169], v[230:233], v[88:91]
	v_mfma_f32_16x16x32_bf16 v[72:75], v[166:169], v[238:241], v[72:75]
	v_mfma_f32_16x16x32_bf16 v[76:79], v[140:143], v[238:241], v[76:79]
	v_mfma_f32_16x16x32_bf16 v[124:127], v[162:165], v[218:221], v[124:127]
	v_mfma_f32_16x16x32_bf16 v[120:123], v[170:173], v[218:221], v[120:123]
	v_mfma_f32_16x16x32_bf16 v[104:107], v[170:173], v[226:229], v[104:107]
	v_mfma_f32_16x16x32_bf16 v[108:111], v[162:165], v[226:229], v[108:111]
	v_mfma_f32_16x16x32_bf16 v[92:95], v[162:165], v[234:237], v[92:95]
	v_mfma_f32_16x16x32_bf16 v[88:91], v[170:173], v[234:237], v[88:91]
	v_mfma_f32_16x16x32_bf16 v[72:75], v[170:173], v[242:245], v[72:75]
	v_mfma_f32_16x16x32_bf16 v[76:79], v[162:165], v[242:245], v[76:79]
	v_mfma_f32_16x16x32_bf16 v[116:119], v[180:183], v[214:217], v[116:119]
	v_mfma_f32_16x16x32_bf16 v[112:115], v[188:191], v[214:217], v[112:115]
	v_mfma_f32_16x16x32_bf16 v[96:99], v[188:191], v[222:225], v[96:99]
	v_mfma_f32_16x16x32_bf16 v[100:103], v[180:183], v[222:225], v[100:103]
	v_mfma_f32_16x16x32_bf16 v[84:87], v[180:183], v[230:233], v[84:87]
	v_mfma_f32_16x16x32_bf16 v[80:83], v[188:191], v[230:233], v[80:83]
	v_mfma_f32_16x16x32_bf16 v[64:67], v[188:191], v[238:241], v[64:67]
	v_mfma_f32_16x16x32_bf16 v[68:71], v[180:183], v[238:241], v[68:71]
	v_mfma_f32_16x16x32_bf16 v[116:119], v[184:187], v[218:221], v[116:119]
	v_mfma_f32_16x16x32_bf16 v[112:115], v[210:213], v[218:221], v[112:115]
	v_mfma_f32_16x16x32_bf16 v[96:99], v[210:213], v[226:229], v[96:99]
	v_mfma_f32_16x16x32_bf16 v[100:103], v[184:187], v[226:229], v[100:103]
	v_mfma_f32_16x16x32_bf16 v[84:87], v[184:187], v[234:237], v[84:87]
	v_mfma_f32_16x16x32_bf16 v[80:83], v[210:213], v[234:237], v[80:83]
	v_mfma_f32_16x16x32_bf16 v[64:67], v[210:213], v[242:245], v[64:67]
	v_mfma_f32_16x16x32_bf16 v[68:71], v[184:187], v[242:245], v[68:71]
	s_setprio 0
	s_barrier
	s_mov_b32 m0, s31
	s_add_u32 s56, s2, 0x40000
	s_addc_u32 s57, s3, 0
	ds_read_b128 v[214:217], v178 offset:16384
	ds_read_b128 v[218:221], v178 offset:17408
	ds_read_b128 v[222:225], v178 offset:18432
	ds_read_b128 v[226:229], v178 offset:19456
	ds_read_b128 v[230:233], v178 offset:20480
	ds_read_b128 v[234:237], v178 offset:21504
	ds_read_b128 v[238:241], v178 offset:22528
	ds_read_b128 v[242:245], v178 offset:23552
	global_load_lds_dwordx4 v132, s[2:3]
	s_mov_b32 m0, s34
	s_nop 0
	global_load_lds_dwordx4 v128, s[2:3]
	s_mov_b32 m0, s35
	s_nop 0
	global_load_lds_dwordx4 v132, s[56:57]
	s_mov_b32 m0, s40
	s_nop 0
	global_load_lds_dwordx4 v128, s[56:57]
	s_mov_b32 m0, s6
	s_nop 0
	global_load_lds_dwordx4 v134, s[4:5]
	s_mov_b32 m0, s41
	s_nop 0
	global_load_lds_dwordx4 v130, s[4:5]
	s_waitcnt vmcnt(8)
	s_waitcnt lgkmcnt(0)
	s_barrier
	s_setprio 1
	v_mfma_f32_16x16x32_bf16 v[60:63], v[140:143], v[214:217], v[60:63]
	v_mfma_f32_16x16x32_bf16 v[56:59], v[166:169], v[214:217], v[56:59]
	v_mfma_f32_16x16x32_bf16 v[40:43], v[166:169], v[222:225], v[40:43]
	v_mfma_f32_16x16x32_bf16 v[44:47], v[140:143], v[222:225], v[44:47]
	v_mfma_f32_16x16x32_bf16 v[28:31], v[140:143], v[230:233], v[28:31]
	v_mfma_f32_16x16x32_bf16 v[24:27], v[166:169], v[230:233], v[24:27]
	v_mfma_f32_16x16x32_bf16 v[8:11], v[166:169], v[238:241], v[8:11]
	v_mfma_f32_16x16x32_bf16 v[12:15], v[140:143], v[238:241], v[12:15]
	v_mfma_f32_16x16x32_bf16 v[60:63], v[162:165], v[218:221], v[60:63]
	v_mfma_f32_16x16x32_bf16 v[56:59], v[170:173], v[218:221], v[56:59]
	v_mfma_f32_16x16x32_bf16 v[40:43], v[170:173], v[226:229], v[40:43]
	v_mfma_f32_16x16x32_bf16 v[44:47], v[162:165], v[226:229], v[44:47]
	v_mfma_f32_16x16x32_bf16 v[28:31], v[162:165], v[234:237], v[28:31]
	v_mfma_f32_16x16x32_bf16 v[24:27], v[170:173], v[234:237], v[24:27]
	v_mfma_f32_16x16x32_bf16 v[8:11], v[170:173], v[242:245], v[8:11]
	v_mfma_f32_16x16x32_bf16 v[12:15], v[162:165], v[242:245], v[12:15]
	v_mfma_f32_16x16x32_bf16 v[52:55], v[180:183], v[214:217], v[52:55]
	v_mfma_f32_16x16x32_bf16 v[48:51], v[188:191], v[214:217], v[48:51]
	v_mfma_f32_16x16x32_bf16 v[32:35], v[188:191], v[222:225], v[32:35]
	v_mfma_f32_16x16x32_bf16 v[36:39], v[180:183], v[222:225], v[36:39]
	v_mfma_f32_16x16x32_bf16 v[20:23], v[180:183], v[230:233], v[20:23]
	v_mfma_f32_16x16x32_bf16 v[16:19], v[188:191], v[230:233], v[16:19]
	v_mfma_f32_16x16x32_bf16 v[0:3], v[188:191], v[238:241], v[0:3]
	v_mfma_f32_16x16x32_bf16 v[4:7], v[180:183], v[238:241], v[4:7]
	v_mfma_f32_16x16x32_bf16 v[52:55], v[184:187], v[218:221], v[52:55]
	v_mfma_f32_16x16x32_bf16 v[48:51], v[210:213], v[218:221], v[48:51]
	v_mfma_f32_16x16x32_bf16 v[32:35], v[210:213], v[226:229], v[32:35]
	v_mfma_f32_16x16x32_bf16 v[36:39], v[184:187], v[226:229], v[36:39]
	v_mfma_f32_16x16x32_bf16 v[20:23], v[184:187], v[234:237], v[20:23]
	v_mfma_f32_16x16x32_bf16 v[16:19], v[210:213], v[234:237], v[16:19]
	v_mfma_f32_16x16x32_bf16 v[0:3], v[210:213], v[242:245], v[0:3]
	v_mfma_f32_16x16x32_bf16 v[4:7], v[184:187], v[242:245], v[4:7]
	s_setprio 0
	s_barrier
; #define PG8_STAGE(bufoff, gbase, voff) do { _Pragma("unroll") for (int _i = 0; _i < 2; ++_i) \
;         __builtin_amdgcn_global_load_lds((const unsigned*)((const char*)(gbase) + (voff)[_i]), (PG8_LAS unsigned*)(lds + (bufoff) + ldsw + _i * 8192), 16, 0, 0); } while (0)
; #define PG8_LDA(dst, b, h) do { _Pragma("unroll") for (int m = 0; m < 4; ++m) _Pragma("unroll") for (int k = 0; k < 2; ++k) dst[m][k] = *(const PG8_LAS bf16x8*)(lds + PG8_SA(b, h) + aoff + m * 2048 + k * 1024); } while (0)
; #define PG8_LDB(dst, b, h) do { _Pragma("unroll") for (int n = 0; n < 2; ++n) _Pragma("unroll") for (int k = 0; k < 2; ++k) dst[n][k] = *(const PG8_LAS bf16x8*)(lds + PG8_SB(b, h) + boff + n * 2048 + k * 1024); } while (0)
; #define PG8_MMA(ai, bj, At, Bt) do { __builtin_amdgcn_s_setprio(1); _Pragma("unroll") for (int m = 0; m < 4; ++m) _Pragma("unroll") for (int n = 0; n < 2; ++n) _Pragma("unroll") for (int k = 0; k < 2; ++k) \
;         acc[ai][bj][m][n] = __builtin_amdgcn_mfma_f32_16x16x32_bf16(Bt[n][k], At[m][k], acc[ai][bj][m][n], 0, 0, 0); __builtin_amdgcn_s_setprio(0); } while (0)
; #define PG8_WAIT_V(n) asm volatile("s_waitcnt vmcnt(" #n ")" ::: "memory")
; #define PG8_WAIT_L(n) asm volatile("s_waitcnt lgkmcnt(" #n ")" ::: "memory")
; #define PG8_BAR __builtin_amdgcn_s_barrier()
; #define PG8_SCHED __builtin_amdgcn_sched_barrier(0)
; template <class Epi, class Sched, bool ALIGN_EPI = false, bool SP2 = false>
; __device__ __forceinline__ void gemm_phase(PG8_LAS unsigned char* lds, const Gemm g, const Sched& S, const Epi& E) {
;     ...
;             PG8_LDB(B0, 1, 0); PG8_LDB(B1, 1, 1); PG8_SCHED; PG8_LDA(At, 1, 0); PG8_STAGE(PG8_SA(0, 1), a2 + hstep, voffA);
;             PG8_WAIT_V(8); PG8_WAIT_L(0); PG8_BAR; PG8_MMA(0, 0, At, B0); PG8_MMA(0, 1, At, B1); PG8_BAR; PG8_SCHED;
;             PG8_LDA(At, 1, 1); PG8_STAGE(PG8_SB(1, 0), b3, voffB); PG8_STAGE(PG8_SB(1, 1), b3 + hstep, voffB); PG8_STAGE(PG8_SA(1, 0), a3, voffA);
;             PG8_WAIT_V(8); PG8_WAIT_L(0); PG8_BAR; PG8_MMA(1, 0, At, B0); PG8_MMA(1, 1, At, B1); PG8_BAR; PG8_SCHED;
	ds_read_b128 v[140:143], v254 offset:32768
	ds_read_b128 v[162:165], v254 offset:33792
	ds_read_b128 v[166:169], v254 offset:34816
	ds_read_b128 v[170:173], v254 offset:35840
	ds_read_b128 v[180:183], v254 offset:49152
	ds_read_b128 v[184:187], v254 offset:50176
	ds_read_b128 v[188:191], v254 offset:51200
	ds_read_b128 v[210:213], v254 offset:52224
	s_add_u32 s4, s4, 0x40000
	s_addc_u32 s5, s5, 0
	s_mov_b32 m0, s42
	ds_read_b128 v[214:217], v178 offset:32768
	ds_read_b128 v[218:221], v178 offset:33792
	ds_read_b128 v[222:225], v178 offset:34816
	ds_read_b128 v[226:229], v178 offset:35840
	ds_read_b128 v[230:233], v178 offset:36864
	ds_read_b128 v[234:237], v178 offset:37888
	ds_read_b128 v[238:241], v178 offset:38912
	ds_read_b128 v[242:245], v178 offset:39936
	global_load_lds_dwordx4 v134, s[4:5]
	s_mov_b32 m0, s43
	s_nop 0
	global_load_lds_dwordx4 v130, s[4:5]
	s_waitcnt vmcnt(8)
	s_waitcnt lgkmcnt(0)
	s_barrier
	s_setprio 1
	v_mfma_f32_16x16x32_bf16 v[124:127], v[140:143], v[214:217], v[124:127]
	v_mfma_f32_16x16x32_bf16 v[120:123], v[166:169], v[214:217], v[120:123]
	v_mfma_f32_16x16x32_bf16 v[104:107], v[166:169], v[222:225], v[104:107]
	v_mfma_f32_16x16x32_bf16 v[108:111], v[140:143], v[222:225], v[108:111]
	v_mfma_f32_16x16x32_bf16 v[92:95], v[140:143], v[230:233], v[92:95]
	v_mfma_f32_16x16x32_bf16 v[88:91], v[166:169], v[230:233], v[88:91]
	v_mfma_f32_16x16x32_bf16 v[72:75], v[166:169], v[238:241], v[72:75]
	v_mfma_f32_16x16x32_bf16 v[76:79], v[140:143], v[238:241], v[76:79]
	v_mfma_f32_16x16x32_bf16 v[124:127], v[162:165], v[218:221], v[124:127]
	v_mfma_f32_16x16x32_bf16 v[120:123], v[170:173], v[218:221], v[120:123]
	v_mfma_f32_16x16x32_bf16 v[104:107], v[170:173], v[226:229], v[104:107]
	v_mfma_f32_16x16x32_bf16 v[108:111], v[162:165], v[226:229], v[108:111]
	v_mfma_f32_16x16x32_bf16 v[92:95], v[162:165], v[234:237], v[92:95]
	v_mfma_f32_16x16x32_bf16 v[88:91], v[170:173], v[234:237], v[88:91]
	v_mfma_f32_16x16x32_bf16 v[72:75], v[170:173], v[242:245], v[72:75]
	v_mfma_f32_16x16x32_bf16 v[76:79], v[162:165], v[242:245], v[76:79]
	v_mfma_f32_16x16x32_bf16 v[116:119], v[180:183], v[214:217], v[116:119]
	v_mfma_f32_16x16x32_bf16 v[112:115], v[188:191], v[214:217], v[112:115]
	v_mfma_f32_16x16x32_bf16 v[96:99], v[188:191], v[222:225], v[96:99]
	v_mfma_f32_16x16x32_bf16 v[100:103], v[180:183], v[222:225], v[100:103]
	v_mfma_f32_16x16x32_bf16 v[84:87], v[180:183], v[230:233], v[84:87]
	v_mfma_f32_16x16x32_bf16 v[80:83], v[188:191], v[230:233], v[80:83]
	v_mfma_f32_16x16x32_bf16 v[64:67], v[188:191], v[238:241], v[64:67]
	v_mfma_f32_16x16x32_bf16 v[68:71], v[180:183], v[238:241], v[68:71]
	v_mfma_f32_16x16x32_bf16 v[116:119], v[184:187], v[218:221], v[116:119]
	v_mfma_f32_16x16x32_bf16 v[112:115], v[210:213], v[218:221], v[112:115]
	v_mfma_f32_16x16x32_bf16 v[96:99], v[210:213], v[226:229], v[96:99]
	v_mfma_f32_16x16x32_bf16 v[100:103], v[184:187], v[226:229], v[100:103]
	v_mfma_f32_16x16x32_bf16 v[84:87], v[184:187], v[234:237], v[84:87]
	v_mfma_f32_16x16x32_bf16 v[80:83], v[210:213], v[234:237], v[80:83]
	v_mfma_f32_16x16x32_bf16 v[64:67], v[210:213], v[242:245], v[64:67]
	v_mfma_f32_16x16x32_bf16 v[68:71], v[184:187], v[242:245], v[68:71]
	s_setprio 0
	s_barrier
	s_mov_b32 m0, s48
	s_add_u32 s2, s2, 0x40080
	s_addc_u32 s3, s3, 0
	ds_read_b128 v[214:217], v178 offset:49152
	ds_read_b128 v[218:221], v178 offset:50176
	ds_read_b128 v[222:225], v178 offset:51200
	ds_read_b128 v[226:229], v178 offset:52224
	ds_read_b128 v[230:233], v178 offset:53248
	ds_read_b128 v[234:237], v178 offset:54272
	ds_read_b128 v[238:241], v178 offset:55296
	ds_read_b128 v[242:245], v178 offset:56320
	s_add_u32 s98, s2, 0xfffc0000
	s_addc_u32 s99, s3, -1
	global_load_lds_dwordx4 v132, s[98:99]
	s_mov_b32 m0, s49
	s_nop 0
	global_load_lds_dwordx4 v128, s[98:99]
	s_mov_b32 m0, s52
	s_nop 0
	global_load_lds_dwordx4 v132, s[2:3]
	s_mov_b32 m0, s53
	s_nop 0
	global_load_lds_dwordx4 v128, s[2:3]
	s_mov_b32 m0, s50
	s_nop 0
	s_add_u32 s100, s4, 0xfffc0080
	s_addc_u32 s101, s5, -1
	global_load_lds_dwordx4 v134, s[100:101]
	s_mov_b32 m0, s51
	s_nop 0
	global_load_lds_dwordx4 v130, s[100:101]
	s_waitcnt vmcnt(8)
	s_waitcnt lgkmcnt(0)
	s_barrier
	s_setprio 1
	v_mfma_f32_16x16x32_bf16 v[60:63], v[140:143], v[214:217], v[60:63]
	v_mfma_f32_16x16x32_bf16 v[56:59], v[166:169], v[214:217], v[56:59]
	v_mfma_f32_16x16x32_bf16 v[40:43], v[166:169], v[222:225], v[40:43]
	v_mfma_f32_16x16x32_bf16 v[44:47], v[140:143], v[222:225], v[44:47]
	v_mfma_f32_16x16x32_bf16 v[28:31], v[140:143], v[230:233], v[28:31]
	v_mfma_f32_16x16x32_bf16 v[24:27], v[166:169], v[230:233], v[24:27]
	v_mfma_f32_16x16x32_bf16 v[8:11], v[166:169], v[238:241], v[8:11]
	v_mfma_f32_16x16x32_bf16 v[12:15], v[140:143], v[238:241], v[12:15]
	v_mfma_f32_16x16x32_bf16 v[60:63], v[162:165], v[218:221], v[60:63]
	v_mfma_f32_16x16x32_bf16 v[56:59], v[170:173], v[218:221], v[56:59]
	v_mfma_f32_16x16x32_bf16 v[40:43], v[170:173], v[226:229], v[40:43]
	v_mfma_f32_16x16x32_bf16 v[44:47], v[162:165], v[226:229], v[44:47]
	v_mfma_f32_16x16x32_bf16 v[28:31], v[162:165], v[234:237], v[28:31]
	v_mfma_f32_16x16x32_bf16 v[24:27], v[170:173], v[234:237], v[24:27]
	v_mfma_f32_16x16x32_bf16 v[8:11], v[170:173], v[242:245], v[8:11]
	v_mfma_f32_16x16x32_bf16 v[12:15], v[162:165], v[242:245], v[12:15]
	v_mfma_f32_16x16x32_bf16 v[52:55], v[180:183], v[214:217], v[52:55]
	v_mfma_f32_16x16x32_bf16 v[48:51], v[188:191], v[214:217], v[48:51]
	v_mfma_f32_16x16x32_bf16 v[32:35], v[188:191], v[222:225], v[32:35]
	v_mfma_f32_16x16x32_bf16 v[36:39], v[180:183], v[222:225], v[36:39]
	v_mfma_f32_16x16x32_bf16 v[20:23], v[180:183], v[230:233], v[20:23]
	v_mfma_f32_16x16x32_bf16 v[16:19], v[188:191], v[230:233], v[16:19]
	v_mfma_f32_16x16x32_bf16 v[0:3], v[188:191], v[238:241], v[0:3]
	v_mfma_f32_16x16x32_bf16 v[4:7], v[180:183], v[238:241], v[4:7]
	v_mfma_f32_16x16x32_bf16 v[52:55], v[184:187], v[218:221], v[52:55]
	v_mfma_f32_16x16x32_bf16 v[48:51], v[210:213], v[218:221], v[48:51]
	v_mfma_f32_16x16x32_bf16 v[32:35], v[210:213], v[226:229], v[32:35]
	v_mfma_f32_16x16x32_bf16 v[36:39], v[184:187], v[226:229], v[36:39]
	v_mfma_f32_16x16x32_bf16 v[20:23], v[184:187], v[234:237], v[20:23]
	v_mfma_f32_16x16x32_bf16 v[16:19], v[210:213], v[234:237], v[16:19]
	v_mfma_f32_16x16x32_bf16 v[0:3], v[210:213], v[242:245], v[0:3]
	v_mfma_f32_16x16x32_bf16 v[4:7], v[184:187], v[242:245], v[4:7]
	s_setprio 0
	s_barrier
	s_add_i32 s55, s55, 2
	s_add_u32 s0, s0, 0x100
	s_addc_u32 s1, s1, 0
	s_add_u32 s38, s38, 0x100
	s_addc_u32 s39, s39, 0
	s_cmp_gt_u32 s55, 13
	s_cbranch_scc0 .LBB0_749
	s_and_b64 vcc, exec, s[18:19]
	s_cbranch_vccz .LBB0_752
	s_barrier

; #define PG8_STAGE(bufoff, gbase, voff) do { _Pragma("unroll") for (int _i = 0; _i < 2; ++_i) \
;         __builtin_amdgcn_global_load_lds((const unsigned*)((const char*)(gbase) + (voff)[_i]), (PG8_LAS unsigned*)(lds + (bufoff) + ldsw + _i * 8192), 16, 0, 0); } while (0)
; #define PG8_LDA(dst, b, h) do { _Pragma("unroll") for (int m = 0; m < 4; ++m) _Pragma("unroll") for (int k = 0; k < 2; ++k) dst[m][k] = *(const PG8_LAS bf16x8*)(lds + PG8_SA(b, h) + aoff + m * 2048 + k * 1024); } while (0)
; #define PG8_LDB(dst, b, h) do { _Pragma("unroll") for (int n = 0; n < 2; ++n) _Pragma("unroll") for (int k = 0; k < 2; ++k) dst[n][k] = *(const PG8_LAS bf16x8*)(lds + PG8_SB(b, h) + boff + n * 2048 + k * 1024); } while (0)
; #define PG8_MMA(ai, bj, At, Bt) do { __builtin_amdgcn_s_setprio(1); _Pragma("unroll") for (int m = 0; m < 4; ++m) _Pragma("unroll") for (int n = 0; n < 2; ++n) _Pragma("unroll") for (int k = 0; k < 2; ++k) \
;         acc[ai][bj][m][n] = __builtin_amdgcn_mfma_f32_16x16x32_bf16(Bt[n][k], At[m][k], acc[ai][bj][m][n], 0, 0, 0); __builtin_amdgcn_s_setprio(0); } while (0)
; #define PG8_WAIT_V(n) asm volatile("s_waitcnt vmcnt(" #n ")" ::: "memory")
; #define PG8_BAR __builtin_amdgcn_s_barrier()
; template <class Epi, class Sched, bool ALIGN_EPI = false, bool SP2 = false>
; __device__ __forceinline__ void gemm_phase(PG8_LAS unsigned char* lds, const Gemm g, const Sched& S, const Epi& E) {
;     ...
;         for (int t = 0; t < nt; t += 2) {
;             const bool last = (t == nt - 2);
;             const char* a1 = cA + (size_t)(t + 1) * kstep;
;             const char* a2 = last ? nA : cA + (size_t)(t + 2) * kstep; const char* b2 = last ? nB : cB + (size_t)(t + 2) * kstep;
;             const char* a3 = a2 + kstep; const char* b3 = b2 + kstep;
;             if (last && has_next) S.a_ready(nxt);
;             if constexpr (SP2) {
;             PG8_LDB(B0, 0, 0); PG8_LDB(B1, 0, 1); PG8_SCHED; PG8_LDA(At, 0, 0); PG8_STAGE(PG8_SA(1, 1), a1 + hstep, voffA);
;             PG8_WAIT_V(8); PG8_WAIT_L(0); PG8_BAR; PG8_MMA(0, 0, At, B0); PG8_MMA(0, 1, At, B1); PG8_BAR; PG8_SCHED;
;             PG8_LDA(At, 0, 1); PG8_STAGE(PG8_SB(0, 0), b2, voffB); PG8_STAGE(PG8_SB(0, 1), b2 + hstep, voffB); PG8_STAGE(PG8_SA(0, 0), a2, voffA);
;             PG8_WAIT_V(8); PG8_WAIT_L(0); PG8_BAR; PG8_MMA(1, 0, At, B0); PG8_MMA(1, 1, At, B1); PG8_BAR; PG8_SCHED;
.Labi_peel:
	s_waitcnt lgkmcnt(0)
	ds_read_b128 v[140:143], v254
	ds_read_b128 v[162:165], v254 offset:1024
	ds_read_b128 v[166:169], v254 offset:2048
	ds_read_b128 v[176:179], v254 offset:3072
	ds_read_b128 v[180:183], v254 offset:16384
	ds_read_b128 v[184:187], v254 offset:17408
	ds_read_b128 v[188:191], v254 offset:18432
	ds_read_b128 v[210:213], v254 offset:19456
	s_add_u32 s2, s0, 0xfffc0080
	s_addc_u32 s3, s1, -1
	s_cmp_eq_u32 s52, 12
	s_cselect_b32 s5, s17, s3
	s_cselect_b32 s4, s48, s2
	s_cselect_b32 s3, s15, s51
	s_cselect_b32 s2, s49, s50
	s_add_i32 m0, s6, 0xc000
	ds_read_b128 v[214:217], v173
	ds_read_b128 v[218:221], v173 offset:1024
	ds_read_b128 v[222:225], v173 offset:2048
	ds_read_b128 v[226:229], v173 offset:3072
	ds_read_b128 v[230:233], v173 offset:4096
	ds_read_b128 v[234:237], v173 offset:5120
	ds_read_b128 v[238:241], v173 offset:6144
	ds_read_b128 v[242:245], v173 offset:7168
	global_load_lds_dwordx4 v136, s[0:1]
	s_add_i32 m0, s6, 0xe000
	s_nop 0
	global_load_lds_dwordx4 v138, s[0:1]
	s_waitcnt vmcnt(8)
	s_waitcnt lgkmcnt(0)
	s_barrier
	s_setprio 1
	v_mfma_f32_16x16x32_bf16 v[124:127], v[140:143], v[214:217], 0
	v_mfma_f32_16x16x32_bf16 v[120:123], v[166:169], v[214:217], 0
	v_mfma_f32_16x16x32_bf16 v[104:107], v[166:169], v[222:225], 0
	v_mfma_f32_16x16x32_bf16 v[112:115], v[140:143], v[222:225], 0
	v_mfma_f32_16x16x32_bf16 v[96:99], v[140:143], v[230:233], 0
	v_mfma_f32_16x16x32_bf16 v[88:91], v[166:169], v[230:233], 0
	v_mfma_f32_16x16x32_bf16 v[72:75], v[166:169], v[238:241], 0
	v_mfma_f32_16x16x32_bf16 v[80:83], v[140:143], v[238:241], 0
	v_mfma_f32_16x16x32_bf16 v[124:127], v[162:165], v[218:221], v[124:127]
	v_mfma_f32_16x16x32_bf16 v[120:123], v[176:179], v[218:221], v[120:123]
	v_mfma_f32_16x16x32_bf16 v[104:107], v[176:179], v[226:229], v[104:107]
	v_mfma_f32_16x16x32_bf16 v[112:115], v[162:165], v[226:229], v[112:115]
	v_mfma_f32_16x16x32_bf16 v[96:99], v[162:165], v[234:237], v[96:99]
	v_mfma_f32_16x16x32_bf16 v[88:91], v[176:179], v[234:237], v[88:91]
	v_mfma_f32_16x16x32_bf16 v[72:75], v[176:179], v[242:245], v[72:75]
	v_mfma_f32_16x16x32_bf16 v[80:83], v[162:165], v[242:245], v[80:83]
	v_mfma_f32_16x16x32_bf16 v[116:119], v[180:183], v[214:217], 0
	v_mfma_f32_16x16x32_bf16 v[108:111], v[188:191], v[214:217], 0
	v_mfma_f32_16x16x32_bf16 v[92:95], v[188:191], v[222:225], 0
	v_mfma_f32_16x16x32_bf16 v[100:103], v[180:183], v[222:225], 0
	v_mfma_f32_16x16x32_bf16 v[84:87], v[180:183], v[230:233], 0
	v_mfma_f32_16x16x32_bf16 v[76:79], v[188:191], v[230:233], 0
	v_mfma_f32_16x16x32_bf16 v[64:67], v[188:191], v[238:241], 0
	v_mfma_f32_16x16x32_bf16 v[68:71], v[180:183], v[238:241], 0
	v_mfma_f32_16x16x32_bf16 v[116:119], v[184:187], v[218:221], v[116:119]
	v_mfma_f32_16x16x32_bf16 v[108:111], v[210:213], v[218:221], v[108:111]
	v_mfma_f32_16x16x32_bf16 v[92:95], v[210:213], v[226:229], v[92:95]
	v_mfma_f32_16x16x32_bf16 v[100:103], v[184:187], v[226:229], v[100:103]
	v_mfma_f32_16x16x32_bf16 v[84:87], v[184:187], v[234:237], v[84:87]
	v_mfma_f32_16x16x32_bf16 v[76:79], v[210:213], v[234:237], v[76:79]
	v_mfma_f32_16x16x32_bf16 v[64:67], v[210:213], v[242:245], v[64:67]
	v_mfma_f32_16x16x32_bf16 v[68:71], v[184:187], v[242:245], v[68:71]
	s_setprio 0
	s_barrier
	s_mov_b32 m0, s27
	s_add_u32 s54, s2, 0x40000
	s_addc_u32 s55, s3, 0
	ds_read_b128 v[214:217], v173 offset:16384
	ds_read_b128 v[218:221], v173 offset:17408
	ds_read_b128 v[222:225], v173 offset:18432
	ds_read_b128 v[226:229], v173 offset:19456
	ds_read_b128 v[230:233], v173 offset:20480
	ds_read_b128 v[234:237], v173 offset:21504
	ds_read_b128 v[238:241], v173 offset:22528
	ds_read_b128 v[242:245], v173 offset:23552
	global_load_lds_dwordx4 v132, s[2:3]
	s_mov_b32 m0, s28
	s_nop 0
	global_load_lds_dwordx4 v128, s[2:3]
	s_mov_b32 m0, s29
	s_nop 0
	global_load_lds_dwordx4 v132, s[54:55]
	s_mov_b32 m0, s30
	s_nop 0
	global_load_lds_dwordx4 v128, s[54:55]
	s_mov_b32 m0, s6
	s_nop 0
	global_load_lds_dwordx4 v134, s[4:5]
	s_mov_b32 m0, s31
	s_nop 0
	global_load_lds_dwordx4 v130, s[4:5]
	s_waitcnt vmcnt(8)
	s_waitcnt lgkmcnt(0)
	s_barrier
	s_setprio 1
	v_mfma_f32_16x16x32_bf16 v[60:63], v[140:143], v[214:217], 0
	v_mfma_f32_16x16x32_bf16 v[56:59], v[166:169], v[214:217], 0
	v_mfma_f32_16x16x32_bf16 v[40:43], v[166:169], v[222:225], 0
	v_mfma_f32_16x16x32_bf16 v[48:51], v[140:143], v[222:225], 0
	v_mfma_f32_16x16x32_bf16 v[32:35], v[140:143], v[230:233], 0
	v_mfma_f32_16x16x32_bf16 v[24:27], v[166:169], v[230:233], 0
	v_mfma_f32_16x16x32_bf16 v[8:11], v[166:169], v[238:241], 0
	v_mfma_f32_16x16x32_bf16 v[16:19], v[140:143], v[238:241], 0
	v_mfma_f32_16x16x32_bf16 v[60:63], v[162:165], v[218:221], v[60:63]
	v_mfma_f32_16x16x32_bf16 v[56:59], v[176:179], v[218:221], v[56:59]
	v_mfma_f32_16x16x32_bf16 v[40:43], v[176:179], v[226:229], v[40:43]
	v_mfma_f32_16x16x32_bf16 v[48:51], v[162:165], v[226:229], v[48:51]
	v_mfma_f32_16x16x32_bf16 v[32:35], v[162:165], v[234:237], v[32:35]
	v_mfma_f32_16x16x32_bf16 v[24:27], v[176:179], v[234:237], v[24:27]
	v_mfma_f32_16x16x32_bf16 v[8:11], v[176:179], v[242:245], v[8:11]
	v_mfma_f32_16x16x32_bf16 v[16:19], v[162:165], v[242:245], v[16:19]
	v_mfma_f32_16x16x32_bf16 v[52:55], v[180:183], v[214:217], 0
	v_mfma_f32_16x16x32_bf16 v[44:47], v[188:191], v[214:217], 0
	v_mfma_f32_16x16x32_bf16 v[28:31], v[188:191], v[222:225], 0
	v_mfma_f32_16x16x32_bf16 v[36:39], v[180:183], v[222:225], 0
	v_mfma_f32_16x16x32_bf16 v[20:23], v[180:183], v[230:233], 0
	v_mfma_f32_16x16x32_bf16 v[12:15], v[188:191], v[230:233], 0
	v_mfma_f32_16x16x32_bf16 v[0:3], v[188:191], v[238:241], 0
	v_mfma_f32_16x16x32_bf16 v[4:7], v[180:183], v[238:241], 0
	v_mfma_f32_16x16x32_bf16 v[52:55], v[184:187], v[218:221], v[52:55]
	v_mfma_f32_16x16x32_bf16 v[44:47], v[210:213], v[218:221], v[44:47]
	v_mfma_f32_16x16x32_bf16 v[28:31], v[210:213], v[226:229], v[28:31]
	v_mfma_f32_16x16x32_bf16 v[36:39], v[184:187], v[226:229], v[36:39]
	v_mfma_f32_16x16x32_bf16 v[20:23], v[184:187], v[234:237], v[20:23]
	v_mfma_f32_16x16x32_bf16 v[12:15], v[210:213], v[234:237], v[12:15]
	v_mfma_f32_16x16x32_bf16 v[0:3], v[210:213], v[242:245], v[0:3]
	v_mfma_f32_16x16x32_bf16 v[4:7], v[184:187], v[242:245], v[4:7]
	s_setprio 0
	s_barrier
; #define PG8_STAGE(bufoff, gbase, voff) do { _Pragma("unroll") for (int _i = 0; _i < 2; ++_i) \
;         __builtin_amdgcn_global_load_lds((const unsigned*)((const char*)(gbase) + (voff)[_i]), (PG8_LAS unsigned*)(lds + (bufoff) + ldsw + _i * 8192), 16, 0, 0); } while (0)
; #define PG8_LDA(dst, b, h) do { _Pragma("unroll") for (int m = 0; m < 4; ++m) _Pragma("unroll") for (int k = 0; k < 2; ++k) dst[m][k] = *(const PG8_LAS bf16x8*)(lds + PG8_SA(b, h) + aoff + m * 2048 + k * 1024); } while (0)
; #define PG8_LDB(dst, b, h) do { _Pragma("unroll") for (int n = 0; n < 2; ++n) _Pragma("unroll") for (int k = 0; k < 2; ++k) dst[n][k] = *(const PG8_LAS bf16x8*)(lds + PG8_SB(b, h) + boff + n * 2048 + k * 1024); } while (0)
; #define PG8_MMA(ai, bj, At, Bt) do { __builtin_amdgcn_s_setprio(1); _Pragma("unroll") for (int m = 0; m < 4; ++m) _Pragma("unroll") for (int n = 0; n < 2; ++n) _Pragma("unroll") for (int k = 0; k < 2; ++k) \
;         acc[ai][bj][m][n] = __builtin_amdgcn_mfma_f32_16x16x32_bf16(Bt[n][k], At[m][k], acc[ai][bj][m][n], 0, 0, 0); __builtin_amdgcn_s_setprio(0); } while (0)
; #define PG8_WAIT_V(n) asm volatile("s_waitcnt vmcnt(" #n ")" ::: "memory")
; #define PG8_WAIT_L(n) asm volatile("s_waitcnt lgkmcnt(" #n ")" ::: "memory")
; #define PG8_BAR __builtin_amdgcn_s_barrier()
; #define PG8_SCHED __builtin_amdgcn_sched_barrier(0)
; template <class Epi, class Sched, bool ALIGN_EPI = false, bool SP2 = false>
; __device__ __forceinline__ void gemm_phase(PG8_LAS unsigned char* lds, const Gemm g, const Sched& S, const Epi& E) {
;     ...
;             PG8_LDB(B0, 1, 0); PG8_LDB(B1, 1, 1); PG8_SCHED; PG8_LDA(At, 1, 0); PG8_STAGE(PG8_SA(0, 1), a2 + hstep, voffA);
;             PG8_WAIT_V(8); PG8_WAIT_L(0); PG8_BAR; PG8_MMA(0, 0, At, B0); PG8_MMA(0, 1, At, B1); PG8_BAR; PG8_SCHED;
;             PG8_LDA(At, 1, 1); PG8_STAGE(PG8_SB(1, 0), b3, voffB); PG8_STAGE(PG8_SB(1, 1), b3 + hstep, voffB); PG8_STAGE(PG8_SA(1, 0), a3, voffA);
;             PG8_WAIT_V(8); PG8_WAIT_L(0); PG8_BAR; PG8_MMA(1, 0, At, B0); PG8_MMA(1, 1, At, B1); PG8_BAR; PG8_SCHED;
	ds_read_b128 v[140:143], v254 offset:32768
	ds_read_b128 v[162:165], v254 offset:33792
	ds_read_b128 v[166:169], v254 offset:34816
	ds_read_b128 v[176:179], v254 offset:35840
	ds_read_b128 v[180:183], v254 offset:49152
	ds_read_b128 v[184:187], v254 offset:50176
	ds_read_b128 v[188:191], v254 offset:51200
	ds_read_b128 v[210:213], v254 offset:52224
	s_add_u32 s4, s4, 0x40000
	s_addc_u32 s5, s5, 0
	s_mov_b32 m0, s33
	ds_read_b128 v[214:217], v173 offset:32768
	ds_read_b128 v[218:221], v173 offset:33792
	ds_read_b128 v[222:225], v173 offset:34816
	ds_read_b128 v[226:229], v173 offset:35840
	ds_read_b128 v[230:233], v173 offset:36864
	ds_read_b128 v[234:237], v173 offset:37888
	ds_read_b128 v[238:241], v173 offset:38912
	ds_read_b128 v[242:245], v173 offset:39936
	global_load_lds_dwordx4 v134, s[4:5]
	s_mov_b32 m0, s34
	s_nop 0
	global_load_lds_dwordx4 v130, s[4:5]
	s_waitcnt vmcnt(8)
	s_waitcnt lgkmcnt(0)
	s_barrier
	s_setprio 1
	v_mfma_f32_16x16x32_bf16 v[124:127], v[140:143], v[214:217], v[124:127]
	v_mfma_f32_16x16x32_bf16 v[120:123], v[166:169], v[214:217], v[120:123]
	v_mfma_f32_16x16x32_bf16 v[104:107], v[166:169], v[222:225], v[104:107]
	v_mfma_f32_16x16x32_bf16 v[112:115], v[140:143], v[222:225], v[112:115]
	v_mfma_f32_16x16x32_bf16 v[96:99], v[140:143], v[230:233], v[96:99]
	v_mfma_f32_16x16x32_bf16 v[88:91], v[166:169], v[230:233], v[88:91]
	v_mfma_f32_16x16x32_bf16 v[72:75], v[166:169], v[238:241], v[72:75]
	v_mfma_f32_16x16x32_bf16 v[80:83], v[140:143], v[238:241], v[80:83]
	v_mfma_f32_16x16x32_bf16 v[124:127], v[162:165], v[218:221], v[124:127]
	v_mfma_f32_16x16x32_bf16 v[120:123], v[176:179], v[218:221], v[120:123]
	v_mfma_f32_16x16x32_bf16 v[104:107], v[176:179], v[226:229], v[104:107]
	v_mfma_f32_16x16x32_bf16 v[112:115], v[162:165], v[226:229], v[112:115]
	v_mfma_f32_16x16x32_bf16 v[96:99], v[162:165], v[234:237], v[96:99]
	v_mfma_f32_16x16x32_bf16 v[88:91], v[176:179], v[234:237], v[88:91]
	v_mfma_f32_16x16x32_bf16 v[72:75], v[176:179], v[242:245], v[72:75]
	v_mfma_f32_16x16x32_bf16 v[80:83], v[162:165], v[242:245], v[80:83]
	v_mfma_f32_16x16x32_bf16 v[116:119], v[180:183], v[214:217], v[116:119]
	v_mfma_f32_16x16x32_bf16 v[108:111], v[188:191], v[214:217], v[108:111]
	v_mfma_f32_16x16x32_bf16 v[92:95], v[188:191], v[222:225], v[92:95]
	v_mfma_f32_16x16x32_bf16 v[100:103], v[180:183], v[222:225], v[100:103]
	v_mfma_f32_16x16x32_bf16 v[84:87], v[180:183], v[230:233], v[84:87]
	v_mfma_f32_16x16x32_bf16 v[76:79], v[188:191], v[230:233], v[76:79]
	v_mfma_f32_16x16x32_bf16 v[64:67], v[188:191], v[238:241], v[64:67]
	v_mfma_f32_16x16x32_bf16 v[68:71], v[180:183], v[238:241], v[68:71]
	v_mfma_f32_16x16x32_bf16 v[116:119], v[184:187], v[218:221], v[116:119]
	v_mfma_f32_16x16x32_bf16 v[108:111], v[210:213], v[218:221], v[108:111]
	v_mfma_f32_16x16x32_bf16 v[92:95], v[210:213], v[226:229], v[92:95]
	v_mfma_f32_16x16x32_bf16 v[100:103], v[184:187], v[226:229], v[100:103]
	v_mfma_f32_16x16x32_bf16 v[84:87], v[184:187], v[234:237], v[84:87]
	v_mfma_f32_16x16x32_bf16 v[76:79], v[210:213], v[234:237], v[76:79]
	v_mfma_f32_16x16x32_bf16 v[64:67], v[210:213], v[242:245], v[64:67]
	v_mfma_f32_16x16x32_bf16 v[68:71], v[184:187], v[242:245], v[68:71]
	s_setprio 0
	s_barrier
	s_mov_b32 m0, s37
	s_add_u32 s2, s2, 0x40080
	s_addc_u32 s3, s3, 0
	ds_read_b128 v[214:217], v173 offset:49152
	ds_read_b128 v[218:221], v173 offset:50176
	ds_read_b128 v[222:225], v173 offset:51200
	ds_read_b128 v[226:229], v173 offset:52224
	ds_read_b128 v[230:233], v173 offset:53248
	ds_read_b128 v[234:237], v173 offset:54272
	ds_read_b128 v[238:241], v173 offset:55296
	ds_read_b128 v[242:245], v173 offset:56320
	s_add_u32 s98, s2, 0xfffc0000
	s_addc_u32 s99, s3, -1
	global_load_lds_dwordx4 v132, s[98:99]
	s_mov_b32 m0, s38
	s_nop 0
	global_load_lds_dwordx4 v128, s[98:99]
	s_mov_b32 m0, s41
	s_nop 0
	global_load_lds_dwordx4 v132, s[2:3]
	s_mov_b32 m0, s42
	s_nop 0
	global_load_lds_dwordx4 v128, s[2:3]
	s_mov_b32 m0, s39
	s_nop 0
	s_add_u32 s100, s4, 0xfffc0080
	s_addc_u32 s101, s5, -1
	global_load_lds_dwordx4 v134, s[100:101]
	s_mov_b32 m0, s40
	s_nop 0
	global_load_lds_dwordx4 v130, s[100:101]
	s_waitcnt vmcnt(8)
	s_waitcnt lgkmcnt(0)
	s_barrier
	s_setprio 1
	v_mfma_f32_16x16x32_bf16 v[60:63], v[140:143], v[214:217], v[60:63]
	v_mfma_f32_16x16x32_bf16 v[56:59], v[166:169], v[214:217], v[56:59]
	v_mfma_f32_16x16x32_bf16 v[40:43], v[166:169], v[222:225], v[40:43]
	v_mfma_f32_16x16x32_bf16 v[48:51], v[140:143], v[222:225], v[48:51]
	v_mfma_f32_16x16x32_bf16 v[32:35], v[140:143], v[230:233], v[32:35]
	v_mfma_f32_16x16x32_bf16 v[24:27], v[166:169], v[230:233], v[24:27]
	v_mfma_f32_16x16x32_bf16 v[8:11], v[166:169], v[238:241], v[8:11]
	v_mfma_f32_16x16x32_bf16 v[16:19], v[140:143], v[238:241], v[16:19]
	v_mfma_f32_16x16x32_bf16 v[60:63], v[162:165], v[218:221], v[60:63]
	v_mfma_f32_16x16x32_bf16 v[56:59], v[176:179], v[218:221], v[56:59]
	v_mfma_f32_16x16x32_bf16 v[40:43], v[176:179], v[226:229], v[40:43]
	v_mfma_f32_16x16x32_bf16 v[48:51], v[162:165], v[226:229], v[48:51]
	v_mfma_f32_16x16x32_bf16 v[32:35], v[162:165], v[234:237], v[32:35]
	v_mfma_f32_16x16x32_bf16 v[24:27], v[176:179], v[234:237], v[24:27]
	v_mfma_f32_16x16x32_bf16 v[8:11], v[176:179], v[242:245], v[8:11]
	v_mfma_f32_16x16x32_bf16 v[16:19], v[162:165], v[242:245], v[16:19]
	v_mfma_f32_16x16x32_bf16 v[52:55], v[180:183], v[214:217], v[52:55]
	v_mfma_f32_16x16x32_bf16 v[44:47], v[188:191], v[214:217], v[44:47]
	v_mfma_f32_16x16x32_bf16 v[28:31], v[188:191], v[222:225], v[28:31]
	v_mfma_f32_16x16x32_bf16 v[36:39], v[180:183], v[222:225], v[36:39]
	v_mfma_f32_16x16x32_bf16 v[20:23], v[180:183], v[230:233], v[20:23]
	v_mfma_f32_16x16x32_bf16 v[12:15], v[188:191], v[230:233], v[12:15]
	v_mfma_f32_16x16x32_bf16 v[0:3], v[188:191], v[238:241], v[0:3]
	v_mfma_f32_16x16x32_bf16 v[4:7], v[180:183], v[238:241], v[4:7]
	v_mfma_f32_16x16x32_bf16 v[52:55], v[184:187], v[218:221], v[52:55]
	v_mfma_f32_16x16x32_bf16 v[44:47], v[210:213], v[218:221], v[44:47]
	v_mfma_f32_16x16x32_bf16 v[28:31], v[210:213], v[226:229], v[28:31]
	v_mfma_f32_16x16x32_bf16 v[36:39], v[184:187], v[226:229], v[36:39]
	v_mfma_f32_16x16x32_bf16 v[20:23], v[184:187], v[234:237], v[20:23]
	v_mfma_f32_16x16x32_bf16 v[12:15], v[210:213], v[234:237], v[12:15]
	v_mfma_f32_16x16x32_bf16 v[0:3], v[210:213], v[242:245], v[0:3]
	v_mfma_f32_16x16x32_bf16 v[4:7], v[184:187], v[242:245], v[4:7]
	s_setprio 0
	s_barrier
	s_add_i32 s52, s52, 2
	s_add_u32 s0, s0, 0x100
	s_addc_u32 s1, s1, 0
	s_add_u32 s50, s50, 0x100
	s_addc_u32 s51, s51, 0
	s_cmp_gt_u32 s52, 13
; #define PG8_STAGE(bufoff, gbase, voff) do { _Pragma("unroll") for (int _i = 0; _i < 2; ++_i) \
;         __builtin_amdgcn_global_load_lds((const unsigned*)((const char*)(gbase) + (voff)[_i]), (PG8_LAS unsigned*)(lds + (bufoff) + ldsw + _i * 8192), 16, 0, 0); } while (0)
; #define PG8_LDA(dst, b, h) do { _Pragma("unroll") for (int m = 0; m < 4; ++m) _Pragma("unroll") for (int k = 0; k < 2; ++k) dst[m][k] = *(const PG8_LAS bf16x8*)(lds + PG8_SA(b, h) + aoff + m * 2048 + k * 1024); } while (0)
; #define PG8_LDB(dst, b, h) do { _Pragma("unroll") for (int n = 0; n < 2; ++n) _Pragma("unroll") for (int k = 0; k < 2; ++k) dst[n][k] = *(const PG8_LAS bf16x8*)(lds + PG8_SB(b, h) + boff + n * 2048 + k * 1024); } while (0)
; #define PG8_MMA(ai, bj, At, Bt) do { __builtin_amdgcn_s_setprio(1); _Pragma("unroll") for (int m = 0; m < 4; ++m) _Pragma("unroll") for (int n = 0; n < 2; ++n) _Pragma("unroll") for (int k = 0; k < 2; ++k) \
;         acc[ai][bj][m][n] = __builtin_amdgcn_mfma_f32_16x16x32_bf16(Bt[n][k], At[m][k], acc[ai][bj][m][n], 0, 0, 0); __builtin_amdgcn_s_setprio(0); } while (0)
; #define PG8_WAIT_V(n) asm volatile("s_waitcnt vmcnt(" #n ")" ::: "memory")
; #define PG8_BAR __builtin_amdgcn_s_barrier()
; template <class Epi, class Sched, bool ALIGN_EPI = false, bool SP2 = false>
; __device__ __forceinline__ void gemm_phase(PG8_LAS unsigned char* lds, const Gemm g, const Sched& S, const Epi& E) {
;     ...
;         for (int t = 0; t < nt; t += 2) {
;             const bool last = (t == nt - 2);
;             const char* a1 = cA + (size_t)(t + 1) * kstep;
;             const char* a2 = last ? nA : cA + (size_t)(t + 2) * kstep; const char* b2 = last ? nB : cB + (size_t)(t + 2) * kstep;
;             const char* a3 = a2 + kstep; const char* b3 = b2 + kstep;
;             if (last && has_next) S.a_ready(nxt);
;             if constexpr (SP2) {
;             PG8_LDB(B0, 0, 0); PG8_LDB(B1, 0, 1); PG8_SCHED; PG8_LDA(At, 0, 0); PG8_STAGE(PG8_SA(1, 1), a1 + hstep, voffA);
;             PG8_WAIT_V(8); PG8_WAIT_L(0); PG8_BAR; PG8_MMA(0, 0, At, B0); PG8_MMA(0, 1, At, B1); PG8_BAR; PG8_SCHED;
;             PG8_LDA(At, 0, 1); PG8_STAGE(PG8_SB(0, 0), b2, voffB); PG8_STAGE(PG8_SB(0, 1), b2 + hstep, voffB); PG8_STAGE(PG8_SA(0, 0), a2, voffA);
;             PG8_WAIT_V(8); PG8_WAIT_L(0); PG8_BAR; PG8_MMA(1, 0, At, B0); PG8_MMA(1, 1, At, B1); PG8_BAR; PG8_SCHED;
.LBB0_792:
	s_waitcnt lgkmcnt(0)
	ds_read_b128 v[140:143], v254
	ds_read_b128 v[162:165], v254 offset:1024
	ds_read_b128 v[166:169], v254 offset:2048
	ds_read_b128 v[176:179], v254 offset:3072
	ds_read_b128 v[180:183], v254 offset:16384
	ds_read_b128 v[184:187], v254 offset:17408
	ds_read_b128 v[188:191], v254 offset:18432
	ds_read_b128 v[210:213], v254 offset:19456
	s_add_u32 s2, s0, 0xfffc0080
	s_addc_u32 s3, s1, -1
	s_cmp_eq_u32 s52, 12
	s_cselect_b32 s5, s17, s3
	s_cselect_b32 s4, s48, s2
	s_cselect_b32 s3, s15, s51
	s_cselect_b32 s2, s49, s50
	s_add_i32 m0, s6, 0xc000
	ds_read_b128 v[214:217], v173
	ds_read_b128 v[218:221], v173 offset:1024
	ds_read_b128 v[222:225], v173 offset:2048
	ds_read_b128 v[226:229], v173 offset:3072
	ds_read_b128 v[230:233], v173 offset:4096
	ds_read_b128 v[234:237], v173 offset:5120
	ds_read_b128 v[238:241], v173 offset:6144
	ds_read_b128 v[242:245], v173 offset:7168
	global_load_lds_dwordx4 v136, s[0:1]
	s_add_i32 m0, s6, 0xe000
	s_nop 0
	global_load_lds_dwordx4 v138, s[0:1]
	s_waitcnt vmcnt(8)
	s_waitcnt lgkmcnt(0)
	s_barrier
	s_setprio 1
	v_mfma_f32_16x16x32_bf16 v[124:127], v[140:143], v[214:217], v[124:127]
	v_mfma_f32_16x16x32_bf16 v[120:123], v[166:169], v[214:217], v[120:123]
	v_mfma_f32_16x16x32_bf16 v[104:107], v[166:169], v[222:225], v[104:107]
	v_mfma_f32_16x16x32_bf16 v[112:115], v[140:143], v[222:225], v[112:115]
	v_mfma_f32_16x16x32_bf16 v[96:99], v[140:143], v[230:233], v[96:99]
	v_mfma_f32_16x16x32_bf16 v[88:91], v[166:169], v[230:233], v[88:91]
	v_mfma_f32_16x16x32_bf16 v[72:75], v[166:169], v[238:241], v[72:75]
	v_mfma_f32_16x16x32_bf16 v[80:83], v[140:143], v[238:241], v[80:83]
	v_mfma_f32_16x16x32_bf16 v[124:127], v[162:165], v[218:221], v[124:127]
	v_mfma_f32_16x16x32_bf16 v[120:123], v[176:179], v[218:221], v[120:123]
	v_mfma_f32_16x16x32_bf16 v[104:107], v[176:179], v[226:229], v[104:107]
	v_mfma_f32_16x16x32_bf16 v[112:115], v[162:165], v[226:229], v[112:115]
	v_mfma_f32_16x16x32_bf16 v[96:99], v[162:165], v[234:237], v[96:99]
	v_mfma_f32_16x16x32_bf16 v[88:91], v[176:179], v[234:237], v[88:91]
	v_mfma_f32_16x16x32_bf16 v[72:75], v[176:179], v[242:245], v[72:75]
	v_mfma_f32_16x16x32_bf16 v[80:83], v[162:165], v[242:245], v[80:83]
	v_mfma_f32_16x16x32_bf16 v[116:119], v[180:183], v[214:217], v[116:119]
	v_mfma_f32_16x16x32_bf16 v[108:111], v[188:191], v[214:217], v[108:111]
	v_mfma_f32_16x16x32_bf16 v[92:95], v[188:191], v[222:225], v[92:95]
	v_mfma_f32_16x16x32_bf16 v[100:103], v[180:183], v[222:225], v[100:103]
	v_mfma_f32_16x16x32_bf16 v[84:87], v[180:183], v[230:233], v[84:87]
	v_mfma_f32_16x16x32_bf16 v[76:79], v[188:191], v[230:233], v[76:79]
	v_mfma_f32_16x16x32_bf16 v[64:67], v[188:191], v[238:241], v[64:67]
	v_mfma_f32_16x16x32_bf16 v[68:71], v[180:183], v[238:241], v[68:71]
	v_mfma_f32_16x16x32_bf16 v[116:119], v[184:187], v[218:221], v[116:119]
	v_mfma_f32_16x16x32_bf16 v[108:111], v[210:213], v[218:221], v[108:111]
	v_mfma_f32_16x16x32_bf16 v[92:95], v[210:213], v[226:229], v[92:95]
	v_mfma_f32_16x16x32_bf16 v[100:103], v[184:187], v[226:229], v[100:103]
	v_mfma_f32_16x16x32_bf16 v[84:87], v[184:187], v[234:237], v[84:87]
	v_mfma_f32_16x16x32_bf16 v[76:79], v[210:213], v[234:237], v[76:79]
	v_mfma_f32_16x16x32_bf16 v[64:67], v[210:213], v[242:245], v[64:67]
	v_mfma_f32_16x16x32_bf16 v[68:71], v[184:187], v[242:245], v[68:71]
	s_setprio 0
	s_barrier
	s_mov_b32 m0, s27
	s_add_u32 s54, s2, 0x40000
	s_addc_u32 s55, s3, 0
	ds_read_b128 v[214:217], v173 offset:16384
	ds_read_b128 v[218:221], v173 offset:17408
	ds_read_b128 v[222:225], v173 offset:18432
	ds_read_b128 v[226:229], v173 offset:19456
	ds_read_b128 v[230:233], v173 offset:20480
	ds_read_b128 v[234:237], v173 offset:21504
	ds_read_b128 v[238:241], v173 offset:22528
	ds_read_b128 v[242:245], v173 offset:23552
	global_load_lds_dwordx4 v132, s[2:3]
	s_mov_b32 m0, s28
	s_nop 0
	global_load_lds_dwordx4 v128, s[2:3]
	s_mov_b32 m0, s29
	s_nop 0
	global_load_lds_dwordx4 v132, s[54:55]
	s_mov_b32 m0, s30
	s_nop 0
	global_load_lds_dwordx4 v128, s[54:55]
	s_mov_b32 m0, s6
	s_nop 0
	global_load_lds_dwordx4 v134, s[4:5]
	s_mov_b32 m0, s31
	s_nop 0
	global_load_lds_dwordx4 v130, s[4:5]
	s_waitcnt vmcnt(8)
	s_waitcnt lgkmcnt(0)
	s_barrier
	s_setprio 1
	v_mfma_f32_16x16x32_bf16 v[60:63], v[140:143], v[214:217], v[60:63]
	v_mfma_f32_16x16x32_bf16 v[56:59], v[166:169], v[214:217], v[56:59]
	v_mfma_f32_16x16x32_bf16 v[40:43], v[166:169], v[222:225], v[40:43]
	v_mfma_f32_16x16x32_bf16 v[48:51], v[140:143], v[222:225], v[48:51]
	v_mfma_f32_16x16x32_bf16 v[32:35], v[140:143], v[230:233], v[32:35]
	v_mfma_f32_16x16x32_bf16 v[24:27], v[166:169], v[230:233], v[24:27]
	v_mfma_f32_16x16x32_bf16 v[8:11], v[166:169], v[238:241], v[8:11]
	v_mfma_f32_16x16x32_bf16 v[16:19], v[140:143], v[238:241], v[16:19]
	v_mfma_f32_16x16x32_bf16 v[60:63], v[162:165], v[218:221], v[60:63]
	v_mfma_f32_16x16x32_bf16 v[56:59], v[176:179], v[218:221], v[56:59]
	v_mfma_f32_16x16x32_bf16 v[40:43], v[176:179], v[226:229], v[40:43]
	v_mfma_f32_16x16x32_bf16 v[48:51], v[162:165], v[226:229], v[48:51]
	v_mfma_f32_16x16x32_bf16 v[32:35], v[162:165], v[234:237], v[32:35]
	v_mfma_f32_16x16x32_bf16 v[24:27], v[176:179], v[234:237], v[24:27]
	v_mfma_f32_16x16x32_bf16 v[8:11], v[176:179], v[242:245], v[8:11]
	v_mfma_f32_16x16x32_bf16 v[16:19], v[162:165], v[242:245], v[16:19]
	v_mfma_f32_16x16x32_bf16 v[52:55], v[180:183], v[214:217], v[52:55]
	v_mfma_f32_16x16x32_bf16 v[44:47], v[188:191], v[214:217], v[44:47]
	v_mfma_f32_16x16x32_bf16 v[28:31], v[188:191], v[222:225], v[28:31]
	v_mfma_f32_16x16x32_bf16 v[36:39], v[180:183], v[222:225], v[36:39]
	v_mfma_f32_16x16x32_bf16 v[20:23], v[180:183], v[230:233], v[20:23]
	v_mfma_f32_16x16x32_bf16 v[12:15], v[188:191], v[230:233], v[12:15]
	v_mfma_f32_16x16x32_bf16 v[0:3], v[188:191], v[238:241], v[0:3]
	v_mfma_f32_16x16x32_bf16 v[4:7], v[180:183], v[238:241], v[4:7]
	v_mfma_f32_16x16x32_bf16 v[52:55], v[184:187], v[218:221], v[52:55]
	v_mfma_f32_16x16x32_bf16 v[44:47], v[210:213], v[218:221], v[44:47]
	v_mfma_f32_16x16x32_bf16 v[28:31], v[210:213], v[226:229], v[28:31]
	v_mfma_f32_16x16x32_bf16 v[36:39], v[184:187], v[226:229], v[36:39]
	v_mfma_f32_16x16x32_bf16 v[20:23], v[184:187], v[234:237], v[20:23]
	v_mfma_f32_16x16x32_bf16 v[12:15], v[210:213], v[234:237], v[12:15]
	v_mfma_f32_16x16x32_bf16 v[0:3], v[210:213], v[242:245], v[0:3]
	v_mfma_f32_16x16x32_bf16 v[4:7], v[184:187], v[242:245], v[4:7]
	s_setprio 0
	s_barrier
; #define PG8_STAGE(bufoff, gbase, voff) do { _Pragma("unroll") for (int _i = 0; _i < 2; ++_i) \
;         __builtin_amdgcn_global_load_lds((const unsigned*)((const char*)(gbase) + (voff)[_i]), (PG8_LAS unsigned*)(lds + (bufoff) + ldsw + _i * 8192), 16, 0, 0); } while (0)
; #define PG8_LDA(dst, b, h) do { _Pragma("unroll") for (int m = 0; m < 4; ++m) _Pragma("unroll") for (int k = 0; k < 2; ++k) dst[m][k] = *(const PG8_LAS bf16x8*)(lds + PG8_SA(b, h) + aoff + m * 2048 + k * 1024); } while (0)
; #define PG8_LDB(dst, b, h) do { _Pragma("unroll") for (int n = 0; n < 2; ++n) _Pragma("unroll") for (int k = 0; k < 2; ++k) dst[n][k] = *(const PG8_LAS bf16x8*)(lds + PG8_SB(b, h) + boff + n * 2048 + k * 1024); } while (0)
; #define PG8_MMA(ai, bj, At, Bt) do { __builtin_amdgcn_s_setprio(1); _Pragma("unroll") for (int m = 0; m < 4; ++m) _Pragma("unroll") for (int n = 0; n < 2; ++n) _Pragma("unroll") for (int k = 0; k < 2; ++k) \
;         acc[ai][bj][m][n] = __builtin_amdgcn_mfma_f32_16x16x32_bf16(Bt[n][k], At[m][k], acc[ai][bj][m][n], 0, 0, 0); __builtin_amdgcn_s_setprio(0); } while (0)
; #define PG8_WAIT_V(n) asm volatile("s_waitcnt vmcnt(" #n ")" ::: "memory")
; #define PG8_WAIT_L(n) asm volatile("s_waitcnt lgkmcnt(" #n ")" ::: "memory")
; #define PG8_BAR __builtin_amdgcn_s_barrier()
; #define PG8_SCHED __builtin_amdgcn_sched_barrier(0)
; template <class Epi, class Sched, bool ALIGN_EPI = false, bool SP2 = false>
; __device__ __forceinline__ void gemm_phase(PG8_LAS unsigned char* lds, const Gemm g, const Sched& S, const Epi& E) {
;     ...
;             PG8_LDB(B0, 1, 0); PG8_LDB(B1, 1, 1); PG8_SCHED; PG8_LDA(At, 1, 0); PG8_STAGE(PG8_SA(0, 1), a2 + hstep, voffA);
;             PG8_WAIT_V(8); PG8_WAIT_L(0); PG8_BAR; PG8_MMA(0, 0, At, B0); PG8_MMA(0, 1, At, B1); PG8_BAR; PG8_SCHED;
;             PG8_LDA(At, 1, 1); PG8_STAGE(PG8_SB(1, 0), b3, voffB); PG8_STAGE(PG8_SB(1, 1), b3 + hstep, voffB); PG8_STAGE(PG8_SA(1, 0), a3, voffA);
;             PG8_WAIT_V(8); PG8_WAIT_L(0); PG8_BAR; PG8_MMA(1, 0, At, B0); PG8_MMA(1, 1, At, B1); PG8_BAR; PG8_SCHED;
	ds_read_b128 v[140:143], v254 offset:32768
	ds_read_b128 v[162:165], v254 offset:33792
	ds_read_b128 v[166:169], v254 offset:34816
	ds_read_b128 v[176:179], v254 offset:35840
	ds_read_b128 v[180:183], v254 offset:49152
	ds_read_b128 v[184:187], v254 offset:50176
	ds_read_b128 v[188:191], v254 offset:51200
	ds_read_b128 v[210:213], v254 offset:52224
	s_add_u32 s4, s4, 0x40000
	s_addc_u32 s5, s5, 0
	s_mov_b32 m0, s33
	ds_read_b128 v[214:217], v173 offset:32768
	ds_read_b128 v[218:221], v173 offset:33792
	ds_read_b128 v[222:225], v173 offset:34816
	ds_read_b128 v[226:229], v173 offset:35840
	ds_read_b128 v[230:233], v173 offset:36864
	ds_read_b128 v[234:237], v173 offset:37888
	ds_read_b128 v[238:241], v173 offset:38912
	ds_read_b128 v[242:245], v173 offset:39936
	global_load_lds_dwordx4 v134, s[4:5]
	s_mov_b32 m0, s34
	s_nop 0
	global_load_lds_dwordx4 v130, s[4:5]
	s_waitcnt vmcnt(8)
	s_waitcnt lgkmcnt(0)
	s_barrier
	s_setprio 1
	v_mfma_f32_16x16x32_bf16 v[124:127], v[140:143], v[214:217], v[124:127]
	v_mfma_f32_16x16x32_bf16 v[120:123], v[166:169], v[214:217], v[120:123]
	v_mfma_f32_16x16x32_bf16 v[104:107], v[166:169], v[222:225], v[104:107]
	v_mfma_f32_16x16x32_bf16 v[112:115], v[140:143], v[222:225], v[112:115]
	v_mfma_f32_16x16x32_bf16 v[96:99], v[140:143], v[230:233], v[96:99]
	v_mfma_f32_16x16x32_bf16 v[88:91], v[166:169], v[230:233], v[88:91]
	v_mfma_f32_16x16x32_bf16 v[72:75], v[166:169], v[238:241], v[72:75]
	v_mfma_f32_16x16x32_bf16 v[80:83], v[140:143], v[238:241], v[80:83]
	v_mfma_f32_16x16x32_bf16 v[124:127], v[162:165], v[218:221], v[124:127]
	v_mfma_f32_16x16x32_bf16 v[120:123], v[176:179], v[218:221], v[120:123]
	v_mfma_f32_16x16x32_bf16 v[104:107], v[176:179], v[226:229], v[104:107]
	v_mfma_f32_16x16x32_bf16 v[112:115], v[162:165], v[226:229], v[112:115]
	v_mfma_f32_16x16x32_bf16 v[96:99], v[162:165], v[234:237], v[96:99]
	v_mfma_f32_16x16x32_bf16 v[88:91], v[176:179], v[234:237], v[88:91]
	v_mfma_f32_16x16x32_bf16 v[72:75], v[176:179], v[242:245], v[72:75]
	v_mfma_f32_16x16x32_bf16 v[80:83], v[162:165], v[242:245], v[80:83]
	v_mfma_f32_16x16x32_bf16 v[116:119], v[180:183], v[214:217], v[116:119]
	v_mfma_f32_16x16x32_bf16 v[108:111], v[188:191], v[214:217], v[108:111]
	v_mfma_f32_16x16x32_bf16 v[92:95], v[188:191], v[222:225], v[92:95]
	v_mfma_f32_16x16x32_bf16 v[100:103], v[180:183], v[222:225], v[100:103]
	v_mfma_f32_16x16x32_bf16 v[84:87], v[180:183], v[230:233], v[84:87]
	v_mfma_f32_16x16x32_bf16 v[76:79], v[188:191], v[230:233], v[76:79]
	v_mfma_f32_16x16x32_bf16 v[64:67], v[188:191], v[238:241], v[64:67]
	v_mfma_f32_16x16x32_bf16 v[68:71], v[180:183], v[238:241], v[68:71]
	v_mfma_f32_16x16x32_bf16 v[116:119], v[184:187], v[218:221], v[116:119]
	v_mfma_f32_16x16x32_bf16 v[108:111], v[210:213], v[218:221], v[108:111]
	v_mfma_f32_16x16x32_bf16 v[92:95], v[210:213], v[226:229], v[92:95]
	v_mfma_f32_16x16x32_bf16 v[100:103], v[184:187], v[226:229], v[100:103]
	v_mfma_f32_16x16x32_bf16 v[84:87], v[184:187], v[234:237], v[84:87]
	v_mfma_f32_16x16x32_bf16 v[76:79], v[210:213], v[234:237], v[76:79]
	v_mfma_f32_16x16x32_bf16 v[64:67], v[210:213], v[242:245], v[64:67]
	v_mfma_f32_16x16x32_bf16 v[68:71], v[184:187], v[242:245], v[68:71]
	s_setprio 0
	s_barrier
	s_mov_b32 m0, s37
	s_add_u32 s2, s2, 0x40080
	s_addc_u32 s3, s3, 0
	ds_read_b128 v[214:217], v173 offset:49152
	ds_read_b128 v[218:221], v173 offset:50176
	ds_read_b128 v[222:225], v173 offset:51200
	ds_read_b128 v[226:229], v173 offset:52224
	ds_read_b128 v[230:233], v173 offset:53248
	ds_read_b128 v[234:237], v173 offset:54272
	ds_read_b128 v[238:241], v173 offset:55296
	ds_read_b128 v[242:245], v173 offset:56320
	s_add_u32 s98, s2, 0xfffc0000
	s_addc_u32 s99, s3, -1
	global_load_lds_dwordx4 v132, s[98:99]
	s_mov_b32 m0, s38
	s_nop 0
	global_load_lds_dwordx4 v128, s[98:99]
	s_mov_b32 m0, s41
	s_nop 0
	global_load_lds_dwordx4 v132, s[2:3]
	s_mov_b32 m0, s42
	s_nop 0
	global_load_lds_dwordx4 v128, s[2:3]
	s_mov_b32 m0, s39
	s_nop 0
	s_add_u32 s100, s4, 0xfffc0080
	s_addc_u32 s101, s5, -1
	global_load_lds_dwordx4 v134, s[100:101]
	s_mov_b32 m0, s40
	s_nop 0
	global_load_lds_dwordx4 v130, s[100:101]
	s_waitcnt vmcnt(8)
	s_waitcnt lgkmcnt(0)
	s_barrier
	s_setprio 1
	v_mfma_f32_16x16x32_bf16 v[60:63], v[140:143], v[214:217], v[60:63]
	v_mfma_f32_16x16x32_bf16 v[56:59], v[166:169], v[214:217], v[56:59]
	v_mfma_f32_16x16x32_bf16 v[40:43], v[166:169], v[222:225], v[40:43]
	v_mfma_f32_16x16x32_bf16 v[48:51], v[140:143], v[222:225], v[48:51]
	v_mfma_f32_16x16x32_bf16 v[32:35], v[140:143], v[230:233], v[32:35]
	v_mfma_f32_16x16x32_bf16 v[24:27], v[166:169], v[230:233], v[24:27]
	v_mfma_f32_16x16x32_bf16 v[8:11], v[166:169], v[238:241], v[8:11]
	v_mfma_f32_16x16x32_bf16 v[16:19], v[140:143], v[238:241], v[16:19]
	v_mfma_f32_16x16x32_bf16 v[60:63], v[162:165], v[218:221], v[60:63]
	v_mfma_f32_16x16x32_bf16 v[56:59], v[176:179], v[218:221], v[56:59]
	v_mfma_f32_16x16x32_bf16 v[40:43], v[176:179], v[226:229], v[40:43]
	v_mfma_f32_16x16x32_bf16 v[48:51], v[162:165], v[226:229], v[48:51]
	v_mfma_f32_16x16x32_bf16 v[32:35], v[162:165], v[234:237], v[32:35]
	v_mfma_f32_16x16x32_bf16 v[24:27], v[176:179], v[234:237], v[24:27]
	v_mfma_f32_16x16x32_bf16 v[8:11], v[176:179], v[242:245], v[8:11]
	v_mfma_f32_16x16x32_bf16 v[16:19], v[162:165], v[242:245], v[16:19]
	v_mfma_f32_16x16x32_bf16 v[52:55], v[180:183], v[214:217], v[52:55]
	v_mfma_f32_16x16x32_bf16 v[44:47], v[188:191], v[214:217], v[44:47]
	v_mfma_f32_16x16x32_bf16 v[28:31], v[188:191], v[222:225], v[28:31]
	v_mfma_f32_16x16x32_bf16 v[36:39], v[180:183], v[222:225], v[36:39]
	v_mfma_f32_16x16x32_bf16 v[20:23], v[180:183], v[230:233], v[20:23]
	v_mfma_f32_16x16x32_bf16 v[12:15], v[188:191], v[230:233], v[12:15]
	v_mfma_f32_16x16x32_bf16 v[0:3], v[188:191], v[238:241], v[0:3]
	v_mfma_f32_16x16x32_bf16 v[4:7], v[180:183], v[238:241], v[4:7]
	v_mfma_f32_16x16x32_bf16 v[52:55], v[184:187], v[218:221], v[52:55]
	v_mfma_f32_16x16x32_bf16 v[44:47], v[210:213], v[218:221], v[44:47]
	v_mfma_f32_16x16x32_bf16 v[28:31], v[210:213], v[226:229], v[28:31]
	v_mfma_f32_16x16x32_bf16 v[36:39], v[184:187], v[226:229], v[36:39]
	v_mfma_f32_16x16x32_bf16 v[20:23], v[184:187], v[234:237], v[20:23]
	v_mfma_f32_16x16x32_bf16 v[12:15], v[210:213], v[234:237], v[12:15]
	v_mfma_f32_16x16x32_bf16 v[0:3], v[210:213], v[242:245], v[0:3]
	v_mfma_f32_16x16x32_bf16 v[4:7], v[184:187], v[242:245], v[4:7]
	s_setprio 0
	s_barrier
	s_add_i32 s52, s52, 2
	s_add_u32 s0, s0, 0x100
	s_addc_u32 s1, s1, 0
	s_add_u32 s50, s50, 0x100
	s_addc_u32 s51, s51, 0
	s_cmp_gt_u32 s52, 13
	s_cbranch_scc0 .LBB0_792
	s_and_b64 vcc, exec, s[12:13]
	s_cbranch_vccz .LBB0_795
	s_barrier

; #define PG8_STAGE(bufoff, gbase, voff) do { _Pragma("unroll") for (int _i = 0; _i < 2; ++_i) \
;         __builtin_amdgcn_global_load_lds((const unsigned*)((const char*)(gbase) + (voff)[_i]), (PG8_LAS unsigned*)(lds + (bufoff) + ldsw + _i * 8192), 16, 0, 0); } while (0)
; #define PG8_LDA(dst, b, h) do { _Pragma("unroll") for (int m = 0; m < 4; ++m) _Pragma("unroll") for (int k = 0; k < 2; ++k) dst[m][k] = *(const PG8_LAS bf16x8*)(lds + PG8_SA(b, h) + aoff + m * 2048 + k * 1024); } while (0)
; #define PG8_LDB(dst, b, h) do { _Pragma("unroll") for (int n = 0; n < 2; ++n) _Pragma("unroll") for (int k = 0; k < 2; ++k) dst[n][k] = *(const PG8_LAS bf16x8*)(lds + PG8_SB(b, h) + boff + n * 2048 + k * 1024); } while (0)
; #define PG8_MMA(ai, bj, At, Bt) do { __builtin_amdgcn_s_setprio(1); _Pragma("unroll") for (int m = 0; m < 4; ++m) _Pragma("unroll") for (int n = 0; n < 2; ++n) _Pragma("unroll") for (int k = 0; k < 2; ++k) \
;         acc[ai][bj][m][n] = __builtin_amdgcn_mfma_f32_16x16x32_bf16(Bt[n][k], At[m][k], acc[ai][bj][m][n], 0, 0, 0); __builtin_amdgcn_s_setprio(0); } while (0)
; #define PG8_WAIT_V(n) asm volatile("s_waitcnt vmcnt(" #n ")" ::: "memory")
; #define PG8_BAR __builtin_amdgcn_s_barrier()
; template <class Epi, class Sched, bool ALIGN_EPI = false, bool SP2 = false>
; __device__ __forceinline__ void gemm_phase(PG8_LAS unsigned char* lds, const Gemm g, const Sched& S, const Epi& E) {
;     ...
;         for (int t = 0; t < nt; t += 2) {
;             const bool last = (t == nt - 2);
;             const char* a1 = cA + (size_t)(t + 1) * kstep;
;             const char* a2 = last ? nA : cA + (size_t)(t + 2) * kstep; const char* b2 = last ? nB : cB + (size_t)(t + 2) * kstep;
;             const char* a3 = a2 + kstep; const char* b3 = b2 + kstep;
;             if (last && has_next) S.a_ready(nxt);
;             if constexpr (SP2) {
;             PG8_LDB(B0, 0, 0); PG8_LDB(B1, 0, 1); PG8_SCHED; PG8_LDA(At, 0, 0); PG8_STAGE(PG8_SA(1, 1), a1 + hstep, voffA);
;             PG8_WAIT_V(8); PG8_WAIT_L(0); PG8_BAR; PG8_MMA(0, 0, At, B0); PG8_MMA(0, 1, At, B1); PG8_BAR; PG8_SCHED;
;             PG8_LDA(At, 0, 1); PG8_STAGE(PG8_SB(0, 0), b2, voffB); PG8_STAGE(PG8_SB(0, 1), b2 + hstep, voffB); PG8_STAGE(PG8_SA(0, 0), a2, voffA);
;             PG8_WAIT_V(8); PG8_WAIT_L(0); PG8_BAR; PG8_MMA(1, 0, At, B0); PG8_MMA(1, 1, At, B1); PG8_BAR; PG8_SCHED;
.Lsgo_peel:
	ds_read_b128 v[140:143], v254
	ds_read_b128 v[166:169], v254 offset:1024
	ds_read_b128 v[170:173], v254 offset:2048
	ds_read_b128 v[174:177], v254 offset:3072
	ds_read_b128 v[178:181], v254 offset:16384
	ds_read_b128 v[182:185], v254 offset:17408
	ds_read_b128 v[186:189], v254 offset:18432
	ds_read_b128 v[210:213], v254 offset:19456
	s_add_u32 s2, s0, 0xfffc0080
	s_addc_u32 s3, s1, -1
	s_cmp_eq_u32 s55, 12
	s_cselect_b32 s5, s23, s3
	s_cselect_b32 s4, s51, s2
	s_cselect_b32 s3, s21, s54
	s_cselect_b32 s2, s52, s53
	s_add_i32 m0, s31, 0xc000
	ds_read_b128 v[214:217], v163
	ds_read_b128 v[218:221], v163 offset:1024
	ds_read_b128 v[222:225], v163 offset:2048
	ds_read_b128 v[226:229], v163 offset:3072
	ds_read_b128 v[230:233], v163 offset:4096
	ds_read_b128 v[234:237], v163 offset:5120
	ds_read_b128 v[238:241], v163 offset:6144
	ds_read_b128 v[242:245], v163 offset:7168
	global_load_lds_dwordx4 v136, s[0:1]
	s_add_i32 m0, s31, 0xe000
	s_nop 0
	global_load_lds_dwordx4 v138, s[0:1]
	s_waitcnt vmcnt(8)
	s_waitcnt lgkmcnt(0)
	s_barrier
	s_setprio 1
	v_mfma_f32_16x16x32_bf16 v[124:127], v[140:143], v[214:217], 0
	v_mfma_f32_16x16x32_bf16 v[120:123], v[170:173], v[214:217], 0
	v_mfma_f32_16x16x32_bf16 v[104:107], v[170:173], v[222:225], 0
	v_mfma_f32_16x16x32_bf16 v[108:111], v[140:143], v[222:225], 0
	v_mfma_f32_16x16x32_bf16 v[92:95], v[140:143], v[230:233], 0
	v_mfma_f32_16x16x32_bf16 v[88:91], v[170:173], v[230:233], 0
	v_mfma_f32_16x16x32_bf16 v[72:75], v[170:173], v[238:241], 0
	v_mfma_f32_16x16x32_bf16 v[76:79], v[140:143], v[238:241], 0
	v_mfma_f32_16x16x32_bf16 v[124:127], v[166:169], v[218:221], v[124:127]
	v_mfma_f32_16x16x32_bf16 v[120:123], v[174:177], v[218:221], v[120:123]
	v_mfma_f32_16x16x32_bf16 v[104:107], v[174:177], v[226:229], v[104:107]
	v_mfma_f32_16x16x32_bf16 v[108:111], v[166:169], v[226:229], v[108:111]
	v_mfma_f32_16x16x32_bf16 v[92:95], v[166:169], v[234:237], v[92:95]
	v_mfma_f32_16x16x32_bf16 v[88:91], v[174:177], v[234:237], v[88:91]
	v_mfma_f32_16x16x32_bf16 v[72:75], v[174:177], v[242:245], v[72:75]
	v_mfma_f32_16x16x32_bf16 v[76:79], v[166:169], v[242:245], v[76:79]
	v_mfma_f32_16x16x32_bf16 v[116:119], v[178:181], v[214:217], 0
	v_mfma_f32_16x16x32_bf16 v[112:115], v[186:189], v[214:217], 0
	v_mfma_f32_16x16x32_bf16 v[96:99], v[186:189], v[222:225], 0
	v_mfma_f32_16x16x32_bf16 v[100:103], v[178:181], v[222:225], 0
	v_mfma_f32_16x16x32_bf16 v[84:87], v[178:181], v[230:233], 0
	v_mfma_f32_16x16x32_bf16 v[80:83], v[186:189], v[230:233], 0
	v_mfma_f32_16x16x32_bf16 v[64:67], v[186:189], v[238:241], 0
	v_mfma_f32_16x16x32_bf16 v[68:71], v[178:181], v[238:241], 0
	v_mfma_f32_16x16x32_bf16 v[116:119], v[182:185], v[218:221], v[116:119]
	v_mfma_f32_16x16x32_bf16 v[112:115], v[210:213], v[218:221], v[112:115]
	v_mfma_f32_16x16x32_bf16 v[96:99], v[210:213], v[226:229], v[96:99]
	v_mfma_f32_16x16x32_bf16 v[100:103], v[182:185], v[226:229], v[100:103]
	v_mfma_f32_16x16x32_bf16 v[84:87], v[182:185], v[234:237], v[84:87]
	v_mfma_f32_16x16x32_bf16 v[80:83], v[210:213], v[234:237], v[80:83]
	v_mfma_f32_16x16x32_bf16 v[64:67], v[210:213], v[242:245], v[64:67]
	v_mfma_f32_16x16x32_bf16 v[68:71], v[182:185], v[242:245], v[68:71]
	s_setprio 0
	s_barrier
	s_mov_b32 m0, s33
	s_add_u32 s56, s2, 0x40000
	s_addc_u32 s57, s3, 0
	ds_read_b128 v[214:217], v163 offset:16384
	ds_read_b128 v[218:221], v163 offset:17408
	ds_read_b128 v[222:225], v163 offset:18432
	ds_read_b128 v[226:229], v163 offset:19456
	ds_read_b128 v[230:233], v163 offset:20480
	ds_read_b128 v[234:237], v163 offset:21504
	ds_read_b128 v[238:241], v163 offset:22528
	ds_read_b128 v[242:245], v163 offset:23552
	global_load_lds_dwordx4 v132, s[2:3]
	s_mov_b32 m0, s34
	s_nop 0
	global_load_lds_dwordx4 v128, s[2:3]
	s_mov_b32 m0, s35
	s_nop 0
	global_load_lds_dwordx4 v132, s[56:57]
	s_mov_b32 m0, s36
	s_nop 0
	global_load_lds_dwordx4 v128, s[56:57]
	s_mov_b32 m0, s31
	s_nop 0
	global_load_lds_dwordx4 v134, s[4:5]
	s_mov_b32 m0, s37
	s_nop 0
	global_load_lds_dwordx4 v130, s[4:5]
	s_waitcnt vmcnt(8)
	s_waitcnt lgkmcnt(0)
	s_barrier
	s_setprio 1
	v_mfma_f32_16x16x32_bf16 v[60:63], v[140:143], v[214:217], 0
	v_mfma_f32_16x16x32_bf16 v[56:59], v[170:173], v[214:217], 0
	v_mfma_f32_16x16x32_bf16 v[40:43], v[170:173], v[222:225], 0
	v_mfma_f32_16x16x32_bf16 v[44:47], v[140:143], v[222:225], 0
	v_mfma_f32_16x16x32_bf16 v[28:31], v[140:143], v[230:233], 0
	v_mfma_f32_16x16x32_bf16 v[24:27], v[170:173], v[230:233], 0
	v_mfma_f32_16x16x32_bf16 v[8:11], v[170:173], v[238:241], 0
	v_mfma_f32_16x16x32_bf16 v[12:15], v[140:143], v[238:241], 0
	v_mfma_f32_16x16x32_bf16 v[60:63], v[166:169], v[218:221], v[60:63]
	v_mfma_f32_16x16x32_bf16 v[56:59], v[174:177], v[218:221], v[56:59]
	v_mfma_f32_16x16x32_bf16 v[40:43], v[174:177], v[226:229], v[40:43]
	v_mfma_f32_16x16x32_bf16 v[44:47], v[166:169], v[226:229], v[44:47]
	v_mfma_f32_16x16x32_bf16 v[28:31], v[166:169], v[234:237], v[28:31]
	v_mfma_f32_16x16x32_bf16 v[24:27], v[174:177], v[234:237], v[24:27]
	v_mfma_f32_16x16x32_bf16 v[8:11], v[174:177], v[242:245], v[8:11]
	v_mfma_f32_16x16x32_bf16 v[12:15], v[166:169], v[242:245], v[12:15]
	v_mfma_f32_16x16x32_bf16 v[52:55], v[178:181], v[214:217], 0
	v_mfma_f32_16x16x32_bf16 v[48:51], v[186:189], v[214:217], 0
	v_mfma_f32_16x16x32_bf16 v[32:35], v[186:189], v[222:225], 0
	v_mfma_f32_16x16x32_bf16 v[36:39], v[178:181], v[222:225], 0
	v_mfma_f32_16x16x32_bf16 v[20:23], v[178:181], v[230:233], 0
	v_mfma_f32_16x16x32_bf16 v[16:19], v[186:189], v[230:233], 0
	v_mfma_f32_16x16x32_bf16 v[0:3], v[186:189], v[238:241], 0
	v_mfma_f32_16x16x32_bf16 v[4:7], v[178:181], v[238:241], 0
	v_mfma_f32_16x16x32_bf16 v[52:55], v[182:185], v[218:221], v[52:55]
	v_mfma_f32_16x16x32_bf16 v[48:51], v[210:213], v[218:221], v[48:51]
	v_mfma_f32_16x16x32_bf16 v[32:35], v[210:213], v[226:229], v[32:35]
	v_mfma_f32_16x16x32_bf16 v[36:39], v[182:185], v[226:229], v[36:39]
	v_mfma_f32_16x16x32_bf16 v[20:23], v[182:185], v[234:237], v[20:23]
	v_mfma_f32_16x16x32_bf16 v[16:19], v[210:213], v[234:237], v[16:19]
	v_mfma_f32_16x16x32_bf16 v[0:3], v[210:213], v[242:245], v[0:3]
	v_mfma_f32_16x16x32_bf16 v[4:7], v[182:185], v[242:245], v[4:7]
	s_setprio 0
	s_barrier
; #define PG8_STAGE(bufoff, gbase, voff) do { _Pragma("unroll") for (int _i = 0; _i < 2; ++_i) \
;         __builtin_amdgcn_global_load_lds((const unsigned*)((const char*)(gbase) + (voff)[_i]), (PG8_LAS unsigned*)(lds + (bufoff) + ldsw + _i * 8192), 16, 0, 0); } while (0)
; #define PG8_LDA(dst, b, h) do { _Pragma("unroll") for (int m = 0; m < 4; ++m) _Pragma("unroll") for (int k = 0; k < 2; ++k) dst[m][k] = *(const PG8_LAS bf16x8*)(lds + PG8_SA(b, h) + aoff + m * 2048 + k * 1024); } while (0)
; #define PG8_LDB(dst, b, h) do { _Pragma("unroll") for (int n = 0; n < 2; ++n) _Pragma("unroll") for (int k = 0; k < 2; ++k) dst[n][k] = *(const PG8_LAS bf16x8*)(lds + PG8_SB(b, h) + boff + n * 2048 + k * 1024); } while (0)
; #define PG8_MMA(ai, bj, At, Bt) do { __builtin_amdgcn_s_setprio(1); _Pragma("unroll") for (int m = 0; m < 4; ++m) _Pragma("unroll") for (int n = 0; n < 2; ++n) _Pragma("unroll") for (int k = 0; k < 2; ++k) \
;         acc[ai][bj][m][n] = __builtin_amdgcn_mfma_f32_16x16x32_bf16(Bt[n][k], At[m][k], acc[ai][bj][m][n], 0, 0, 0); __builtin_amdgcn_s_setprio(0); } while (0)
; #define PG8_WAIT_V(n) asm volatile("s_waitcnt vmcnt(" #n ")" ::: "memory")
; #define PG8_WAIT_L(n) asm volatile("s_waitcnt lgkmcnt(" #n ")" ::: "memory")
; #define PG8_BAR __builtin_amdgcn_s_barrier()
; #define PG8_SCHED __builtin_amdgcn_sched_barrier(0)
; template <class Epi, class Sched, bool ALIGN_EPI = false, bool SP2 = false>
; __device__ __forceinline__ void gemm_phase(PG8_LAS unsigned char* lds, const Gemm g, const Sched& S, const Epi& E) {
;     ...
;             PG8_LDB(B0, 1, 0); PG8_LDB(B1, 1, 1); PG8_SCHED; PG8_LDA(At, 1, 0); PG8_STAGE(PG8_SA(0, 1), a2 + hstep, voffA);
;             PG8_WAIT_V(8); PG8_WAIT_L(0); PG8_BAR; PG8_MMA(0, 0, At, B0); PG8_MMA(0, 1, At, B1); PG8_BAR; PG8_SCHED;
;             PG8_LDA(At, 1, 1); PG8_STAGE(PG8_SB(1, 0), b3, voffB); PG8_STAGE(PG8_SB(1, 1), b3 + hstep, voffB); PG8_STAGE(PG8_SA(1, 0), a3, voffA);
;             PG8_WAIT_V(8); PG8_WAIT_L(0); PG8_BAR; PG8_MMA(1, 0, At, B0); PG8_MMA(1, 1, At, B1); PG8_BAR; PG8_SCHED;
	ds_read_b128 v[140:143], v254 offset:32768
	ds_read_b128 v[166:169], v254 offset:33792
	ds_read_b128 v[170:173], v254 offset:34816
	ds_read_b128 v[174:177], v254 offset:35840
	ds_read_b128 v[178:181], v254 offset:49152
	ds_read_b128 v[182:185], v254 offset:50176
	ds_read_b128 v[186:189], v254 offset:51200
	ds_read_b128 v[210:213], v254 offset:52224
	s_add_u32 s4, s4, 0x40000
	s_addc_u32 s5, s5, 0
	s_mov_b32 m0, s38
	ds_read_b128 v[214:217], v163 offset:32768
	ds_read_b128 v[218:221], v163 offset:33792
	ds_read_b128 v[222:225], v163 offset:34816
	ds_read_b128 v[226:229], v163 offset:35840
	ds_read_b128 v[230:233], v163 offset:36864
	ds_read_b128 v[234:237], v163 offset:37888
	ds_read_b128 v[238:241], v163 offset:38912
	ds_read_b128 v[242:245], v163 offset:39936
	global_load_lds_dwordx4 v134, s[4:5]
	s_mov_b32 m0, s39
	s_nop 0
	global_load_lds_dwordx4 v130, s[4:5]
	s_waitcnt vmcnt(8)
	s_waitcnt lgkmcnt(0)
	s_barrier
	s_setprio 1
	v_mfma_f32_16x16x32_bf16 v[124:127], v[140:143], v[214:217], v[124:127]
	v_mfma_f32_16x16x32_bf16 v[120:123], v[170:173], v[214:217], v[120:123]
	v_mfma_f32_16x16x32_bf16 v[104:107], v[170:173], v[222:225], v[104:107]
	v_mfma_f32_16x16x32_bf16 v[108:111], v[140:143], v[222:225], v[108:111]
	v_mfma_f32_16x16x32_bf16 v[92:95], v[140:143], v[230:233], v[92:95]
	v_mfma_f32_16x16x32_bf16 v[88:91], v[170:173], v[230:233], v[88:91]
	v_mfma_f32_16x16x32_bf16 v[72:75], v[170:173], v[238:241], v[72:75]
	v_mfma_f32_16x16x32_bf16 v[76:79], v[140:143], v[238:241], v[76:79]
	v_mfma_f32_16x16x32_bf16 v[124:127], v[166:169], v[218:221], v[124:127]
	v_mfma_f32_16x16x32_bf16 v[120:123], v[174:177], v[218:221], v[120:123]
	v_mfma_f32_16x16x32_bf16 v[104:107], v[174:177], v[226:229], v[104:107]
	v_mfma_f32_16x16x32_bf16 v[108:111], v[166:169], v[226:229], v[108:111]
	v_mfma_f32_16x16x32_bf16 v[92:95], v[166:169], v[234:237], v[92:95]
	v_mfma_f32_16x16x32_bf16 v[88:91], v[174:177], v[234:237], v[88:91]
	v_mfma_f32_16x16x32_bf16 v[72:75], v[174:177], v[242:245], v[72:75]
	v_mfma_f32_16x16x32_bf16 v[76:79], v[166:169], v[242:245], v[76:79]
	v_mfma_f32_16x16x32_bf16 v[116:119], v[178:181], v[214:217], v[116:119]
	v_mfma_f32_16x16x32_bf16 v[112:115], v[186:189], v[214:217], v[112:115]
	v_mfma_f32_16x16x32_bf16 v[96:99], v[186:189], v[222:225], v[96:99]
	v_mfma_f32_16x16x32_bf16 v[100:103], v[178:181], v[222:225], v[100:103]
	v_mfma_f32_16x16x32_bf16 v[84:87], v[178:181], v[230:233], v[84:87]
	v_mfma_f32_16x16x32_bf16 v[80:83], v[186:189], v[230:233], v[80:83]
	v_mfma_f32_16x16x32_bf16 v[64:67], v[186:189], v[238:241], v[64:67]
	v_mfma_f32_16x16x32_bf16 v[68:71], v[178:181], v[238:241], v[68:71]
	v_mfma_f32_16x16x32_bf16 v[116:119], v[182:185], v[218:221], v[116:119]
	v_mfma_f32_16x16x32_bf16 v[112:115], v[210:213], v[218:221], v[112:115]
	v_mfma_f32_16x16x32_bf16 v[96:99], v[210:213], v[226:229], v[96:99]
	v_mfma_f32_16x16x32_bf16 v[100:103], v[182:185], v[226:229], v[100:103]
	v_mfma_f32_16x16x32_bf16 v[84:87], v[182:185], v[234:237], v[84:87]
	v_mfma_f32_16x16x32_bf16 v[80:83], v[210:213], v[234:237], v[80:83]
	v_mfma_f32_16x16x32_bf16 v[64:67], v[210:213], v[242:245], v[64:67]
	v_mfma_f32_16x16x32_bf16 v[68:71], v[182:185], v[242:245], v[68:71]
	s_setprio 0
	s_barrier
	s_mov_b32 m0, s43
	s_add_u32 s2, s2, 0x40080
	s_addc_u32 s3, s3, 0
	ds_read_b128 v[214:217], v163 offset:49152
	ds_read_b128 v[218:221], v163 offset:50176
	ds_read_b128 v[222:225], v163 offset:51200
	ds_read_b128 v[226:229], v163 offset:52224
	ds_read_b128 v[230:233], v163 offset:53248
	ds_read_b128 v[234:237], v163 offset:54272
	ds_read_b128 v[238:241], v163 offset:55296
	ds_read_b128 v[242:245], v163 offset:56320
	s_add_u32 s98, s2, 0xfffc0000
	s_addc_u32 s99, s3, -1
	global_load_lds_dwordx4 v132, s[98:99]
	s_mov_b32 m0, s44
	s_nop 0
	global_load_lds_dwordx4 v128, s[98:99]
	s_mov_b32 m0, s48
	s_nop 0
	global_load_lds_dwordx4 v132, s[2:3]
	s_mov_b32 m0, s49
	s_nop 0
	global_load_lds_dwordx4 v128, s[2:3]
	s_mov_b32 m0, s45
	s_nop 0
	s_add_u32 s100, s4, 0xfffc0080
	s_addc_u32 s101, s5, -1
	global_load_lds_dwordx4 v134, s[100:101]
	s_mov_b32 m0, s47
	s_nop 0
	global_load_lds_dwordx4 v130, s[100:101]
	s_waitcnt vmcnt(8)
	s_waitcnt lgkmcnt(0)
	s_barrier
	s_setprio 1
	v_mfma_f32_16x16x32_bf16 v[60:63], v[140:143], v[214:217], v[60:63]
	v_mfma_f32_16x16x32_bf16 v[56:59], v[170:173], v[214:217], v[56:59]
	v_mfma_f32_16x16x32_bf16 v[40:43], v[170:173], v[222:225], v[40:43]
	v_mfma_f32_16x16x32_bf16 v[44:47], v[140:143], v[222:225], v[44:47]
	v_mfma_f32_16x16x32_bf16 v[28:31], v[140:143], v[230:233], v[28:31]
	v_mfma_f32_16x16x32_bf16 v[24:27], v[170:173], v[230:233], v[24:27]
	v_mfma_f32_16x16x32_bf16 v[8:11], v[170:173], v[238:241], v[8:11]
	v_mfma_f32_16x16x32_bf16 v[12:15], v[140:143], v[238:241], v[12:15]
	v_mfma_f32_16x16x32_bf16 v[60:63], v[166:169], v[218:221], v[60:63]
	v_mfma_f32_16x16x32_bf16 v[56:59], v[174:177], v[218:221], v[56:59]
	v_mfma_f32_16x16x32_bf16 v[40:43], v[174:177], v[226:229], v[40:43]
	v_mfma_f32_16x16x32_bf16 v[44:47], v[166:169], v[226:229], v[44:47]
	v_mfma_f32_16x16x32_bf16 v[28:31], v[166:169], v[234:237], v[28:31]
	v_mfma_f32_16x16x32_bf16 v[24:27], v[174:177], v[234:237], v[24:27]
	v_mfma_f32_16x16x32_bf16 v[8:11], v[174:177], v[242:245], v[8:11]
	v_mfma_f32_16x16x32_bf16 v[12:15], v[166:169], v[242:245], v[12:15]
	v_mfma_f32_16x16x32_bf16 v[52:55], v[178:181], v[214:217], v[52:55]
	v_mfma_f32_16x16x32_bf16 v[48:51], v[186:189], v[214:217], v[48:51]
	v_mfma_f32_16x16x32_bf16 v[32:35], v[186:189], v[222:225], v[32:35]
	v_mfma_f32_16x16x32_bf16 v[36:39], v[178:181], v[222:225], v[36:39]
	v_mfma_f32_16x16x32_bf16 v[20:23], v[178:181], v[230:233], v[20:23]
	v_mfma_f32_16x16x32_bf16 v[16:19], v[186:189], v[230:233], v[16:19]
	v_mfma_f32_16x16x32_bf16 v[0:3], v[186:189], v[238:241], v[0:3]
	v_mfma_f32_16x16x32_bf16 v[4:7], v[178:181], v[238:241], v[4:7]
	v_mfma_f32_16x16x32_bf16 v[52:55], v[182:185], v[218:221], v[52:55]
	v_mfma_f32_16x16x32_bf16 v[48:51], v[210:213], v[218:221], v[48:51]
	v_mfma_f32_16x16x32_bf16 v[32:35], v[210:213], v[226:229], v[32:35]
	v_mfma_f32_16x16x32_bf16 v[36:39], v[182:185], v[226:229], v[36:39]
	v_mfma_f32_16x16x32_bf16 v[20:23], v[182:185], v[234:237], v[20:23]
	v_mfma_f32_16x16x32_bf16 v[16:19], v[210:213], v[234:237], v[16:19]
	v_mfma_f32_16x16x32_bf16 v[0:3], v[210:213], v[242:245], v[0:3]
	v_mfma_f32_16x16x32_bf16 v[4:7], v[182:185], v[242:245], v[4:7]
	s_setprio 0
	s_barrier
	s_add_i32 s55, s55, 2
	s_add_u32 s0, s0, 0x100
	s_addc_u32 s1, s1, 0
	s_add_u32 s53, s53, 0x100
	s_addc_u32 s54, s54, 0
	s_cmp_gt_u32 s55, 13
; #define PG8_STAGE(bufoff, gbase, voff) do { _Pragma("unroll") for (int _i = 0; _i < 2; ++_i) \
;         __builtin_amdgcn_global_load_lds((const unsigned*)((const char*)(gbase) + (voff)[_i]), (PG8_LAS unsigned*)(lds + (bufoff) + ldsw + _i * 8192), 16, 0, 0); } while (0)
; #define PG8_LDA(dst, b, h) do { _Pragma("unroll") for (int m = 0; m < 4; ++m) _Pragma("unroll") for (int k = 0; k < 2; ++k) dst[m][k] = *(const PG8_LAS bf16x8*)(lds + PG8_SA(b, h) + aoff + m * 2048 + k * 1024); } while (0)
; #define PG8_LDB(dst, b, h) do { _Pragma("unroll") for (int n = 0; n < 2; ++n) _Pragma("unroll") for (int k = 0; k < 2; ++k) dst[n][k] = *(const PG8_LAS bf16x8*)(lds + PG8_SB(b, h) + boff + n * 2048 + k * 1024); } while (0)
; #define PG8_MMA(ai, bj, At, Bt) do { __builtin_amdgcn_s_setprio(1); _Pragma("unroll") for (int m = 0; m < 4; ++m) _Pragma("unroll") for (int n = 0; n < 2; ++n) _Pragma("unroll") for (int k = 0; k < 2; ++k) \
;         acc[ai][bj][m][n] = __builtin_amdgcn_mfma_f32_16x16x32_bf16(Bt[n][k], At[m][k], acc[ai][bj][m][n], 0, 0, 0); __builtin_amdgcn_s_setprio(0); } while (0)
; #define PG8_WAIT_V(n) asm volatile("s_waitcnt vmcnt(" #n ")" ::: "memory")
; #define PG8_WAIT_L(n) asm volatile("s_waitcnt lgkmcnt(" #n ")" ::: "memory")
; #define PG8_BAR __builtin_amdgcn_s_barrier()
; #define PG8_SCHED __builtin_amdgcn_sched_barrier(0)
; template <class Epi, class Sched, bool ALIGN_EPI = false, bool SP2 = false>
; __device__ __forceinline__ void gemm_phase(PG8_LAS unsigned char* lds, const Gemm g, const Sched& S, const Epi& E) {
;     ...
;             PG8_LDB(B0, 0, 0); PG8_LDB(B1, 0, 1); PG8_SCHED; PG8_LDA(At, 0, 0); PG8_STAGE(PG8_SA(1, 1), a1 + hstep, voffA);
;             PG8_WAIT_V(8); PG8_WAIT_L(0); PG8_BAR; PG8_MMA(0, 0, At, B0); PG8_MMA(0, 1, At, B1); PG8_BAR; PG8_SCHED;
;             PG8_LDA(At, 0, 1); PG8_STAGE(PG8_SB(0, 0), b2, voffB); PG8_STAGE(PG8_SB(0, 1), b2 + hstep, voffB); PG8_STAGE(PG8_SA(0, 0), a2, voffA);
;             PG8_WAIT_V(8); PG8_WAIT_L(0); PG8_BAR; PG8_MMA(1, 0, At, B0); PG8_MMA(1, 1, At, B1); PG8_BAR; PG8_SCHED;
.LBB0_1042:
	ds_read_b128 v[140:143], v254
	ds_read_b128 v[166:169], v254 offset:1024
	ds_read_b128 v[170:173], v254 offset:2048
	ds_read_b128 v[174:177], v254 offset:3072
	ds_read_b128 v[178:181], v254 offset:16384
	ds_read_b128 v[182:185], v254 offset:17408
	ds_read_b128 v[186:189], v254 offset:18432
	ds_read_b128 v[210:213], v254 offset:19456
	s_add_u32 s2, s0, 0xfffc0080
	s_addc_u32 s3, s1, -1
	s_cmp_eq_u32 s55, 12
	s_cselect_b32 s5, s23, s3
	s_cselect_b32 s4, s51, s2
	s_cselect_b32 s3, s21, s54
	s_cselect_b32 s2, s52, s53
	s_add_i32 m0, s31, 0xc000
	ds_read_b128 v[214:217], v163
	ds_read_b128 v[218:221], v163 offset:1024
	ds_read_b128 v[222:225], v163 offset:2048
	ds_read_b128 v[226:229], v163 offset:3072
	ds_read_b128 v[230:233], v163 offset:4096
	ds_read_b128 v[234:237], v163 offset:5120
	ds_read_b128 v[238:241], v163 offset:6144
	ds_read_b128 v[242:245], v163 offset:7168
	global_load_lds_dwordx4 v136, s[0:1]
	s_add_i32 m0, s31, 0xe000
	s_nop 0
	global_load_lds_dwordx4 v138, s[0:1]
	s_waitcnt vmcnt(8)
	s_waitcnt lgkmcnt(0)
	s_barrier
	s_setprio 1
	v_mfma_f32_16x16x32_bf16 v[124:127], v[140:143], v[214:217], v[124:127]
	v_mfma_f32_16x16x32_bf16 v[120:123], v[170:173], v[214:217], v[120:123]
	v_mfma_f32_16x16x32_bf16 v[104:107], v[170:173], v[222:225], v[104:107]
	v_mfma_f32_16x16x32_bf16 v[108:111], v[140:143], v[222:225], v[108:111]
	v_mfma_f32_16x16x32_bf16 v[92:95], v[140:143], v[230:233], v[92:95]
	v_mfma_f32_16x16x32_bf16 v[88:91], v[170:173], v[230:233], v[88:91]
	v_mfma_f32_16x16x32_bf16 v[72:75], v[170:173], v[238:241], v[72:75]
	v_mfma_f32_16x16x32_bf16 v[76:79], v[140:143], v[238:241], v[76:79]
	v_mfma_f32_16x16x32_bf16 v[124:127], v[166:169], v[218:221], v[124:127]
	v_mfma_f32_16x16x32_bf16 v[120:123], v[174:177], v[218:221], v[120:123]
	v_mfma_f32_16x16x32_bf16 v[104:107], v[174:177], v[226:229], v[104:107]
	v_mfma_f32_16x16x32_bf16 v[108:111], v[166:169], v[226:229], v[108:111]
	v_mfma_f32_16x16x32_bf16 v[92:95], v[166:169], v[234:237], v[92:95]
	v_mfma_f32_16x16x32_bf16 v[88:91], v[174:177], v[234:237], v[88:91]
	v_mfma_f32_16x16x32_bf16 v[72:75], v[174:177], v[242:245], v[72:75]
	v_mfma_f32_16x16x32_bf16 v[76:79], v[166:169], v[242:245], v[76:79]
	v_mfma_f32_16x16x32_bf16 v[116:119], v[178:181], v[214:217], v[116:119]
	v_mfma_f32_16x16x32_bf16 v[112:115], v[186:189], v[214:217], v[112:115]
	v_mfma_f32_16x16x32_bf16 v[96:99], v[186:189], v[222:225], v[96:99]
	v_mfma_f32_16x16x32_bf16 v[100:103], v[178:181], v[222:225], v[100:103]
	v_mfma_f32_16x16x32_bf16 v[84:87], v[178:181], v[230:233], v[84:87]
	v_mfma_f32_16x16x32_bf16 v[80:83], v[186:189], v[230:233], v[80:83]
	v_mfma_f32_16x16x32_bf16 v[64:67], v[186:189], v[238:241], v[64:67]
	v_mfma_f32_16x16x32_bf16 v[68:71], v[178:181], v[238:241], v[68:71]
	v_mfma_f32_16x16x32_bf16 v[116:119], v[182:185], v[218:221], v[116:119]
	v_mfma_f32_16x16x32_bf16 v[112:115], v[210:213], v[218:221], v[112:115]
	v_mfma_f32_16x16x32_bf16 v[96:99], v[210:213], v[226:229], v[96:99]
	v_mfma_f32_16x16x32_bf16 v[100:103], v[182:185], v[226:229], v[100:103]
	v_mfma_f32_16x16x32_bf16 v[84:87], v[182:185], v[234:237], v[84:87]
	v_mfma_f32_16x16x32_bf16 v[80:83], v[210:213], v[234:237], v[80:83]
	v_mfma_f32_16x16x32_bf16 v[64:67], v[210:213], v[242:245], v[64:67]
	v_mfma_f32_16x16x32_bf16 v[68:71], v[182:185], v[242:245], v[68:71]
	s_setprio 0
	s_barrier
	s_mov_b32 m0, s33
	s_add_u32 s56, s2, 0x40000
	s_addc_u32 s57, s3, 0
	ds_read_b128 v[214:217], v163 offset:16384
	ds_read_b128 v[218:221], v163 offset:17408
	ds_read_b128 v[222:225], v163 offset:18432
	ds_read_b128 v[226:229], v163 offset:19456
	ds_read_b128 v[230:233], v163 offset:20480
	ds_read_b128 v[234:237], v163 offset:21504
	ds_read_b128 v[238:241], v163 offset:22528
	ds_read_b128 v[242:245], v163 offset:23552
	global_load_lds_dwordx4 v132, s[2:3]
	s_mov_b32 m0, s34
	s_nop 0
	global_load_lds_dwordx4 v128, s[2:3]
	s_mov_b32 m0, s35
	s_nop 0
	global_load_lds_dwordx4 v132, s[56:57]
	s_mov_b32 m0, s36
	s_nop 0
	global_load_lds_dwordx4 v128, s[56:57]
	s_mov_b32 m0, s31
	s_nop 0
	global_load_lds_dwordx4 v134, s[4:5]
	s_mov_b32 m0, s37
	s_nop 0
	global_load_lds_dwordx4 v130, s[4:5]
	s_waitcnt vmcnt(8)
	s_waitcnt lgkmcnt(0)
	s_barrier
	s_setprio 1
	v_mfma_f32_16x16x32_bf16 v[60:63], v[140:143], v[214:217], v[60:63]
	v_mfma_f32_16x16x32_bf16 v[56:59], v[170:173], v[214:217], v[56:59]
	v_mfma_f32_16x16x32_bf16 v[40:43], v[170:173], v[222:225], v[40:43]
	v_mfma_f32_16x16x32_bf16 v[44:47], v[140:143], v[222:225], v[44:47]
	v_mfma_f32_16x16x32_bf16 v[28:31], v[140:143], v[230:233], v[28:31]
	v_mfma_f32_16x16x32_bf16 v[24:27], v[170:173], v[230:233], v[24:27]
	v_mfma_f32_16x16x32_bf16 v[8:11], v[170:173], v[238:241], v[8:11]
	v_mfma_f32_16x16x32_bf16 v[12:15], v[140:143], v[238:241], v[12:15]
	v_mfma_f32_16x16x32_bf16 v[60:63], v[166:169], v[218:221], v[60:63]
	v_mfma_f32_16x16x32_bf16 v[56:59], v[174:177], v[218:221], v[56:59]
	v_mfma_f32_16x16x32_bf16 v[40:43], v[174:177], v[226:229], v[40:43]
	v_mfma_f32_16x16x32_bf16 v[44:47], v[166:169], v[226:229], v[44:47]
	v_mfma_f32_16x16x32_bf16 v[28:31], v[166:169], v[234:237], v[28:31]
	v_mfma_f32_16x16x32_bf16 v[24:27], v[174:177], v[234:237], v[24:27]
	v_mfma_f32_16x16x32_bf16 v[8:11], v[174:177], v[242:245], v[8:11]
	v_mfma_f32_16x16x32_bf16 v[12:15], v[166:169], v[242:245], v[12:15]
	v_mfma_f32_16x16x32_bf16 v[52:55], v[178:181], v[214:217], v[52:55]
	v_mfma_f32_16x16x32_bf16 v[48:51], v[186:189], v[214:217], v[48:51]
	v_mfma_f32_16x16x32_bf16 v[32:35], v[186:189], v[222:225], v[32:35]
	v_mfma_f32_16x16x32_bf16 v[36:39], v[178:181], v[222:225], v[36:39]
	v_mfma_f32_16x16x32_bf16 v[20:23], v[178:181], v[230:233], v[20:23]
	v_mfma_f32_16x16x32_bf16 v[16:19], v[186:189], v[230:233], v[16:19]
	v_mfma_f32_16x16x32_bf16 v[0:3], v[186:189], v[238:241], v[0:3]
	v_mfma_f32_16x16x32_bf16 v[4:7], v[178:181], v[238:241], v[4:7]
	v_mfma_f32_16x16x32_bf16 v[52:55], v[182:185], v[218:221], v[52:55]
	v_mfma_f32_16x16x32_bf16 v[48:51], v[210:213], v[218:221], v[48:51]
	v_mfma_f32_16x16x32_bf16 v[32:35], v[210:213], v[226:229], v[32:35]
	v_mfma_f32_16x16x32_bf16 v[36:39], v[182:185], v[226:229], v[36:39]
	v_mfma_f32_16x16x32_bf16 v[20:23], v[182:185], v[234:237], v[20:23]
	v_mfma_f32_16x16x32_bf16 v[16:19], v[210:213], v[234:237], v[16:19]
	v_mfma_f32_16x16x32_bf16 v[0:3], v[210:213], v[242:245], v[0:3]
	v_mfma_f32_16x16x32_bf16 v[4:7], v[182:185], v[242:245], v[4:7]
	s_setprio 0
	s_barrier
; #define PG8_STAGE(bufoff, gbase, voff) do { _Pragma("unroll") for (int _i = 0; _i < 2; ++_i) \
;         __builtin_amdgcn_global_load_lds((const unsigned*)((const char*)(gbase) + (voff)[_i]), (PG8_LAS unsigned*)(lds + (bufoff) + ldsw + _i * 8192), 16, 0, 0); } while (0)
; #define PG8_LDA(dst, b, h) do { _Pragma("unroll") for (int m = 0; m < 4; ++m) _Pragma("unroll") for (int k = 0; k < 2; ++k) dst[m][k] = *(const PG8_LAS bf16x8*)(lds + PG8_SA(b, h) + aoff + m * 2048 + k * 1024); } while (0)
; #define PG8_LDB(dst, b, h) do { _Pragma("unroll") for (int n = 0; n < 2; ++n) _Pragma("unroll") for (int k = 0; k < 2; ++k) dst[n][k] = *(const PG8_LAS bf16x8*)(lds + PG8_SB(b, h) + boff + n * 2048 + k * 1024); } while (0)
; #define PG8_MMA(ai, bj, At, Bt) do { __builtin_amdgcn_s_setprio(1); _Pragma("unroll") for (int m = 0; m < 4; ++m) _Pragma("unroll") for (int n = 0; n < 2; ++n) _Pragma("unroll") for (int k = 0; k < 2; ++k) \
;         acc[ai][bj][m][n] = __builtin_amdgcn_mfma_f32_16x16x32_bf16(Bt[n][k], At[m][k], acc[ai][bj][m][n], 0, 0, 0); __builtin_amdgcn_s_setprio(0); } while (0)
; #define PG8_WAIT_V(n) asm volatile("s_waitcnt vmcnt(" #n ")" ::: "memory")
; #define PG8_WAIT_L(n) asm volatile("s_waitcnt lgkmcnt(" #n ")" ::: "memory")
; #define PG8_BAR __builtin_amdgcn_s_barrier()
; #define PG8_SCHED __builtin_amdgcn_sched_barrier(0)
; template <class Epi, class Sched, bool ALIGN_EPI = false, bool SP2 = false>
; __device__ __forceinline__ void gemm_phase(PG8_LAS unsigned char* lds, const Gemm g, const Sched& S, const Epi& E) {
;     ...
;             PG8_LDB(B0, 1, 0); PG8_LDB(B1, 1, 1); PG8_SCHED; PG8_LDA(At, 1, 0); PG8_STAGE(PG8_SA(0, 1), a2 + hstep, voffA);
;             PG8_WAIT_V(8); PG8_WAIT_L(0); PG8_BAR; PG8_MMA(0, 0, At, B0); PG8_MMA(0, 1, At, B1); PG8_BAR; PG8_SCHED;
;             PG8_LDA(At, 1, 1); PG8_STAGE(PG8_SB(1, 0), b3, voffB); PG8_STAGE(PG8_SB(1, 1), b3 + hstep, voffB); PG8_STAGE(PG8_SA(1, 0), a3, voffA);
;             PG8_WAIT_V(8); PG8_WAIT_L(0); PG8_BAR; PG8_MMA(1, 0, At, B0); PG8_MMA(1, 1, At, B1); PG8_BAR; PG8_SCHED;
;     ...
;         if constexpr (ALIGN_EPI) { if (wr == 0) PG8_BAR; }
	ds_read_b128 v[140:143], v254 offset:32768
	ds_read_b128 v[166:169], v254 offset:33792
	ds_read_b128 v[170:173], v254 offset:34816
	ds_read_b128 v[174:177], v254 offset:35840
	ds_read_b128 v[178:181], v254 offset:49152
	ds_read_b128 v[182:185], v254 offset:50176
	ds_read_b128 v[186:189], v254 offset:51200
	ds_read_b128 v[210:213], v254 offset:52224
	s_add_u32 s4, s4, 0x40000
	s_addc_u32 s5, s5, 0
	s_mov_b32 m0, s38
	ds_read_b128 v[214:217], v163 offset:32768
	ds_read_b128 v[218:221], v163 offset:33792
	ds_read_b128 v[222:225], v163 offset:34816
	ds_read_b128 v[226:229], v163 offset:35840
	ds_read_b128 v[230:233], v163 offset:36864
	ds_read_b128 v[234:237], v163 offset:37888
	ds_read_b128 v[238:241], v163 offset:38912
	ds_read_b128 v[242:245], v163 offset:39936
	global_load_lds_dwordx4 v134, s[4:5]
	s_mov_b32 m0, s39
	s_nop 0
	global_load_lds_dwordx4 v130, s[4:5]
	s_waitcnt vmcnt(8)
	s_waitcnt lgkmcnt(0)
	s_barrier
	s_setprio 1
	v_mfma_f32_16x16x32_bf16 v[124:127], v[140:143], v[214:217], v[124:127]
	v_mfma_f32_16x16x32_bf16 v[120:123], v[170:173], v[214:217], v[120:123]
	v_mfma_f32_16x16x32_bf16 v[104:107], v[170:173], v[222:225], v[104:107]
	v_mfma_f32_16x16x32_bf16 v[108:111], v[140:143], v[222:225], v[108:111]
	v_mfma_f32_16x16x32_bf16 v[92:95], v[140:143], v[230:233], v[92:95]
	v_mfma_f32_16x16x32_bf16 v[88:91], v[170:173], v[230:233], v[88:91]
	v_mfma_f32_16x16x32_bf16 v[72:75], v[170:173], v[238:241], v[72:75]
	v_mfma_f32_16x16x32_bf16 v[76:79], v[140:143], v[238:241], v[76:79]
	v_mfma_f32_16x16x32_bf16 v[124:127], v[166:169], v[218:221], v[124:127]
	v_mfma_f32_16x16x32_bf16 v[120:123], v[174:177], v[218:221], v[120:123]
	v_mfma_f32_16x16x32_bf16 v[104:107], v[174:177], v[226:229], v[104:107]
	v_mfma_f32_16x16x32_bf16 v[108:111], v[166:169], v[226:229], v[108:111]
	v_mfma_f32_16x16x32_bf16 v[92:95], v[166:169], v[234:237], v[92:95]
	v_mfma_f32_16x16x32_bf16 v[88:91], v[174:177], v[234:237], v[88:91]
	v_mfma_f32_16x16x32_bf16 v[72:75], v[174:177], v[242:245], v[72:75]
	v_mfma_f32_16x16x32_bf16 v[76:79], v[166:169], v[242:245], v[76:79]
	v_mfma_f32_16x16x32_bf16 v[116:119], v[178:181], v[214:217], v[116:119]
	v_mfma_f32_16x16x32_bf16 v[112:115], v[186:189], v[214:217], v[112:115]
	v_mfma_f32_16x16x32_bf16 v[96:99], v[186:189], v[222:225], v[96:99]
	v_mfma_f32_16x16x32_bf16 v[100:103], v[178:181], v[222:225], v[100:103]
	v_mfma_f32_16x16x32_bf16 v[84:87], v[178:181], v[230:233], v[84:87]
	v_mfma_f32_16x16x32_bf16 v[80:83], v[186:189], v[230:233], v[80:83]
	v_mfma_f32_16x16x32_bf16 v[64:67], v[186:189], v[238:241], v[64:67]
	v_mfma_f32_16x16x32_bf16 v[68:71], v[178:181], v[238:241], v[68:71]
	v_mfma_f32_16x16x32_bf16 v[116:119], v[182:185], v[218:221], v[116:119]
	v_mfma_f32_16x16x32_bf16 v[112:115], v[210:213], v[218:221], v[112:115]
	v_mfma_f32_16x16x32_bf16 v[96:99], v[210:213], v[226:229], v[96:99]
	v_mfma_f32_16x16x32_bf16 v[100:103], v[182:185], v[226:229], v[100:103]
	v_mfma_f32_16x16x32_bf16 v[84:87], v[182:185], v[234:237], v[84:87]
	v_mfma_f32_16x16x32_bf16 v[80:83], v[210:213], v[234:237], v[80:83]
	v_mfma_f32_16x16x32_bf16 v[64:67], v[210:213], v[242:245], v[64:67]
	v_mfma_f32_16x16x32_bf16 v[68:71], v[182:185], v[242:245], v[68:71]
	s_setprio 0
	s_barrier
	s_mov_b32 m0, s43
	s_add_u32 s2, s2, 0x40080
	s_addc_u32 s3, s3, 0
	ds_read_b128 v[214:217], v163 offset:49152
	ds_read_b128 v[218:221], v163 offset:50176
	ds_read_b128 v[222:225], v163 offset:51200
	ds_read_b128 v[226:229], v163 offset:52224
	ds_read_b128 v[230:233], v163 offset:53248
	ds_read_b128 v[234:237], v163 offset:54272
	ds_read_b128 v[238:241], v163 offset:55296
	ds_read_b128 v[242:245], v163 offset:56320
	s_add_u32 s98, s2, 0xfffc0000
	s_addc_u32 s99, s3, -1
	global_load_lds_dwordx4 v132, s[98:99]
	s_mov_b32 m0, s44
	s_nop 0
	global_load_lds_dwordx4 v128, s[98:99]
	s_mov_b32 m0, s48
	s_nop 0
	global_load_lds_dwordx4 v132, s[2:3]
	s_mov_b32 m0, s49
	s_nop 0
	global_load_lds_dwordx4 v128, s[2:3]
	s_mov_b32 m0, s45
	s_nop 0
	s_add_u32 s100, s4, 0xfffc0080
	s_addc_u32 s101, s5, -1
	global_load_lds_dwordx4 v134, s[100:101]
	s_mov_b32 m0, s47
	s_nop 0
	global_load_lds_dwordx4 v130, s[100:101]
	s_waitcnt vmcnt(8)
	s_waitcnt lgkmcnt(0)
	s_barrier
	s_setprio 1
	v_mfma_f32_16x16x32_bf16 v[60:63], v[140:143], v[214:217], v[60:63]
	v_mfma_f32_16x16x32_bf16 v[56:59], v[170:173], v[214:217], v[56:59]
	v_mfma_f32_16x16x32_bf16 v[40:43], v[170:173], v[222:225], v[40:43]
	v_mfma_f32_16x16x32_bf16 v[44:47], v[140:143], v[222:225], v[44:47]
	v_mfma_f32_16x16x32_bf16 v[28:31], v[140:143], v[230:233], v[28:31]
	v_mfma_f32_16x16x32_bf16 v[24:27], v[170:173], v[230:233], v[24:27]
	v_mfma_f32_16x16x32_bf16 v[8:11], v[170:173], v[238:241], v[8:11]
	v_mfma_f32_16x16x32_bf16 v[12:15], v[140:143], v[238:241], v[12:15]
	v_mfma_f32_16x16x32_bf16 v[60:63], v[166:169], v[218:221], v[60:63]
	v_mfma_f32_16x16x32_bf16 v[56:59], v[174:177], v[218:221], v[56:59]
	v_mfma_f32_16x16x32_bf16 v[40:43], v[174:177], v[226:229], v[40:43]
	v_mfma_f32_16x16x32_bf16 v[44:47], v[166:169], v[226:229], v[44:47]
	v_mfma_f32_16x16x32_bf16 v[28:31], v[166:169], v[234:237], v[28:31]
	v_mfma_f32_16x16x32_bf16 v[24:27], v[174:177], v[234:237], v[24:27]
	v_mfma_f32_16x16x32_bf16 v[8:11], v[174:177], v[242:245], v[8:11]
	v_mfma_f32_16x16x32_bf16 v[12:15], v[166:169], v[242:245], v[12:15]
	v_mfma_f32_16x16x32_bf16 v[52:55], v[178:181], v[214:217], v[52:55]
	v_mfma_f32_16x16x32_bf16 v[48:51], v[186:189], v[214:217], v[48:51]
	v_mfma_f32_16x16x32_bf16 v[32:35], v[186:189], v[222:225], v[32:35]
	v_mfma_f32_16x16x32_bf16 v[36:39], v[178:181], v[222:225], v[36:39]
	v_mfma_f32_16x16x32_bf16 v[20:23], v[178:181], v[230:233], v[20:23]
	v_mfma_f32_16x16x32_bf16 v[16:19], v[186:189], v[230:233], v[16:19]
	v_mfma_f32_16x16x32_bf16 v[0:3], v[186:189], v[238:241], v[0:3]
	v_mfma_f32_16x16x32_bf16 v[4:7], v[178:181], v[238:241], v[4:7]
	v_mfma_f32_16x16x32_bf16 v[52:55], v[182:185], v[218:221], v[52:55]
	v_mfma_f32_16x16x32_bf16 v[48:51], v[210:213], v[218:221], v[48:51]
	v_mfma_f32_16x16x32_bf16 v[32:35], v[210:213], v[226:229], v[32:35]
	v_mfma_f32_16x16x32_bf16 v[36:39], v[182:185], v[226:229], v[36:39]
	v_mfma_f32_16x16x32_bf16 v[20:23], v[182:185], v[234:237], v[20:23]
	v_mfma_f32_16x16x32_bf16 v[16:19], v[210:213], v[234:237], v[16:19]
	v_mfma_f32_16x16x32_bf16 v[0:3], v[210:213], v[242:245], v[0:3]
	v_mfma_f32_16x16x32_bf16 v[4:7], v[182:185], v[242:245], v[4:7]
	s_setprio 0
	s_barrier
	s_add_i32 s55, s55, 2
	s_add_u32 s0, s0, 0x100
	s_addc_u32 s1, s1, 0
	s_add_u32 s53, s53, 0x100
	s_addc_u32 s54, s54, 0
	s_cmp_gt_u32 s55, 13
	s_cbranch_scc0 .LBB0_1042
	s_and_b64 vcc, exec, s[18:19]
	s_cbranch_vccz .LBB0_1045
	s_barrier
